# byte-matched variant of the rescale-flag trim: s_mov flag,-1 before the row-max branch and s_mov flag,0 after it replace s_cmp_lg_u64+s_cselect (same code size, flag no longer depends on vcc) at 19 si
# baseline (speedup 1.0000x reference)
; #define WAIT_BAR(N) asm volatile("s_waitcnt vmcnt(" #N ") lgkmcnt(0)\n\ts_barrier":::"memory")
;   #define DMA_K(t,slot) glds16(ksrc+(long)(t)*KVBLK*PQ,(unsigned)__builtin_amdgcn_readfirstlane(kdst+(slot)))
;   #define CMASK(P0,P1,t) do{}while(0)
; template<int THRL,int MODE> __device__ __forceinline__ void attn_unit128(const bf16*Qblk,const bf16*__restrict__ Kh,const bf16*__restrict__ Vh,bf16*Oblk,const int NT,char*shm,const bf16*O1blk,bf16*AOblk,const float lam,const float*sln,const float omli){
;   int tid_=threadIdx.x; asm volatile("":"+v"(tid_));
;   const int tid=tid_,lane=tid&63,r32=lane&31,hi=lane>>5; const int wid=__builtin_amdgcn_readfirstlane(tid>>6);
;   const bf16*Qw=Qblk+(long)wid*QBLK*PQ;
;   const unsigned lds0=(unsigned)(uintptr_t)shm;
;   float*wsf=(float*)(shm+LDS_WS8)+wid*64;
;   const unsigned koff=(unsigned)(lane*PQ+wid*8)*2u;
;   const unsigned voff=(unsigned)((16*(wid&3)+(lane>>2))*PQ+(wid>>2)*32+(lane&3)*8)*2u;
;   const unsigned kdst=lds0+LDS_K+wid*1024, vdst=lds0+LDS_V+wid*1024;
;     ...
;   const char*Kbase=shm+LDS_K; bf16x8 kf[8];
;   const lds_cptr shm3=(lds_cptr)shm; const lds_cptr kp0=shm3+LDS_K+hi*1024+r32*16; const lds_cptr vp0=shm3+LDS_V+((lane>>4)&1)*32+(lane&3)*8+(4*hi+((lane&15)>>2))*64;
;   DMA_K(0,0);DMA_V(0,0);DMA_K(1,SLOTB);
;   bf16x8 qr[4];
;   #pragma unroll
;   for(int d0=0;d0<4;++d0)qr[d0]=*reinterpret_cast<const bf16x8*>(&Qw[(long)r32*PQ+d0*16+hi*8]);
;   float mhat=0.f,l_reg=0.f;f32x16 o[4];o[0]=f32x16{};o[1]=f32x16{};o[2]=f32x16{};o[3]=f32x16{};f32x16 negm=f32x16{};asm volatile("":"+v"(negm));
;     ...
;   bool resc=false;
;     ...
;   f32x16 pA0,pA1,pB0,pB1;
;   int sl_prev=0,sl_cur=0,sl_next=SLOTB;
;     ...
;   DMA_K(2,2*SLOTB);
;   WAIT_BAR(4);
;   qkt(pA0,pA1,Kbase,qr,negm,r32,hi);asm volatile("s_nop 15\n\ts_nop 7":"+v"(pA0),"+v"(pA1));CMASK(pA0,pA1,0);
;   START(pA0,pA1);
;   _Pragma("unroll") for(int r=0;r<16;++r)pA1[r]=__builtin_amdgcn_exp2f(pA1[r]);
; DI void p_attn(const bfu* QKV, bfu* AOR, bfu* AO, const float* lq1, const float* lk1, const float* lq2, const float* lk2, const float* subln, float lam_init, bool ctx_out, char* lds, int bx, int G, int vcu, int xmap) {
;     ...
;         if (u < 512) attn_pair(QKV, AOR, AO, (u >> 6) >> 2, (u >> 6) & 3, CTXL + (size_t)(u & 63) * 256, SEGR / 64, lam, subln, omli, lds);
;         else attn_pair(QKV, AOR, AO, (u - 512) >> 2, (u - 512) & 3, 0, CTXL / 64, lam, subln, omli, lds);
.LBB0_514:
	s_andn2_b64 vcc, exec, s[0:1]
	s_mov_b64 s[0:1], -1
	s_cbranch_vccnz .LBB0_505
	s_cmpk_gt_i32 s35, 0x1ff
	s_cbranch_scc0 .LBB0_539
	s_add_i32 s0, s35, 0xfffffe00
	s_lshr_b32 s28, s0, 2
	s_and_b32 s36, s35, 3
	s_mul_i32 s1, s28, 0x4920000
	s_mul_hi_u32 s0, s28, 0x4920000
	s_add_u32 s6, s58, s1
	s_addc_u32 s7, s59, s0
	s_lshl_b32 s42, s36, 7
	s_lshl_b32 s0, s36, 8
	s_add_u32 s0, s6, s0
	s_addc_u32 s1, s7, 0
	s_add_u32 s4, s0, 0x800
	s_addc_u32 s5, s1, 0
	v_mov_b32_e32 v44, v220
	s_add_u32 s6, s6, s42
	s_addc_u32 s7, s7, 0
	v_readfirstlane_b32 s8, v44
	s_ashr_i32 s33, s8, 6
	s_mul_i32 s10, s33, 0x24000
	s_mul_hi_i32 s9, s33, 0x24000
	s_add_u32 s16, s6, s10
	s_addc_u32 s17, s7, s9
	s_and_b32 s10, s8, 0x3fffffc0
	s_ashr_i32 s8, s8, 3
	s_lshl_b32 s9, s33, 4
	v_bfe_u32 v2, v44, 2, 4
	s_and_b32 s8, s8, 0x7fffffe0
	v_and_or_b32 v2, s9, 48, v2
	v_mov_b32_e32 v3, s8
	s_movk_i32 s8, 0x900
	v_mad_u32_u24 v2, v2, s8, v3
	v_lshlrev_b32_e32 v215, 3, v44
	s_lshl_b32 s8, s33, 10
	v_and_b32_e32 v212, 63, v44
	v_mov_b32_e32 v0, s9
	v_and_b32_e32 v45, 24, v215
	s_cmp_lg_u32 0, -1
	v_mad_u32_u24 v0, v212, s81, v0
	v_or_b32_e32 v2, v2, v45
	s_cselect_b32 s9, 0, 0
	v_lshlrev_b32_e32 v4, 1, v2
	s_add_i32 s22, s9, s8
	v_lshl_add_u64 v[34:35], s[6:7], 0, v[0:1]
	s_mov_b64 s[8:9], 0x400
	v_lshl_add_u64 v[2:3], v[34:35], 0, s[8:9]
	s_mov_b32 s8, m0
	s_mov_b32 m0, s22
	s_nop 0
	global_load_lds_dwordx4 v[2:3], off
	s_mov_b32 m0, s8
	v_mov_b32_e32 v0, v4
	s_add_i32 s26, s22, 0x6000
	v_lshl_add_u64 v[2:3], s[4:5], 0, v[0:1]
	s_mov_b32 s8, m0
	s_mov_b32 m0, s26
	s_nop 0
	global_load_lds_dwordx4 v[2:3], off
	s_mov_b32 m0, s8
	s_add_u32 s8, s0, 0x880
	s_addc_u32 s9, s1, 0
	v_lshl_add_u64 v[2:3], s[8:9], 0, v[0:1]
	s_add_i32 s11, s22, 0x8000
	s_mov_b32 s18, m0
	s_mov_b32 m0, s11
	s_nop 0
	global_load_lds_dwordx4 v[2:3], off
	s_mov_b32 m0, s18
	s_mov_b64 s[18:19], 0x48400
	v_and_b32_e32 v213, 31, v44
	v_lshl_add_u64 v[2:3], v[34:35], 0, s[18:19]
	s_add_i32 s11, s22, 0x2000
	s_mov_b32 s18, m0
	s_mov_b32 m0, s11
	s_nop 0
	global_load_lds_dwordx4 v[2:3], off
	s_mov_b32 m0, s18
	v_mul_u32_u24_e32 v2, 0x900, v213
	v_bfe_u32 v214, v44, 5, 1
	v_lshlrev_b32_e32 v2, 1, v2
	v_lshl_or_b32 v10, v214, 4, v2
	global_load_dwordx4 v[174:177], v10, s[16:17]
	global_load_dwordx4 v[170:173], v10, s[16:17] offset:32
	global_load_dwordx4 v[166:169], v10, s[16:17] offset:64
	global_load_dwordx4 v[162:165], v10, s[16:17] offset:96
	v_mov_b32_e32 v2, v1
	v_mov_b32_e32 v3, v1
	v_mov_b32_e32 v4, v1
	v_mov_b32_e32 v5, v1
	v_mov_b32_e32 v6, v1
	v_mov_b32_e32 v7, v1
	v_mov_b32_e32 v8, v1
	v_mov_b32_e32 v9, v1
	v_mov_b32_e32 v10, v1
	v_mov_b32_e32 v11, v1
	v_mov_b32_e32 v12, v1
	v_mov_b32_e32 v13, v1
	v_mov_b32_e32 v14, v1
	v_mov_b32_e32 v15, v1
	v_mov_b32_e32 v16, v1
	v_mov_b32_e32 v17, v1
	v_lshlrev_b32_e32 v18, 4, v213
	v_lshl_add_u32 v19, v214, 10, 0
	s_mov_b64 s[16:17], 0x90400
	v_add_u32_e32 v235, v19, v18
	v_lshl_add_u64 v[18:19], v[34:35], 0, s[16:17]
	s_add_i32 s11, s22, 0x4000
	s_mov_b32 s16, m0
	s_mov_b32 m0, s11
	s_nop 0
	global_load_lds_dwordx4 v[18:19], off
	s_mov_b32 m0, s16
	s_waitcnt vmcnt(4) lgkmcnt(0)
	s_barrier
	ds_read_b128 v[36:39], v235
	ds_read_b128 v[40:43], v235 offset:512
	s_lshl_b32 s10, s10, 2
	s_add_i32 s24, s10, 0
	s_mov_b64 s[10:11], 0xd8400
	s_add_i32 s24, s24, 0x12000
	v_cmp_gt_u32_e64 s[40:41], 32, v212
	v_lshl_add_u32 v216, v213, 2, s24
	s_waitcnt vmcnt(3) lgkmcnt(1)
	v_mfma_f32_32x32x16_bf16 v[18:33], v[36:39], v[174:177], v[2:17]
	s_waitcnt lgkmcnt(0)
	v_mfma_f32_32x32x16_bf16 v[2:17], v[40:43], v[174:177], v[2:17]
	ds_read_b128 v[36:39], v235 offset:2048
	ds_read_b128 v[40:43], v235 offset:2560
	s_waitcnt vmcnt(2) lgkmcnt(1)
	v_mfma_f32_32x32x16_bf16 v[18:33], v[36:39], v[170:173], v[18:33]
	s_waitcnt lgkmcnt(0)
	v_mfma_f32_32x32x16_bf16 v[2:17], v[40:43], v[170:173], v[2:17]
	ds_read_b128 v[36:39], v235 offset:4096
	ds_read_b128 v[40:43], v235 offset:4608
	s_waitcnt vmcnt(1) lgkmcnt(1)
	v_mfma_f32_32x32x16_bf16 v[18:33], v[36:39], v[166:169], v[18:33]
	s_waitcnt lgkmcnt(0)
	v_mfma_f32_32x32x16_bf16 v[2:17], v[40:43], v[166:169], v[2:17]
	ds_read_b128 v[36:39], v235 offset:6144
	ds_read_b128 v[40:43], v235 offset:6656
	s_waitcnt vmcnt(0) lgkmcnt(1)
	v_mfma_f32_32x32x16_bf16 v[18:33], v[36:39], v[162:165], v[18:33]
	v_lshlrev_b32_e32 v36, 1, v44
	v_and_b32_e32 v36, 32, v36
	v_lshlrev_b32_e32 v37, 4, v44
	v_add3_u32 v36, 0, v36, v45
	v_lshlrev_b32_e32 v38, 8, v214
	v_and_b32_e32 v37, 0xc0, v37
	v_add3_u32 v233, v36, v38, v37
	s_waitcnt lgkmcnt(0)
	v_mfma_f32_32x32x16_bf16 v[2:17], v[40:43], v[162:165], v[2:17]
	s_nop 15
	s_nop 7
	s_nop 0
	v_max3_f32 v39, v18, v19, v2
	v_max3_f32 v40, v20, v21, v3
	s_nop 0
	v_max3_f32 v39, v39, v4, v5
	v_max3_f32 v40, v40, v24, v25
	s_nop 0
	v_max3_f32 v39, v39, v22, v23
	v_max3_f32 v40, v40, v8, v9
	s_nop 0
	v_max3_f32 v39, v39, v6, v7
	v_max3_f32 v40, v40, v28, v29
	s_nop 0
	v_max3_f32 v39, v39, v26, v27
	v_max3_f32 v40, v40, v12, v13
	s_nop 0
	v_max3_f32 v39, v39, v10, v11
	v_max3_f32 v40, v40, v32, v33
	s_nop 0
	v_max3_f32 v39, v39, v30, v31
	v_max3_f32 v40, v40, v16, v17
	s_nop 0
	v_max3_f32 v39, v39, v14, v15
	s_nop 0
	v_max_f32_e32 v39, v39, v40
	s_nop 0
	v_mov_b32_e32 v40, v39
	s_nop 1
	v_permlane32_swap_b32_e32 v39, v40
	v_max_f32_e32 v39, v39, v40
	s_nop 0
	v_add_f32_e32 v234, v1, v39
	v_sub_f32_e32 v40, v2, v39
	v_sub_f32_e32 v18, v18, v39
	v_sub_f32_e32 v19, v19, v39
	v_sub_f32_e32 v41, v3, v39
	v_sub_f32_e32 v20, v20, v39
	s_nop 0
	v_xor_b32_e32 v2, 0x80000000, v234
	v_sub_f32_e32 v42, v4, v39
	v_sub_f32_e32 v21, v21, v39
	v_sub_f32_e32 v43, v5, v39
	v_sub_f32_e32 v22, v22, v39
	v_sub_f32_e32 v44, v6, v39
	v_sub_f32_e32 v23, v23, v39
	v_sub_f32_e32 v45, v7, v39
	v_sub_f32_e32 v24, v24, v39
	v_sub_f32_e32 v46, v8, v39
	v_sub_f32_e32 v25, v25, v39
	v_sub_f32_e32 v47, v9, v39
	v_sub_f32_e32 v26, v26, v39
	v_sub_f32_e32 v48, v10, v39
	v_sub_f32_e32 v27, v27, v39
	v_sub_f32_e32 v49, v11, v39
	v_sub_f32_e32 v28, v28, v39
	v_sub_f32_e32 v50, v12, v39
	v_sub_f32_e32 v29, v29, v39
	v_sub_f32_e32 v51, v13, v39
	v_sub_f32_e32 v30, v30, v39
	v_sub_f32_e32 v52, v14, v39
	v_sub_f32_e32 v31, v31, v39
	v_sub_f32_e32 v53, v15, v39
	v_sub_f32_e32 v32, v32, v39
	v_sub_f32_e32 v54, v16, v39
	v_sub_f32_e32 v33, v33, v39
	v_sub_f32_e32 v39, v17, v39
	v_mov_b32_e32 v3, v2
	v_mov_b32_e32 v4, v2
	v_mov_b32_e32 v5, v2
	v_mov_b32_e32 v6, v2
	v_mov_b32_e32 v7, v2
	v_mov_b32_e32 v8, v2
	v_mov_b32_e32 v9, v2
	v_mov_b32_e32 v10, v2
	v_mov_b32_e32 v11, v2
	v_mov_b32_e32 v12, v2
	v_mov_b32_e32 v13, v2
	v_mov_b32_e32 v14, v2
	v_mov_b32_e32 v15, v2
	v_mov_b32_e32 v16, v2
	v_mov_b32_e32 v17, v2
	s_waitcnt vmcnt(0) lgkmcnt(0)
	s_barrier
; #define WAIT_BAR(N) asm volatile("s_waitcnt vmcnt(" #N ") lgkmcnt(0)\n\ts_barrier":::"memory")
;   #define DMA_K(t,slot) glds16(ksrc+(long)(t)*KVBLK*PQ,(unsigned)__builtin_amdgcn_readfirstlane(kdst+(slot)))
;   #define DMA_V(t,slot) glds16(vsrc+(long)(t)*KVBLK*PQ,(unsigned)__builtin_amdgcn_readfirstlane(vdst+(slot)))
;   #define ROT() do{sl_prev=sl_cur;sl_cur=sl_next;sl_next=(sl_next==(NSLOT-1)*SLOTB)?0:sl_next+SLOTB;}while(0)
;   #define DMA_K(t,slot) glds16((const char*)Kh+(size_t)(t)*(KVBLK*PQ*2)+koff,(unsigned)__builtin_amdgcn_readfirstlane(kdst+(slot)))
;   #define DMA_V(t,slot) do{ glds16((const char*)Vh+(size_t)(t)*(KVBLK*PQ*2)+voff,(unsigned)__builtin_amdgcn_readfirstlane(vdst+2*(slot))); glds16((const char*)Vh+(size_t)(t)*(KVBLK*PQ*2)+128+voff,(unsigned)__builtin_amdgcn_readfirstlane(vdst+2*(slot)+8192)); }while(0)
;   #define ROT() do{sl_prev=sl_cur;sl_cur=sl_next;sl_next=(sl_next==(NSLOT-1)*SLOTB)?0:sl_next+SLOTB;}while(0)
; template<int THRL,int MODE> __device__ __forceinline__ void attn_unit128(const bf16*Qblk,const bf16*__restrict__ Kh,const bf16*__restrict__ Vh,bf16*Oblk,const int NT,char*shm,const bf16*O1blk,bf16*AOblk,const float lam,const float*sln,const float omli){
;     ...
;   _Pragma("unroll") for(int r=0;r<16;++r)pA1[r]=__builtin_amdgcn_exp2f(pA1[r]);
;   WAIT_BAR(0);
;   DMA_K(3,0);DMA_V(1,SLOTB);
;   ROT();
;   kload8(kf,kp0+sl_cur);
;   WAIT_BAR(3);
;   s16x4 vlo[8],vhi[8]; u32x4 pw0,pw1,pw2,pw3;
	v_exp_f32_e32 v55, v18
	v_exp_f32_e32 v56, v19
	v_lshl_add_u64 v[18:19], v[34:35], 0, s[10:11]
	s_mov_b32 s10, m0
	s_mov_b32 m0, s22
	s_nop 0
	global_load_lds_dwordx4 v[18:19], off
	s_mov_b32 m0, s10
	s_add_u32 s10, s0, 0x48800
	s_addc_u32 s11, s1, 0
	s_add_i32 s16, s22, 0xa000
	v_lshl_add_u64 v[18:19], s[10:11], 0, v[0:1]
	s_mov_b32 s17, m0
	s_mov_b32 m0, s16
	s_nop 0
	global_load_lds_dwordx4 v[18:19], off
	s_mov_b32 m0, s17
	s_add_u32 s16, s0, 0x48880
	s_addc_u32 s17, s1, 0
	v_lshl_add_u64 v[18:19], s[16:17], 0, v[0:1]
	s_add_i32 s18, s22, 0xc000
	s_mov_b32 s19, m0
	s_mov_b32 m0, s18
	s_nop 0
	global_load_lds_dwordx4 v[18:19], off
	s_mov_b32 m0, s19
	v_exp_f32_e32 v57, v20
	v_exp_f32_e32 v58, v21
	v_exp_f32_e32 v59, v22
	v_exp_f32_e32 v60, v23
	v_exp_f32_e32 v61, v24
	v_exp_f32_e32 v62, v25
	v_exp_f32_e32 v63, v26
	v_exp_f32_e32 v64, v27
	v_exp_f32_e32 v65, v28
	v_exp_f32_e32 v66, v29
	v_exp_f32_e32 v67, v30
	v_exp_f32_e32 v68, v31
	v_exp_f32_e32 v69, v32
	v_exp_f32_e32 v70, v33
	v_exp_f32_e32 v71, v40
	v_exp_f32_e32 v72, v41
	v_exp_f32_e32 v73, v42
	v_exp_f32_e32 v74, v43
	v_exp_f32_e32 v75, v44
	v_exp_f32_e32 v76, v45
	v_exp_f32_e32 v77, v46
	v_exp_f32_e32 v78, v47
	v_exp_f32_e32 v79, v48
	v_exp_f32_e32 v80, v49
	v_exp_f32_e32 v81, v39
	ds_read_b128 v[18:21], v235 offset:8192
	ds_read_b128 v[22:25], v235 offset:8704
	ds_read_b128 v[26:29], v235 offset:10240
	ds_read_b128 v[30:33], v235 offset:10752
	ds_read_b128 v[34:37], v235 offset:12288
	ds_read_b128 v[38:41], v235 offset:12800
	ds_read_b128 v[42:45], v235 offset:14336
	ds_read_b128 v[46:49], v235 offset:14848
	v_exp_f32_e32 v50, v50
	v_exp_f32_e32 v51, v51
	v_exp_f32_e32 v52, v52
	v_exp_f32_e32 v53, v53
	v_exp_f32_e32 v54, v54
	s_waitcnt vmcnt(3) lgkmcnt(0)
	s_barrier
	s_waitcnt lgkmcnt(7)
	v_mfma_f32_32x32x16_bf16 v[130:145], v[18:21], v[174:177], v[2:17]
	v_add_f32_e32 v82, v55, v56
	v_add_f32_e32 v82, v82, v57
	v_add_f32_e32 v82, v82, v58
	v_add_f32_e32 v82, v82, v59
	v_add_f32_e32 v82, v82, v60
	v_cvt_pk_bf16_f32 v146, v55, v56
	v_cvt_pk_bf16_f32 v147, v57, v58
	s_waitcnt lgkmcnt(6)
	v_mfma_f32_32x32x16_bf16 v[98:113], v[22:25], v[174:177], v[2:17]
	v_add_f32_e32 v18, v61, v82
	v_add_f32_e32 v18, v62, v18
	v_add_f32_e32 v18, v63, v18
	v_add_f32_e32 v18, v64, v18
	v_cvt_pk_bf16_f32 v148, v59, v60
	v_cvt_pk_bf16_f32 v149, v61, v62
	s_waitcnt lgkmcnt(5)
	v_mfma_f32_32x32x16_bf16 v[130:145], v[26:29], v[170:173], v[130:145]
	v_add_f32_e32 v18, v65, v18
	v_add_f32_e32 v18, v66, v18
	v_add_f32_e32 v18, v67, v18
	v_add_f32_e32 v18, v68, v18
	v_cvt_pk_bf16_f32 v150, v63, v64
	v_cvt_pk_bf16_f32 v151, v65, v66
	s_waitcnt lgkmcnt(4)
	v_mfma_f32_32x32x16_bf16 v[98:113], v[30:33], v[170:173], v[98:113]
	v_add_f32_e32 v18, v69, v18
	v_add_f32_e32 v18, v70, v18
	v_add_f32_e32 v18, v71, v18
	v_add_f32_e32 v18, v72, v18
	v_cvt_pk_bf16_f32 v152, v67, v68
	v_cvt_pk_bf16_f32 v153, v69, v70
	s_waitcnt lgkmcnt(3)
	v_mfma_f32_32x32x16_bf16 v[130:145], v[34:37], v[166:169], v[130:145]
	v_add_f32_e32 v18, v73, v18
	v_add_f32_e32 v18, v74, v18
	v_add_f32_e32 v18, v75, v18
	v_add_f32_e32 v18, v76, v18
	v_cvt_pk_bf16_f32 v154, v71, v72
	v_cvt_pk_bf16_f32 v155, v73, v74
	s_waitcnt lgkmcnt(2)
	v_mfma_f32_32x32x16_bf16 v[98:113], v[38:41], v[166:169], v[98:113]
	v_add_f32_e32 v18, v77, v18
	v_add_f32_e32 v18, v78, v18
	v_add_f32_e32 v18, v79, v18
	v_add_f32_e32 v18, v80, v18
	v_cvt_pk_bf16_f32 v156, v75, v76
	v_cvt_pk_bf16_f32 v157, v77, v78
	s_waitcnt lgkmcnt(1)
	v_mfma_f32_32x32x16_bf16 v[130:145], v[42:45], v[162:165], v[130:145]
	v_add_f32_e32 v18, v50, v18
	v_add_f32_e32 v18, v51, v18
	v_add_f32_e32 v18, v52, v18
	v_add_f32_e32 v18, v53, v18
	v_cvt_pk_bf16_f32 v158, v79, v80
	v_cvt_pk_bf16_f32 v159, v50, v51
	s_waitcnt lgkmcnt(0)
	v_mfma_f32_32x32x16_bf16 v[98:113], v[46:49], v[162:165], v[98:113]
	v_add_f32_e32 v18, v54, v18
	v_add_f32_e32 v18, v81, v18
	v_add_f32_e32 v18, 0, v18
	v_cvt_pk_bf16_f32 v160, v52, v53
	v_cvt_pk_bf16_f32 v161, v54, v81
	s_nop 0
	v_add_f32_e32 v236, 0, v18
	ds_read_b64_tr_b16 v[18:19], v233 offset:24576
	ds_read_b64_tr_b16 v[20:21], v233 offset:25088
	ds_read_b64_tr_b16 v[34:35], v233 offset:28672
	ds_read_b64_tr_b16 v[36:37], v233 offset:29184
	ds_read_b64_tr_b16 v[70:71], v233 offset:25600
	ds_read_b64_tr_b16 v[72:73], v233 offset:26112
	ds_read_b64_tr_b16 v[66:67], v233 offset:29696
	ds_read_b64_tr_b16 v[68:69], v233 offset:30208
	ds_read_b64_tr_b16 v[62:63], v233 offset:26624
	ds_read_b64_tr_b16 v[64:65], v233 offset:27136
	ds_read_b64_tr_b16 v[54:55], v233 offset:27648
	ds_read_b64_tr_b16 v[56:57], v233 offset:28160
	ds_read_b64_tr_b16 v[58:59], v233 offset:30720
	ds_read_b64_tr_b16 v[60:61], v233 offset:31232
	ds_read_b64_tr_b16 v[50:51], v233 offset:31744
	ds_read_b64_tr_b16 v[52:53], v233 offset:32256
	s_add_u32 s18, s0, 0x90800
	s_addc_u32 s19, s1, 0
	s_add_i32 s20, s22, 0xe000
	v_lshl_add_u64 v[22:23], s[18:19], 0, v[0:1]
	s_mov_b32 s21, m0
	s_mov_b32 m0, s20
	s_nop 0
	global_load_lds_dwordx4 v[22:23], off
	s_mov_b32 m0, s21
	s_add_u32 s20, s0, 0x90880
	s_addc_u32 s21, s1, 0
	v_lshl_add_u64 v[22:23], s[20:21], 0, v[0:1]
	s_add_i32 s0, s22, 0x10000
	s_mov_b32 s1, m0
	s_mov_b32 m0, s0
	s_nop 0
	global_load_lds_dwordx4 v[22:23], off
	s_mov_b32 m0, s1
	v_max_f32_e32 v22, v131, v131
	v_max_f32_e32 v23, v130, v130
	v_max_f32_e32 v22, v23, v22
	v_max3_f32 v23, v132, v133, v99
	v_max3_f32 v22, v22, v98, v100
	v_max3_f32 v22, v22, v101, v134
	v_max3_f32 v23, v23, v136, v137
	v_max3_f32 v22, v22, v135, v102
	v_max3_f32 v23, v23, v104, v105
	v_max3_f32 v22, v22, v103, v138
	v_max3_f32 v23, v23, v140, v141
	v_max3_f32 v22, v22, v139, v106
	v_max3_f32 v23, v23, v108, v109
	v_max3_f32 v22, v22, v107, v142
	v_max3_f32 v23, v23, v144, v145
	v_max3_f32 v22, v22, v143, v110
	v_max3_f32 v23, v23, v112, v113
	v_max3_f32 v22, v22, v111, v23
	v_mov_b32_e32 v23, v22
	s_nop 1
	v_permlane32_swap_b32_e32 v22, v23
	v_max_f32_e32 v23, v23, v23
	v_max_f32_e32 v22, v22, v22
	v_max_f32_e32 v22, v22, v23
	v_cmp_lt_f32_e32 vcc, s15, v22
	s_mov_b64 s[0:1], -1
	s_cbranch_vccnz .LBB0_606
	s_mov_b64 s[0:1], 0

.LBB0_519:
	s_waitcnt lgkmcnt(7)
	v_mfma_f32_32x32x16_bf16 v[114:129], v[82:85], v[174:177], v[2:17]
	v_add_f32_e32 v86, v130, v131
	v_add_f32_e32 v86, v132, v86
	v_add_f32_e32 v86, v133, v86
	v_add_f32_e32 v86, v134, v86
	v_add_f32_e32 v86, v135, v86
	v_cvt_pk_bf16_f32 v146, v130, v131
	v_cvt_pk_bf16_f32 v147, v132, v133
	s_nop 0
	v_add_f32_e32 v82, v136, v86
	v_add_f32_e32 v82, v137, v82
	v_add_f32_e32 v82, v138, v82
	v_add_f32_e32 v130, v139, v82
	s_waitcnt lgkmcnt(6)
	v_mfma_f32_32x32x16_bf16 v[82:97], v[198:201], v[174:177], v[2:17]
	v_cvt_pk_bf16_f32 v148, v134, v135
	v_cvt_pk_bf16_f32 v149, v136, v137
	s_waitcnt lgkmcnt(5)
	v_mfma_f32_32x32x16_bf16 v[114:129], v[202:205], v[170:173], v[114:129]
	v_add_f32_e32 v130, v140, v130
	v_add_f32_e32 v130, v141, v130
	v_add_f32_e32 v130, v142, v130
	v_add_f32_e32 v130, v143, v130
	v_cvt_pk_bf16_f32 v150, v138, v139
	v_cvt_pk_bf16_f32 v151, v140, v141
	s_waitcnt lgkmcnt(4)
	v_mfma_f32_32x32x16_bf16 v[82:97], v[194:197], v[170:173], v[82:97]
	v_add_f32_e32 v130, v144, v130
	v_add_f32_e32 v130, v145, v130
	v_add_f32_e32 v130, v98, v130
	v_add_f32_e32 v130, v99, v130
	v_cvt_pk_bf16_f32 v152, v142, v143
	v_cvt_pk_bf16_f32 v153, v144, v145
	s_waitcnt lgkmcnt(3)
	v_mfma_f32_32x32x16_bf16 v[114:129], v[190:193], v[166:169], v[114:129]
	v_add_f32_e32 v130, v100, v130
	v_add_f32_e32 v130, v101, v130
	v_add_f32_e32 v130, v102, v130
	v_add_f32_e32 v130, v103, v130
	v_cvt_pk_bf16_f32 v154, v98, v99
	v_cvt_pk_bf16_f32 v155, v100, v101
	s_waitcnt lgkmcnt(2)
	v_mfma_f32_32x32x16_bf16 v[82:97], v[186:189], v[166:169], v[82:97]
	v_add_f32_e32 v98, v104, v130
	v_add_f32_e32 v98, v105, v98
	v_add_f32_e32 v98, v106, v98
	v_add_f32_e32 v98, v107, v98
	v_cvt_pk_bf16_f32 v156, v102, v103
	v_cvt_pk_bf16_f32 v157, v104, v105
	s_waitcnt lgkmcnt(1)
	v_mfma_f32_32x32x16_bf16 v[114:129], v[182:185], v[162:165], v[114:129]
	v_add_f32_e32 v98, v108, v98
	v_add_f32_e32 v98, v109, v98
	v_add_f32_e32 v98, v110, v98
	v_add_f32_e32 v98, v111, v98
	v_cvt_pk_bf16_f32 v158, v106, v107
	v_cvt_pk_bf16_f32 v159, v108, v109
	s_waitcnt lgkmcnt(0)
	v_mfma_f32_32x32x16_bf16 v[82:97], v[178:181], v[162:165], v[82:97]
	v_add_f32_e32 v98, v112, v98
	v_add_f32_e32 v98, v113, v98
	v_add_f32_e32 v98, 0, v98
	v_cvt_pk_bf16_f32 v160, v110, v111
	v_cvt_pk_bf16_f32 v161, v112, v113
	ds_read_b64_tr_b16 v[142:143], v233 offset:40960
	ds_read_b64_tr_b16 v[144:145], v233 offset:41472
	ds_read_b64_tr_b16 v[138:139], v233 offset:45056
	ds_read_b64_tr_b16 v[140:141], v233 offset:45568
	ds_read_b64_tr_b16 v[134:135], v233 offset:41984
	ds_read_b64_tr_b16 v[136:137], v233 offset:42496
	ds_read_b64_tr_b16 v[130:131], v233 offset:46080
	ds_read_b64_tr_b16 v[132:133], v233 offset:46592
	v_add_f32_e32 v194, v236, v98
	ds_read_b64_tr_b16 v[110:111], v233 offset:43008
	ds_read_b64_tr_b16 v[112:113], v233 offset:43520
	ds_read_b64_tr_b16 v[102:103], v233 offset:44032
	ds_read_b64_tr_b16 v[104:105], v233 offset:44544
	ds_read_b64_tr_b16 v[106:107], v233 offset:47104
	ds_read_b64_tr_b16 v[108:109], v233 offset:47616
	ds_read_b64_tr_b16 v[98:99], v233 offset:48128
	ds_read_b64_tr_b16 v[100:101], v233 offset:48640
	s_add_u32 s22, s4, 0xd8000
	s_addc_u32 s23, s5, 0
	s_add_u32 s24, s4, 0xd8080
	v_lshl_add_u64 v[178:179], s[22:23], 0, v[0:1]
	s_addc_u32 s25, s5, 0
	s_mov_b32 s0, m0
	s_mov_b32 m0, s26
	s_nop 0
	global_load_lds_dwordx4 v[178:179], off
	s_mov_b32 m0, s0
	v_lshl_add_u64 v[178:179], s[24:25], 0, v[0:1]
	s_addk_i32 s26, 0x2000
	s_mov_b32 s0, m0
	s_mov_b32 m0, s26
	s_nop 0
	global_load_lds_dwordx4 v[178:179], off
	s_mov_b32 m0, s0
	v_max_f32_e32 v0, v115, v115
	v_max_f32_e32 v178, v114, v114
	v_max_f32_e32 v0, v178, v0
	v_max3_f32 v178, v116, v117, v83
	v_max3_f32 v0, v0, v82, v84
	v_max3_f32 v0, v0, v85, v118
	v_max3_f32 v178, v178, v120, v121
	v_max3_f32 v0, v0, v119, v86
	v_max3_f32 v178, v178, v88, v89
	v_max3_f32 v0, v0, v87, v122
	v_max3_f32 v178, v178, v124, v125
	v_max3_f32 v0, v0, v123, v90
	v_max3_f32 v178, v178, v92, v93
	v_max3_f32 v0, v0, v91, v126
	v_max3_f32 v178, v178, v128, v129
	v_max3_f32 v0, v0, v127, v94
	v_max3_f32 v178, v178, v96, v97
	v_max3_f32 v0, v0, v95, v178
	v_mov_b32_e32 v178, v0
	s_nop 1
	v_permlane32_swap_b32_e32 v0, v178
	v_max_f32_e32 v178, v178, v178
	v_max_f32_e32 v0, v0, v0
	v_max_f32_e32 v0, v0, v178
	v_cmp_lt_f32_e32 vcc, s15, v0
	s_mov_b64 s[0:1], -1
	s_cbranch_vccnz .LBB0_609
	s_mov_b64 s[0:1], 0

; __device__ __forceinline__ int crow(int r,int hi){return (r&3)+8*(r>>2)+4*hi;}
; #define SBAR() __builtin_amdgcn_sched_barrier(0)
;   #define RESC() do{ if(resc){ asm volatile("s_waitcnt lgkmcnt(0)":::"memory"); \
;       _Pragma("unroll") for(int d_=0;d_<2;++d_) _Pragma("unroll") for(int r=0;r<16;++r)o[d_][r]*=wsf[crow(r,hi)]; } }while(0)
; __device__ __forceinline__ void pv(f32x16*o,int vb,bf16x8 pa0,bf16x8 pa1,bf16x8 pa2,bf16x8 pa3){
;   #pragma unroll
;   for(int d0=0;d0<2;++d0){s16x4 lo[4],hi[4];
;     #pragma unroll
;     for(int ks=0;ks<4;++ks){
;       asm volatile("ds_read_b64_tr_b16 %0,%1 offset:%c2":"=&v"(lo[ks]):"v"(vb),"i"(d0*4096+ks*1024):"memory");
;       asm volatile("ds_read_b64_tr_b16 %0,%1 offset:%c2":"=&v"(hi[ks]):"v"(vb),"i"(d0*4096+ks*1024+512):"memory");}
;     asm volatile("s_waitcnt lgkmcnt(0)":::"memory");SBAR();
;     ...
;     o[d0]=__builtin_amdgcn_mfma_f32_32x32x16_bf16(pa0,PK(0),o[d0],0,0,0);
;     o[d0]=__builtin_amdgcn_mfma_f32_32x32x16_bf16(pa1,PK(1),o[d0],0,0,0);
;     o[d0]=__builtin_amdgcn_mfma_f32_32x32x16_bf16(pa2,PK(2),o[d0],0,0,0);
;     o[d0]=__builtin_amdgcn_mfma_f32_32x32x16_bf16(pa3,PK(3),o[d0],0,0,0);
;     ...
;   }
; template<int THRL,int MODE> __device__ __forceinline__ void attn_unit128(const bf16*Qblk,const bf16*__restrict__ Kh,const bf16*__restrict__ Vh,bf16*Oblk,const int NT,char*shm,const bf16*O1blk,bf16*AOblk,const float lam,const float*sln,const float omli){
;     ...
;   STEP(pB0,pB1,pA0,pA1,NT-1,false,false,false); RESC();
;   { float sacc=pB0[0]+pB0[1]; _Pragma("unroll") for(int r=2;r<16;++r)sacc+=pB0[r]; _Pragma("unroll") for(int r=0;r<16;++r)sacc+=pB1[r]; l_reg+=sacc;
;     pw0=(u32x4){PKW(pB0,0),PKW(pB0,2),PKW(pB0,4),PKW(pB0,6)};pw1=(u32x4){PKW(pB0,8),PKW(pB0,10),PKW(pB0,12),PKW(pB0,14)};pw2=(u32x4){PKW(pB1,0),PKW(pB1,2),PKW(pB1,4),PKW(pB1,6)};pw3=(u32x4){PKW(pB1,8),PKW(pB1,10),PKW(pB1,12),PKW(pB1,14)};
;     SBAR(); { const int vb0=(int)(unsigned)(size_t)vp0; pv(o,vb0+2*sl_cur,PAF(0),PAF(1),PAF(2),PAF(3)); pv(o+2,vb0+2*sl_cur+8192,PAF(0),PAF(1),PAF(2),PAF(3)); } }
;     ...
;   {auto rr=__builtin_amdgcn_permlane32_swap(__float_as_uint(l_reg),__float_as_uint(l_reg),false,false);l_reg=__uint_as_float(rr[0])+__uint_as_float(rr[1]);}
;   if(hi==0)wsf[32+r32]=l_reg;asm volatile("s_waitcnt lgkmcnt(0)":::"memory");
;   float rli[16];
;   #pragma unroll
;   for(int r=0;r<16;++r)rli[r]=__builtin_amdgcn_rcpf(wsf[32+crow(r,hi)]);
.LBB0_525:
	v_add_f32_e32 v83, v98, v99
	v_add_f32_e32 v83, v100, v83
	v_add_f32_e32 v83, v101, v83
	v_add_f32_e32 v83, v102, v83
	v_add_f32_e32 v83, v103, v83
	v_add_f32_e32 v83, v104, v83
	v_add_f32_e32 v83, v105, v83
	v_add_f32_e32 v83, v106, v83
	v_add_f32_e32 v83, v107, v83
	v_add_f32_e32 v83, v108, v83
	v_add_f32_e32 v83, v109, v83
	v_add_f32_e32 v83, v110, v83
	v_add_f32_e32 v83, v111, v83
	v_add_f32_e32 v83, v112, v83
	v_add_f32_e32 v83, v113, v83
	v_add_f32_e32 v83, v83, v2
	v_add_f32_e32 v83, v3, v83
	v_add_f32_e32 v83, v4, v83
	v_add_f32_e32 v83, v5, v83
	v_add_f32_e32 v83, v6, v83
	v_add_f32_e32 v83, v7, v83
	v_add_f32_e32 v83, v8, v83
	v_add_f32_e32 v83, v9, v83
	v_add_f32_e32 v83, v10, v83
	v_add_f32_e32 v83, v11, v83
	v_add_f32_e32 v83, v12, v83
	v_add_f32_e32 v83, v13, v83
	v_add_f32_e32 v83, v14, v83
	v_add_f32_e32 v83, v15, v83
	v_add_f32_e32 v83, v16, v83
	v_add_f32_e32 v83, v17, v83
	v_add_f32_e32 v0, v0, v83
	v_cvt_pk_bf16_f32 v2, v2, v3
	v_cvt_pk_bf16_f32 v84, v98, v99
	v_cvt_pk_bf16_f32 v85, v100, v101
	v_cvt_pk_bf16_f32 v86, v102, v103
	v_cvt_pk_bf16_f32 v87, v104, v105
	v_cvt_pk_bf16_f32 v88, v106, v107
	v_cvt_pk_bf16_f32 v89, v108, v109
	v_cvt_pk_bf16_f32 v90, v110, v111
	v_cvt_pk_bf16_f32 v91, v112, v113
	v_cvt_pk_bf16_f32 v3, v4, v5
	v_cvt_pk_bf16_f32 v4, v6, v7
	v_cvt_pk_bf16_f32 v5, v8, v9
	v_cvt_pk_bf16_f32 v6, v10, v11
	v_cvt_pk_bf16_f32 v7, v12, v13
	v_cvt_pk_bf16_f32 v8, v14, v15
	v_cvt_pk_bf16_f32 v9, v16, v17
	ds_read_b64_tr_b16 v[10:11],v82 offset:0
	ds_read_b64_tr_b16 v[12:13],v82 offset:512
	ds_read_b64_tr_b16 v[14:15],v82 offset:1024
	ds_read_b64_tr_b16 v[16:17],v82 offset:1536
	ds_read_b64_tr_b16 v[92:93],v82 offset:2048
	ds_read_b64_tr_b16 v[94:95],v82 offset:2560
	ds_read_b64_tr_b16 v[96:97],v82 offset:3072
	ds_read_b64_tr_b16 v[98:99],v82 offset:3584
	s_waitcnt lgkmcnt(0)
	s_nop 0
	v_mfma_f32_32x32x16_bf16 v[18:33], v[84:87], v[10:13], v[18:33]
	ds_read_b64_tr_b16 v[10:11],v82 offset:4096
	ds_read_b64_tr_b16 v[12:13],v82 offset:4608
	v_mfma_f32_32x32x16_bf16 v[18:33], v[88:91], v[14:17], v[18:33]
	ds_read_b64_tr_b16 v[14:15],v82 offset:5120
	ds_read_b64_tr_b16 v[16:17],v82 offset:5632
	v_mfma_f32_32x32x16_bf16 v[18:33], v[2:5], v[92:95], v[18:33]
	ds_read_b64_tr_b16 v[92:93],v82 offset:6144
	ds_read_b64_tr_b16 v[94:95],v82 offset:6656
	v_mfma_f32_32x32x16_bf16 v[18:33], v[6:9], v[96:99], v[18:33]
	ds_read_b64_tr_b16 v[96:97],v82 offset:7168
	ds_read_b64_tr_b16 v[98:99],v82 offset:7680
	s_waitcnt lgkmcnt(0)
	v_mfma_f32_32x32x16_bf16 v[34:49], v[84:87], v[10:13], v[34:49]
	v_add_u32_e32 v82, 0x2000, v82
	ds_read_b64_tr_b16 v[10:11],v82 offset:0
	ds_read_b64_tr_b16 v[12:13],v82 offset:512
	v_mfma_f32_32x32x16_bf16 v[34:49], v[88:91], v[14:17], v[34:49]
	ds_read_b64_tr_b16 v[14:15],v82 offset:1024
	ds_read_b64_tr_b16 v[16:17],v82 offset:1536
	v_mfma_f32_32x32x16_bf16 v[34:49], v[2:5], v[92:95], v[34:49]
	ds_read_b64_tr_b16 v[92:93],v82 offset:2048
	ds_read_b64_tr_b16 v[94:95],v82 offset:2560
	v_mfma_f32_32x32x16_bf16 v[34:49], v[6:9], v[96:99], v[34:49]
	ds_read_b64_tr_b16 v[96:97],v82 offset:3072
	ds_read_b64_tr_b16 v[98:99],v82 offset:3584
	s_waitcnt lgkmcnt(0)
	v_mfma_f32_32x32x16_bf16 v[50:65], v[84:87], v[10:13], v[50:65]
	ds_read_b64_tr_b16 v[10:11],v82 offset:4096
	ds_read_b64_tr_b16 v[12:13],v82 offset:4608
	v_mfma_f32_32x32x16_bf16 v[50:65], v[88:91], v[14:17], v[50:65]
	ds_read_b64_tr_b16 v[14:15],v82 offset:5120
	ds_read_b64_tr_b16 v[16:17],v82 offset:5632
	v_mfma_f32_32x32x16_bf16 v[50:65], v[2:5], v[92:95], v[50:65]
	ds_read_b64_tr_b16 v[92:93],v82 offset:6144
	ds_read_b64_tr_b16 v[94:95],v82 offset:6656
	v_mfma_f32_32x32x16_bf16 v[50:65], v[6:9], v[96:99], v[50:65]
	ds_read_b64_tr_b16 v[96:97],v82 offset:7168
	ds_read_b64_tr_b16 v[98:99],v82 offset:7680
	s_waitcnt lgkmcnt(0)
	v_mfma_f32_32x32x16_bf16 v[66:81], v[84:87], v[10:13], v[66:81]
	v_mfma_f32_32x32x16_bf16 v[66:81], v[88:91], v[14:17], v[66:81]
	v_mfma_f32_32x32x16_bf16 v[66:81], v[2:5], v[92:95], v[66:81]
	v_mov_b32_e32 v2, v0
	s_nop 1
	v_permlane32_swap_b32_e32 v0, v2
	v_mfma_f32_32x32x16_bf16 v[66:81], v[6:9], v[96:99], v[66:81]
	s_and_saveexec_b64 s[0:1], s[40:41]
	v_add_f32_e32 v0, v0, v2
	ds_write_b32 v216, v0 offset:128
	s_or_b64 exec, exec, s[0:1]
	s_waitcnt lgkmcnt(0)
	ds_read_b128 v[2:5], v217 offset:128
	ds_read_b128 v[6:9], v217 offset:160
	s_mul_i32 s1, s28, 0x30c0000
	v_readlane_b32 s26, v254, 63
	s_mul_hi_u32 s0, s28, 0x30c0000
	s_add_u32 s1, s26, s1
	v_readlane_b32 s26, v255, 0
	s_addc_u32 s26, s26, s0
	s_lshl_b32 s0, s36, 9
	s_add_u32 s0, s1, s0
	s_waitcnt lgkmcnt(1)
	v_rcp_f32_e32 v12, v2
	v_rcp_f32_e32 v13, v3
	v_rcp_f32_e32 v14, v4
	v_rcp_f32_e32 v15, v5
	ds_read_b128 v[2:5], v217 offset:192
	s_addc_u32 s1, s26, 0
	s_waitcnt lgkmcnt(1)
	v_rcp_f32_e32 v16, v6
	v_rcp_f32_e32 v17, v7
	v_rcp_f32_e32 v82, v8
	v_rcp_f32_e32 v83, v9
	ds_read_b128 v[6:9], v217 offset:224
	s_mul_i32 s26, s33, 0x18000
	s_mul_hi_i32 s27, s33, 0x18000
	s_add_u32 s26, s0, s26
	s_addc_u32 s27, s1, s27
	s_lshl_b32 s31, s33, 12
	s_add_i32 s31, s31, 0
	s_waitcnt lgkmcnt(1)
	v_rcp_f32_e32 v84, v2
	s_add_i32 s31, s31, 0x12800
	v_lshlrev_b32_e32 v0, 9, v214
	v_lshlrev_b32_e32 v2, 1, v213
	s_waitcnt lgkmcnt(0)
; __device__ __forceinline__ int crow(int r,int hi){return (r&3)+8*(r>>2)+4*hi;}
; template<int THRL,int MODE> __device__ __forceinline__ void attn_unit128(const bf16*Qblk,const bf16*__restrict__ Kh,const bf16*__restrict__ Vh,bf16*Oblk,const int NT,char*shm,const bf16*O1blk,bf16*AOblk,const float lam,const float*sln,const float omli){
;     ...
;   float rli[16];
;   #pragma unroll
;   for(int r=0;r<16;++r)rli[r]=__builtin_amdgcn_rcpf(wsf[32+crow(r,hi)]);
;   bf16*Ow=Oblk+(long)wid*QBLK*PO;
;   if constexpr(MODE==0)
;   { bf16*stg=(bf16*)(shm+LDS_OST8)+wid*2048;
;     #pragma unroll
;     for(int h2=0;h2<2;++h2){
;       #pragma unroll
;       for(int r=0;r<16;++r){const int orow=crow(r,hi);
;         #pragma unroll
;         for(int d0=0;d0<2;++d0)stg[orow*64+d0*32+r32]=__float2bfloat16(o[2*h2+d0][r]*rli[r]);}
;       asm volatile("s_waitcnt lgkmcnt(0)":::"memory");
;       #pragma unroll
;       for(int i=0;i<4;++i){const int row=i*8+(lane>>3),ch=lane&7; const u32x4 v=*(const u32x4*)(stg+row*64+ch*8); ATTN_STORE16(Ow+(long)row*PO+h2*64+ch*8,v);}
;       asm volatile("s_waitcnt lgkmcnt(0)":::"memory");
	v_rcp_f32_e32 v90, v8
	v_add3_u32 v92, s31, v0, v2
	v_lshrrev_b32_e32 v8, 3, v212
	v_lshlrev_b32_e32 v0, 1, v215
	v_and_b32_e32 v0, 0x70, v0
	v_lshlrev_b32_e32 v2, 7, v8
	v_rcp_f32_e32 v88, v6
	v_rcp_f32_e32 v89, v7
	v_lshl_add_u64 v[6:7], s[26:27], 0, v[0:1]
	v_add3_u32 v93, s31, v0, v2
	v_mul_f32_e32 v0, v18, v12
	v_cvt_pk_bf16_f32 v0, v0, s0
	ds_write_b16 v92, v0
	v_mul_f32_e32 v0, v34, v12
	v_cvt_pk_bf16_f32 v0, v0, s0
	ds_write_b16 v92, v0 offset:64
	v_mul_f32_e32 v0, v19, v13
	v_cvt_pk_bf16_f32 v0, v0, s0
	ds_write_b16 v92, v0 offset:128
	v_mul_f32_e32 v0, v35, v13
	v_cvt_pk_bf16_f32 v0, v0, s0
	ds_write_b16 v92, v0 offset:192
	v_mul_f32_e32 v0, v20, v14
	v_cvt_pk_bf16_f32 v0, v0, s0
	ds_write_b16 v92, v0 offset:256
	v_mul_f32_e32 v0, v36, v14
	v_cvt_pk_bf16_f32 v0, v0, s0
	ds_write_b16 v92, v0 offset:320
	v_mul_f32_e32 v0, v21, v15
	v_cvt_pk_bf16_f32 v0, v0, s0
	ds_write_b16 v92, v0 offset:384
	v_mul_f32_e32 v0, v37, v15
	v_cvt_pk_bf16_f32 v0, v0, s0
	ds_write_b16 v92, v0 offset:448
	v_mul_f32_e32 v0, v22, v16
	v_cvt_pk_bf16_f32 v0, v0, s0
	ds_write_b16 v92, v0 offset:1024
	v_mul_f32_e32 v0, v38, v16
	v_cvt_pk_bf16_f32 v0, v0, s0
	ds_write_b16 v92, v0 offset:1088
	v_mul_f32_e32 v0, v23, v17
	v_cvt_pk_bf16_f32 v0, v0, s0
	ds_write_b16 v92, v0 offset:1152
	v_mul_f32_e32 v0, v39, v17
	v_cvt_pk_bf16_f32 v0, v0, s0
	ds_write_b16 v92, v0 offset:1216
	v_mul_f32_e32 v0, v24, v82
	v_cvt_pk_bf16_f32 v0, v0, s0
	ds_write_b16 v92, v0 offset:1280
	v_mul_f32_e32 v0, v40, v82
	v_cvt_pk_bf16_f32 v0, v0, s0
	ds_write_b16 v92, v0 offset:1344
	v_mul_f32_e32 v0, v25, v83
	v_cvt_pk_bf16_f32 v0, v0, s0
	ds_write_b16 v92, v0 offset:1408
	v_mul_f32_e32 v0, v41, v83
	v_cvt_pk_bf16_f32 v0, v0, s0
	v_rcp_f32_e32 v85, v3
	ds_write_b16 v92, v0 offset:1472
	v_mul_f32_e32 v0, v26, v84
	v_cvt_pk_bf16_f32 v0, v0, s0
	ds_write_b16 v92, v0 offset:2048
	v_mul_f32_e32 v0, v42, v84
	v_cvt_pk_bf16_f32 v0, v0, s0
	v_rcp_f32_e32 v86, v4
	ds_write_b16 v92, v0 offset:2112
	v_mul_f32_e32 v0, v27, v85
	v_cvt_pk_bf16_f32 v0, v0, s0
	ds_write_b16 v92, v0 offset:2176
	v_mul_f32_e32 v0, v43, v85
	v_cvt_pk_bf16_f32 v0, v0, s0
	v_rcp_f32_e32 v87, v5
	ds_write_b16 v92, v0 offset:2240
	v_mul_f32_e32 v0, v28, v86
	v_cvt_pk_bf16_f32 v0, v0, s0
	ds_write_b16 v92, v0 offset:2304
	v_mul_f32_e32 v0, v44, v86
	v_cvt_pk_bf16_f32 v0, v0, s0
	ds_write_b16 v92, v0 offset:2368
	v_mul_f32_e32 v0, v29, v87
	v_cvt_pk_bf16_f32 v0, v0, s0
	ds_write_b16 v92, v0 offset:2432
	v_mul_f32_e32 v0, v45, v87
	v_cvt_pk_bf16_f32 v0, v0, s0
	ds_write_b16 v92, v0 offset:2496
	v_mul_f32_e32 v0, v30, v88
	v_cvt_pk_bf16_f32 v0, v0, s0
	ds_write_b16 v92, v0 offset:3072
	v_mul_f32_e32 v0, v46, v88
	v_cvt_pk_bf16_f32 v0, v0, s0
	ds_write_b16 v92, v0 offset:3136
	v_mul_f32_e32 v0, v31, v89
	v_cvt_pk_bf16_f32 v0, v0, s0
	ds_write_b16 v92, v0 offset:3200
	v_mul_f32_e32 v0, v47, v89
	v_cvt_pk_bf16_f32 v0, v0, s0
	v_rcp_f32_e32 v91, v9
	ds_write_b16 v92, v0 offset:3264
	v_mul_f32_e32 v0, v32, v90
	v_cvt_pk_bf16_f32 v0, v0, s0
	ds_write_b16 v92, v0 offset:3328
	v_mul_f32_e32 v0, v48, v90
	v_cvt_pk_bf16_f32 v0, v0, s0
	ds_write_b16 v92, v0 offset:3392
	v_mul_f32_e32 v0, v33, v91
	v_cvt_pk_bf16_f32 v0, v0, s0
	ds_write_b16 v92, v0 offset:3456
	v_mul_f32_e32 v0, v49, v91
	v_cvt_pk_bf16_f32 v0, v0, s0
	ds_write_b16 v92, v0 offset:3520
	s_waitcnt lgkmcnt(0)
	ds_read_b128 v[2:5], v93
	v_mul_u32_u24_e32 v0, 0x600, v8
	v_lshlrev_b32_e32 v0, 1, v0
	v_lshl_add_u64 v[18:19], v[6:7], 0, v[0:1]
	ds_read_b128 v[6:9], v93 offset:1024
	s_mov_b64 s[26:27], 0x6000
	v_lshl_add_u64 v[20:21], v[18:19], 0, s[26:27]
	s_movk_i32 s26, 0x6000
	s_waitcnt lgkmcnt(1)
	global_store_dwordx4 v[18:19], v[2:5], off
	v_mul_f32_e32 v0, v50, v12
	v_cvt_pk_bf16_f32 v0, v0, s0
	v_add_co_u32_e32 v2, vcc, s26, v18
	s_mov_b64 s[26:27], 0xc000
	s_nop 0
	v_addc_co_u32_e32 v3, vcc, 0, v19, vcc
	s_waitcnt lgkmcnt(0)
	global_store_dwordx4 v[2:3], v[6:9], off
	ds_read_b128 v[2:5], v93 offset:2048
	ds_read_b128 v[6:9], v93 offset:3072
	v_lshl_add_u64 v[22:23], v[18:19], 0, s[26:27]
	s_mov_b32 s26, 0xc000
	v_add_co_u32_e32 v10, vcc, s26, v18
	s_mov_b32 s26, 0x12000
	s_nop 0
	v_addc_co_u32_e32 v11, vcc, 0, v19, vcc
	s_waitcnt lgkmcnt(1)
	global_store_dwordx4 v[10:11], v[2:5], off
	v_mov_b32_e32 v213, v220
	s_nop 0
	v_add_co_u32_e32 v2, vcc, s26, v18
	s_mov_b64 s[26:27], 0x12000
	s_nop 0
	v_addc_co_u32_e32 v3, vcc, 0, v19, vcc
	s_waitcnt lgkmcnt(0)
	global_store_dwordx4 v[2:3], v[6:9], off
	s_waitcnt lgkmcnt(0)
; template<int THRL,int MODE> __device__ __forceinline__ void attn_unit128(const bf16*Qblk,const bf16*__restrict__ Kh,const bf16*__restrict__ Vh,bf16*Oblk,const int NT,char*shm,const bf16*O1blk,bf16*AOblk,const float lam,const float*sln,const float omli){
;     ...
;   const unsigned koff=(unsigned)(lane*PQ+wid*8)*2u;
;   const unsigned voff=(unsigned)((16*(wid&3)+(lane>>2))*PQ+(wid>>2)*32+(lane&3)*8)*2u;
;   const unsigned kdst=lds0+LDS_K+wid*1024, vdst=lds0+LDS_V+wid*1024;
;     ...
;   const char*Kbase=shm+LDS_K; bf16x8 kf[8];
;     ...
;       #pragma unroll
;       for(int i=0;i<4;++i){const int row=i*8+(lane>>3),ch=lane&7; const u32x4 v=*(const u32x4*)(stg+row*64+ch*8); ATTN_STORE16(Ow+(long)row*PO+h2*64+ch*8,v);}
;       asm volatile("s_waitcnt lgkmcnt(0)":::"memory");
;     } }
;   else {
;     bf16*stg=(bf16*)(shm+LDS_OST8)+wid*4096;
;     #pragma unroll
;     for(int r=0;r<16;++r){const int orow=crow(r,hi);
;       #pragma unroll
;       for(int d0=0;d0<4;++d0)stg[orow*128+d0*32+r32]=__float2bfloat16(o[d0][r]*rli[r]);}
;     asm volatile("s_waitcnt lgkmcnt(0)":::"memory");
;     const int rr=lane>>4,ch=lane&15;
;     const f32x4_t s0=*(const f32x4_t*)(sln+ch*8), s1=*(const f32x4_t*)(sln+ch*8+4);
;     const bf16*O1w=O1blk+((long)wid*QBLK+rr)*PO+ch*8; bf16*AOw=AOblk+((long)wid*QBLK+rr)*1024+ch*8;
;     u32x4 a1[8];
;     #pragma unroll
;     for(int i=0;i<8;++i)a1[i]=*(const u32x4*)(O1w+(long)(4*i)*PO);
;     #pragma unroll
;     for(int i=0;i<8;++i){ const u32x4 a2=*(const u32x4*)(stg+(rr+4*i)*128+ch*8);
;       float x[8]; float ss=0.f;
;       #pragma unroll
;       for(int c=0;c<4;++c){const unsigned u1=a1[i][c],u2=a2[c];
;         const float lo=__uint_as_float(u1<<16)-lam*__uint_as_float(u2<<16), hi2=__uint_as_float(u1&0xffff0000u)-lam*__uint_as_float(u2&0xffff0000u);
;         x[2*c]=lo; x[2*c+1]=hi2; ss+=lo*lo+hi2*hi2;}
;       ss+=__shfl_xor(ss,1); ss+=__shfl_xor(ss,2); ss+=__shfl_xor(ss,4); ss+=__shfl_xor(ss,8);
;       const float rstd=1.f/sqrtf(ss*(1.f/128.f)+1e-6f)*omli;
;       u32x4 w; w[0]=cvtpk_s(x[0]*rstd*s0[0],x[1]*rstd*s0[1]); w[1]=cvtpk_s(x[2]*rstd*s0[2],x[3]*rstd*s0[3]);
;       w[2]=cvtpk_s(x[4]*rstd*s1[0],x[5]*rstd*s1[1]); w[3]=cvtpk_s(x[6]*rstd*s1[2],x[7]*rstd*s1[3]);
;       ATTN_STORE16(AOw+(long)(4*i)*1024,w);}
;     asm volatile("s_waitcnt lgkmcnt(0)":::"memory");
;   }
;   asm volatile("s_waitcnt lgkmcnt(0)\n\ts_barrier":::"memory");
	ds_write_b16 v92, v0
	v_mul_f32_e32 v0, v66, v12
	v_cvt_pk_bf16_f32 v0, v0, s0
	ds_write_b16 v92, v0 offset:64
	v_mul_f32_e32 v0, v51, v13
	v_cvt_pk_bf16_f32 v0, v0, s0
	ds_write_b16 v92, v0 offset:128
	v_mul_f32_e32 v0, v67, v13
	v_cvt_pk_bf16_f32 v0, v0, s0
	ds_write_b16 v92, v0 offset:192
	v_mul_f32_e32 v0, v52, v14
	v_cvt_pk_bf16_f32 v0, v0, s0
	ds_write_b16 v92, v0 offset:256
	v_mul_f32_e32 v0, v68, v14
	v_cvt_pk_bf16_f32 v0, v0, s0
	ds_write_b16 v92, v0 offset:320
	v_mul_f32_e32 v0, v53, v15
	v_cvt_pk_bf16_f32 v0, v0, s0
	ds_write_b16 v92, v0 offset:384
	v_mul_f32_e32 v0, v69, v15
	v_cvt_pk_bf16_f32 v0, v0, s0
	ds_write_b16 v92, v0 offset:448
	v_mul_f32_e32 v0, v54, v16
	v_cvt_pk_bf16_f32 v0, v0, s0
	ds_write_b16 v92, v0 offset:1024
	v_mul_f32_e32 v0, v70, v16
	v_cvt_pk_bf16_f32 v0, v0, s0
	ds_write_b16 v92, v0 offset:1088
	v_mul_f32_e32 v0, v55, v17
	v_cvt_pk_bf16_f32 v0, v0, s0
	ds_write_b16 v92, v0 offset:1152
	v_mul_f32_e32 v0, v71, v17
	v_cvt_pk_bf16_f32 v0, v0, s0
	ds_write_b16 v92, v0 offset:1216
	v_mul_f32_e32 v0, v56, v82
	v_cvt_pk_bf16_f32 v0, v0, s0
	ds_write_b16 v92, v0 offset:1280
	v_mul_f32_e32 v0, v72, v82
	v_cvt_pk_bf16_f32 v0, v0, s0
	ds_write_b16 v92, v0 offset:1344
	v_mul_f32_e32 v0, v57, v83
	v_cvt_pk_bf16_f32 v0, v0, s0
	ds_write_b16 v92, v0 offset:1408
	v_mul_f32_e32 v0, v73, v83
	v_cvt_pk_bf16_f32 v0, v0, s0
	ds_write_b16 v92, v0 offset:1472
	v_mul_f32_e32 v0, v58, v84
	v_cvt_pk_bf16_f32 v0, v0, s0
	ds_write_b16 v92, v0 offset:2048
	v_mul_f32_e32 v0, v74, v84
	v_cvt_pk_bf16_f32 v0, v0, s0
	ds_write_b16 v92, v0 offset:2112
	v_mul_f32_e32 v0, v59, v85
	v_cvt_pk_bf16_f32 v0, v0, s0
	ds_write_b16 v92, v0 offset:2176
	v_mul_f32_e32 v0, v75, v85
	v_cvt_pk_bf16_f32 v0, v0, s0
	ds_write_b16 v92, v0 offset:2240
	v_mul_f32_e32 v0, v60, v86
	v_cvt_pk_bf16_f32 v0, v0, s0
	ds_write_b16 v92, v0 offset:2304
	v_mul_f32_e32 v0, v76, v86
	v_cvt_pk_bf16_f32 v0, v0, s0
	ds_write_b16 v92, v0 offset:2368
	v_mul_f32_e32 v0, v61, v87
	v_cvt_pk_bf16_f32 v0, v0, s0
	ds_write_b16 v92, v0 offset:2432
	v_mul_f32_e32 v0, v77, v87
	v_cvt_pk_bf16_f32 v0, v0, s0
	ds_write_b16 v92, v0 offset:2496
	v_mul_f32_e32 v0, v62, v88
	v_cvt_pk_bf16_f32 v0, v0, s0
	ds_write_b16 v92, v0 offset:3072
	v_mul_f32_e32 v0, v78, v88
	v_cvt_pk_bf16_f32 v0, v0, s0
	ds_write_b16 v92, v0 offset:3136
	v_mul_f32_e32 v0, v63, v89
	v_cvt_pk_bf16_f32 v0, v0, s0
	ds_write_b16 v92, v0 offset:3200
	v_mul_f32_e32 v0, v79, v89
	v_cvt_pk_bf16_f32 v0, v0, s0
	ds_write_b16 v92, v0 offset:3264
	v_mul_f32_e32 v0, v64, v90
	v_cvt_pk_bf16_f32 v0, v0, s0
	ds_write_b16 v92, v0 offset:3328
	v_mul_f32_e32 v0, v80, v90
	v_cvt_pk_bf16_f32 v0, v0, s0
	ds_write_b16 v92, v0 offset:3392
	v_mul_f32_e32 v0, v65, v91
	v_cvt_pk_bf16_f32 v0, v0, s0
	ds_write_b16 v92, v0 offset:3456
	v_mul_f32_e32 v0, v81, v91
	v_cvt_pk_bf16_f32 v0, v0, s0
	ds_write_b16 v92, v0 offset:3520
	s_waitcnt lgkmcnt(0)
	ds_read_b128 v[2:5], v93
	ds_read_b128 v[6:9], v93 offset:1024
	ds_read_b128 v[10:13], v93 offset:2048
	ds_read_b128 v[14:17], v93 offset:3072
	v_lshl_add_u64 v[24:25], v[18:19], 0, s[26:27]
	s_waitcnt lgkmcnt(3)
	global_store_dwordx4 v[18:19], v[2:5], off offset:128
	s_waitcnt lgkmcnt(2)
	global_store_dwordx4 v[20:21], v[6:9], off offset:128
	s_waitcnt lgkmcnt(1)
	global_store_dwordx4 v[22:23], v[10:13], off offset:128
	s_waitcnt lgkmcnt(0)
	global_store_dwordx4 v[24:25], v[14:17], off offset:128
	s_waitcnt lgkmcnt(0)
	s_waitcnt lgkmcnt(0)
	s_barrier
	v_mov_b32_e32 v5, v1
	v_readfirstlane_b32 s26, v213
	s_ashr_i32 s36, s26, 6
	s_mul_i32 s31, s36, 0x24000
	s_mul_hi_i32 s27, s36, 0x24000
	s_add_u32 s40, s6, s31
	s_addc_u32 s41, s7, s27
	s_and_b32 s31, s26, 0x3fffffc0
	s_ashr_i32 s26, s26, 3
	s_lshl_b32 s27, s36, 4
	v_bfe_u32 v2, v213, 2, 4
	s_and_b32 s26, s26, 0x7fffffe0
	v_and_or_b32 v2, s27, 48, v2
	v_mov_b32_e32 v3, s26
	s_movk_i32 s26, 0x900
	v_mad_u32_u24 v2, v2, s26, v3
	v_lshlrev_b32_e32 v3, 3, v213
	v_and_b32_e32 v39, 63, v213
	v_mov_b32_e32 v0, s27
	v_and_b32_e32 v36, 24, v3
	s_lshl_b32 s26, s36, 10
	v_mad_u32_u24 v0, v39, s81, v0
	v_or_b32_e32 v2, v2, v36
	s_cmp_lg_u32 0, -1
	v_lshlrev_b32_e32 v4, 1, v2
	s_cselect_b32 s27, 0, 0
	v_lshl_add_u64 v[34:35], s[6:7], 0, v[0:1]
	s_mov_b64 s[6:7], 0x600
	s_add_i32 s27, s27, s26
	v_lshl_add_u64 v[2:3], v[34:35], 0, s[6:7]
	s_mov_b32 s6, m0
	s_mov_b32 m0, s27
	s_nop 0
	global_load_lds_dwordx4 v[2:3], off
	s_mov_b32 m0, s6
	v_mov_b32_e32 v0, v4
	s_add_i32 s26, s27, 0x6000
	v_lshl_add_u64 v[2:3], s[4:5], 0, v[0:1]
	s_mov_b32 s4, m0
	s_mov_b32 m0, s26
	s_nop 0
	global_load_lds_dwordx4 v[2:3], off
	s_mov_b32 m0, s4
	v_lshl_add_u64 v[2:3], s[8:9], 0, v[0:1]
	s_add_i32 s4, s27, 0x8000
	s_mov_b32 s5, m0
	s_mov_b32 m0, s4
	s_nop 0
	global_load_lds_dwordx4 v[2:3], off
	s_mov_b32 m0, s5
	s_mov_b64 s[4:5], 0x48600
	v_and_b32_e32 v212, 31, v213
	v_lshl_add_u64 v[2:3], v[34:35], 0, s[4:5]
	s_add_i32 s4, s27, 0x2000
	s_mov_b32 s5, m0
	s_mov_b32 m0, s4
	s_nop 0
	global_load_lds_dwordx4 v[2:3], off
	s_mov_b32 m0, s5
	v_mul_u32_u24_e32 v2, 0x900, v212
	v_bfe_u32 v38, v213, 5, 1
	v_lshlrev_b32_e32 v2, 1, v2
	v_lshl_or_b32 v2, v38, 4, v2
	global_load_dwordx4 v[174:177], v2, s[40:41] offset:512
	global_load_dwordx4 v[170:173], v2, s[40:41] offset:544
	global_load_dwordx4 v[166:169], v2, s[40:41] offset:576
	global_load_dwordx4 v[162:165], v2, s[40:41] offset:608
	v_lshlrev_b32_e32 v214, 10, v38
	v_lshlrev_b32_e32 v3, 4, v212
	v_add_u32_e32 v2, 0, v214
	v_add_u32_e32 v234, v2, v3
	v_mov_b32_e32 v2, v1
	v_mov_b32_e32 v3, v1
	v_mov_b32_e32 v4, v1
	v_mov_b32_e32 v6, v1
	v_mov_b32_e32 v7, v1
	v_mov_b32_e32 v8, v1
	v_mov_b32_e32 v9, v1
	v_mov_b32_e32 v10, v1
	v_mov_b32_e32 v11, v1
	v_mov_b32_e32 v12, v1
	v_mov_b32_e32 v13, v1
	v_mov_b32_e32 v14, v1
	v_mov_b32_e32 v15, v1
	v_mov_b32_e32 v16, v1
	v_mov_b32_e32 v17, v1
	s_mov_b64 s[4:5], 0x90600
	v_lshl_add_u64 v[18:19], v[34:35], 0, s[4:5]
	s_add_i32 s4, s27, 0x4000
	s_mov_b32 s5, m0
	s_mov_b32 m0, s4
	s_nop 0
	global_load_lds_dwordx4 v[18:19], off
	s_mov_b32 m0, s5
	s_waitcnt vmcnt(4) lgkmcnt(0)
	s_barrier
; #define WAIT_BAR(N) asm volatile("s_waitcnt vmcnt(" #N ") lgkmcnt(0)\n\ts_barrier":::"memory")
;   #define DMA_K(t,slot) glds16(ksrc+(long)(t)*KVBLK*PQ,(unsigned)__builtin_amdgcn_readfirstlane(kdst+(slot)))
;   #define DMA_V(t,slot) glds16(vsrc+(long)(t)*KVBLK*PQ,(unsigned)__builtin_amdgcn_readfirstlane(vdst+(slot)))
;   #define CMASK(P0,P1,t) do{}while(0)
;   #define START(P0,P1) do{ const float rm=rowmax(P0,P1); resc=false; \
;     { const float dl=rm; mhat=fadd_s(mhat,dl); \
;       _Pragma("unroll") for(int r=0;r<16;++r){P0[r]=fsub_s(P0[r],dl);P1[r]=fsub_s(P1[r],dl);} \
;       _Pragma("unroll") for(int r=0;r<16;++r)negm[r]=-mhat; asm volatile("":"+v"(negm)); } \
;     _Pragma("unroll") for(int r=0;r<16;++r)P0[r]=__builtin_amdgcn_exp2f(P0[r]); }while(0)
;   #define ROT() do{sl_prev=sl_cur;sl_cur=sl_next;sl_next=(sl_next==(NSLOT-1)*SLOTB)?0:sl_next+SLOTB;}while(0)
;   #define CMASK(P0,P1,t) do{}while(0)
;   #define CMASK(P0,P1,t) do{}while(0)
;   #define DMA_K(t,slot) glds16((const char*)Kh+(size_t)(t)*(KVBLK*PQ*2)+koff,(unsigned)__builtin_amdgcn_readfirstlane(kdst+(slot)))
;   #define DMA_V(t,slot) do{ glds16((const char*)Vh+(size_t)(t)*(KVBLK*PQ*2)+voff,(unsigned)__builtin_amdgcn_readfirstlane(vdst+2*(slot))); glds16((const char*)Vh+(size_t)(t)*(KVBLK*PQ*2)+128+voff,(unsigned)__builtin_amdgcn_readfirstlane(vdst+2*(slot)+8192)); }while(0)
;   #define CMASK(P0,P1,t) do{}while(0)
;   #define START(P0,P1) do{ const float rm=rowmax(P0,P1); resc=false; \
;     { const float dl=rm; mhat=fadd_s(mhat,dl); \
;       _Pragma("unroll") for(int r=0;r<16;++r){P0[r]=fsub_s(P0[r],dl);P1[r]=fsub_s(P1[r],dl);} \
;       _Pragma("unroll") for(int r=0;r<16;++r)negm[r]=-mhat; asm volatile("":"+v"(negm)); } \
;     _Pragma("unroll") for(int r=0;r<16;++r)P0[r]=__builtin_amdgcn_exp2f(P0[r]); }while(0)
; template<int THRL,int MODE> __device__ __forceinline__ void attn_unit128(const bf16*Qblk,const bf16*__restrict__ Kh,const bf16*__restrict__ Vh,bf16*Oblk,const int NT,char*shm,const bf16*O1blk,bf16*AOblk,const float lam,const float*sln,const float omli){
;     ...
;   qkt(pA0,pA1,Kbase,qr,negm,r32,hi);asm volatile("s_nop 15\n\ts_nop 7":"+v"(pA0),"+v"(pA1));CMASK(pA0,pA1,0);
;   START(pA0,pA1);
;   _Pragma("unroll") for(int r=0;r<16;++r)pA1[r]=__builtin_amdgcn_exp2f(pA1[r]);
;   WAIT_BAR(0);
;   DMA_K(3,0);DMA_V(1,SLOTB);
;   ROT();
;   kload8(kf,kp0+sl_cur);
;   WAIT_BAR(3);
	ds_read_b128 v[40:43], v234
	ds_read_b128 v[44:47], v234 offset:512
	s_waitcnt vmcnt(3) lgkmcnt(1)
	v_mfma_f32_32x32x16_bf16 v[18:33], v[40:43], v[174:177], v[2:17]
	s_lshl_b32 s4, s31, 2
	s_add_i32 s8, s4, 0
	s_mov_b64 s[4:5], 0xd8600
	v_lshlrev_b32_e32 v37, 1, v213
	v_and_b32_e32 v37, 32, v37
	v_add3_u32 v36, 0, v37, v36
	v_lshlrev_b32_e32 v37, 8, v38
	s_waitcnt lgkmcnt(0)
	v_mfma_f32_32x32x16_bf16 v[2:17], v[44:47], v[174:177], v[2:17]
	ds_read_b128 v[40:43], v234 offset:2048
	ds_read_b128 v[44:47], v234 offset:2560
	s_add_i32 s8, s8, 0x12000
	v_cmp_gt_u32_e64 s[40:41], 32, v39
	v_lshl_add_u32 v215, v212, 2, s8
	s_waitcnt vmcnt(2) lgkmcnt(1)
	v_mfma_f32_32x32x16_bf16 v[18:33], v[40:43], v[170:173], v[18:33]
	s_waitcnt lgkmcnt(0)
	v_mfma_f32_32x32x16_bf16 v[2:17], v[44:47], v[170:173], v[2:17]
	ds_read_b128 v[40:43], v234 offset:4096
	ds_read_b128 v[44:47], v234 offset:4608
	s_waitcnt vmcnt(1) lgkmcnt(1)
	v_mfma_f32_32x32x16_bf16 v[18:33], v[40:43], v[166:169], v[18:33]
	s_waitcnt lgkmcnt(0)
	v_mfma_f32_32x32x16_bf16 v[2:17], v[44:47], v[166:169], v[2:17]
	ds_read_b128 v[40:43], v234 offset:6144
	ds_read_b128 v[44:47], v234 offset:6656
	s_waitcnt vmcnt(0) lgkmcnt(1)
	v_mfma_f32_32x32x16_bf16 v[18:33], v[40:43], v[162:165], v[18:33]
	v_lshlrev_b32_e32 v40, 4, v213
	v_and_b32_e32 v40, 0xc0, v40
	v_add3_u32 v217, v36, v37, v40
	s_waitcnt lgkmcnt(0)
	v_mfma_f32_32x32x16_bf16 v[2:17], v[44:47], v[162:165], v[2:17]
	s_nop 15
	s_nop 7
	s_nop 0
	v_max3_f32 v41, v18, v19, v2
	v_max3_f32 v42, v20, v21, v3
	s_nop 0
	v_max3_f32 v41, v41, v4, v5
	v_max3_f32 v42, v42, v24, v25
	s_nop 0
	v_max3_f32 v41, v41, v22, v23
	v_max3_f32 v42, v42, v8, v9
	s_nop 0
	v_max3_f32 v41, v41, v6, v7
	v_max3_f32 v42, v42, v28, v29
	s_nop 0
	v_max3_f32 v41, v41, v26, v27
	v_max3_f32 v42, v42, v12, v13
	s_nop 0
	v_max3_f32 v41, v41, v10, v11
	v_max3_f32 v42, v42, v32, v33
	s_nop 0
	v_max3_f32 v41, v41, v30, v31
	v_max3_f32 v42, v42, v16, v17
	s_nop 0
	v_max3_f32 v41, v41, v14, v15
	s_nop 0
	v_max_f32_e32 v41, v41, v42
	s_nop 0
	v_mov_b32_e32 v42, v41
	s_nop 1
	v_permlane32_swap_b32_e32 v41, v42
	v_max_f32_e32 v41, v41, v42
	s_nop 0
	v_add_f32_e32 v233, v1, v41
	v_sub_f32_e32 v42, v2, v41
	v_sub_f32_e32 v18, v18, v41
	v_sub_f32_e32 v19, v19, v41
	v_sub_f32_e32 v43, v3, v41
	v_sub_f32_e32 v20, v20, v41
	s_nop 0
	v_xor_b32_e32 v2, 0x80000000, v233
	v_sub_f32_e32 v44, v4, v41
	v_sub_f32_e32 v21, v21, v41
	v_sub_f32_e32 v45, v5, v41
	v_sub_f32_e32 v22, v22, v41
	v_sub_f32_e32 v46, v6, v41
	v_sub_f32_e32 v23, v23, v41
	v_sub_f32_e32 v47, v7, v41
	v_sub_f32_e32 v24, v24, v41
	v_sub_f32_e32 v48, v8, v41
	v_sub_f32_e32 v25, v25, v41
	v_sub_f32_e32 v49, v9, v41
	v_sub_f32_e32 v26, v26, v41
	v_sub_f32_e32 v50, v10, v41
	v_sub_f32_e32 v27, v27, v41
	v_sub_f32_e32 v51, v11, v41
	v_sub_f32_e32 v28, v28, v41
	v_sub_f32_e32 v52, v12, v41
	v_sub_f32_e32 v29, v29, v41
	v_sub_f32_e32 v53, v13, v41
	v_sub_f32_e32 v30, v30, v41
	v_sub_f32_e32 v54, v14, v41
	v_sub_f32_e32 v31, v31, v41
	v_sub_f32_e32 v55, v15, v41
	v_sub_f32_e32 v32, v32, v41
	v_sub_f32_e32 v56, v16, v41
	v_sub_f32_e32 v33, v33, v41
	v_sub_f32_e32 v41, v17, v41
	v_mov_b32_e32 v3, v2
	v_mov_b32_e32 v4, v2
	v_mov_b32_e32 v5, v2
	v_mov_b32_e32 v6, v2
	v_mov_b32_e32 v7, v2
	v_mov_b32_e32 v8, v2
	v_mov_b32_e32 v9, v2
	v_mov_b32_e32 v10, v2
	v_mov_b32_e32 v11, v2
	v_mov_b32_e32 v12, v2
	v_mov_b32_e32 v13, v2
	v_mov_b32_e32 v14, v2
	v_mov_b32_e32 v15, v2
	v_mov_b32_e32 v16, v2
	v_mov_b32_e32 v17, v2
	s_waitcnt vmcnt(0) lgkmcnt(0)
	s_barrier
	v_exp_f32_e32 v57, v18
	v_exp_f32_e32 v58, v19
	v_lshl_add_u64 v[18:19], v[34:35], 0, s[4:5]
	s_mov_b32 s4, m0
	s_mov_b32 m0, s27
	s_nop 0
	global_load_lds_dwordx4 v[18:19], off
	s_mov_b32 m0, s4
	v_lshl_add_u64 v[18:19], s[10:11], 0, v[0:1]
	s_add_i32 s4, s27, 0xa000
	s_mov_b32 s5, m0
	s_mov_b32 m0, s4
	s_nop 0
	global_load_lds_dwordx4 v[18:19], off
	s_mov_b32 m0, s5
	v_lshl_add_u64 v[18:19], s[16:17], 0, v[0:1]
	s_add_i32 s4, s27, 0xc000
	s_mov_b32 s5, m0
	s_mov_b32 m0, s4
	s_nop 0
	global_load_lds_dwordx4 v[18:19], off
	s_mov_b32 m0, s5
	v_exp_f32_e32 v59, v20
	v_exp_f32_e32 v60, v21
	v_exp_f32_e32 v61, v22
	v_exp_f32_e32 v62, v23
	v_exp_f32_e32 v63, v24
	v_exp_f32_e32 v64, v25
	v_exp_f32_e32 v65, v26
	v_exp_f32_e32 v66, v27
	v_exp_f32_e32 v67, v28
	v_exp_f32_e32 v68, v29
	v_exp_f32_e32 v69, v30
	v_exp_f32_e32 v70, v31
	v_exp_f32_e32 v71, v32
	v_exp_f32_e32 v72, v33
	v_exp_f32_e32 v73, v42
	v_exp_f32_e32 v74, v43
	v_exp_f32_e32 v75, v44
	v_exp_f32_e32 v76, v45
	v_exp_f32_e32 v77, v46
	v_exp_f32_e32 v78, v47
	v_exp_f32_e32 v79, v48
	v_exp_f32_e32 v80, v49
	v_exp_f32_e32 v81, v50
	v_exp_f32_e32 v82, v51
	v_exp_f32_e32 v83, v41
	ds_read_b128 v[18:21], v234 offset:8192
	ds_read_b128 v[22:25], v234 offset:8704
	ds_read_b128 v[26:29], v234 offset:10240
	ds_read_b128 v[30:33], v234 offset:10752
	ds_read_b128 v[34:37], v234 offset:12288
	ds_read_b128 v[40:43], v234 offset:12800
	ds_read_b128 v[44:47], v234 offset:14336
	ds_read_b128 v[48:51], v234 offset:14848
	v_exp_f32_e32 v52, v52
	v_exp_f32_e32 v53, v53
	v_exp_f32_e32 v54, v54
	v_exp_f32_e32 v55, v55
	v_exp_f32_e32 v56, v56
	s_waitcnt vmcnt(3) lgkmcnt(0)
	s_barrier
	s_waitcnt lgkmcnt(7)
	v_mfma_f32_32x32x16_bf16 v[130:145], v[18:21], v[174:177], v[2:17]
	v_add_f32_e32 v39, v57, v58
	v_add_f32_e32 v39, v39, v59
	v_add_f32_e32 v39, v39, v60
	v_add_f32_e32 v39, v39, v61
	v_add_f32_e32 v39, v39, v62
	v_cvt_pk_bf16_f32 v146, v57, v58
	v_cvt_pk_bf16_f32 v147, v59, v60
	s_waitcnt lgkmcnt(6)
	v_mfma_f32_32x32x16_bf16 v[98:113], v[22:25], v[174:177], v[2:17]
	v_add_f32_e32 v18, v63, v39
	v_add_f32_e32 v18, v64, v18
	v_add_f32_e32 v18, v65, v18
	v_add_f32_e32 v18, v66, v18
	v_cvt_pk_bf16_f32 v148, v61, v62
	v_cvt_pk_bf16_f32 v149, v63, v64
	s_waitcnt lgkmcnt(5)
	v_mfma_f32_32x32x16_bf16 v[130:145], v[26:29], v[170:173], v[130:145]
	v_add_f32_e32 v18, v67, v18
	v_add_f32_e32 v18, v68, v18
	v_add_f32_e32 v18, v69, v18
	v_add_f32_e32 v18, v70, v18
	v_cvt_pk_bf16_f32 v150, v65, v66
	v_cvt_pk_bf16_f32 v151, v67, v68
	s_waitcnt lgkmcnt(4)
	v_mfma_f32_32x32x16_bf16 v[98:113], v[30:33], v[170:173], v[98:113]
	v_add_f32_e32 v18, v71, v18
	v_add_f32_e32 v18, v72, v18
	v_add_f32_e32 v18, v73, v18
	v_add_f32_e32 v18, v74, v18
	v_cvt_pk_bf16_f32 v152, v69, v70
	v_cvt_pk_bf16_f32 v153, v71, v72
	s_waitcnt lgkmcnt(3)
	v_mfma_f32_32x32x16_bf16 v[130:145], v[34:37], v[166:169], v[130:145]
	v_add_f32_e32 v18, v75, v18
	v_add_f32_e32 v18, v76, v18
	v_add_f32_e32 v18, v77, v18
	v_add_f32_e32 v18, v78, v18
	v_cvt_pk_bf16_f32 v154, v73, v74
	v_cvt_pk_bf16_f32 v155, v75, v76
	s_waitcnt lgkmcnt(2)
	v_mfma_f32_32x32x16_bf16 v[98:113], v[40:43], v[166:169], v[98:113]
	v_add_f32_e32 v18, v79, v18
	v_add_f32_e32 v18, v80, v18
	v_add_f32_e32 v18, v81, v18
	v_add_f32_e32 v18, v82, v18
	v_cvt_pk_bf16_f32 v156, v77, v78
	v_cvt_pk_bf16_f32 v157, v79, v80
	s_waitcnt lgkmcnt(1)
	v_mfma_f32_32x32x16_bf16 v[130:145], v[44:47], v[162:165], v[130:145]
	v_add_f32_e32 v18, v52, v18
	v_add_f32_e32 v18, v53, v18
	v_add_f32_e32 v18, v54, v18
	v_add_f32_e32 v18, v55, v18
	v_cvt_pk_bf16_f32 v158, v81, v82
	v_cvt_pk_bf16_f32 v159, v52, v53
	s_waitcnt lgkmcnt(0)
	v_mfma_f32_32x32x16_bf16 v[98:113], v[48:51], v[162:165], v[98:113]
	v_add_f32_e32 v18, v56, v18
	v_add_f32_e32 v18, v83, v18
	v_add_f32_e32 v18, 0, v18
	v_cvt_pk_bf16_f32 v160, v54, v55
	v_cvt_pk_bf16_f32 v161, v56, v83
	s_nop 0
	v_add_f32_e32 v235, 0, v18
	ds_read_b64_tr_b16 v[18:19], v217 offset:24576
	ds_read_b64_tr_b16 v[20:21], v217 offset:25088
	ds_read_b64_tr_b16 v[34:35], v217 offset:28672
	ds_read_b64_tr_b16 v[36:37], v217 offset:29184
	ds_read_b64_tr_b16 v[70:71], v217 offset:25600
	ds_read_b64_tr_b16 v[72:73], v217 offset:26112
	ds_read_b64_tr_b16 v[66:67], v217 offset:29696
	ds_read_b64_tr_b16 v[68:69], v217 offset:30208
	ds_read_b64_tr_b16 v[62:63], v217 offset:26624
	ds_read_b64_tr_b16 v[64:65], v217 offset:27136
	ds_read_b64_tr_b16 v[54:55], v217 offset:27648
	ds_read_b64_tr_b16 v[56:57], v217 offset:28160
	ds_read_b64_tr_b16 v[58:59], v217 offset:30720
	ds_read_b64_tr_b16 v[60:61], v217 offset:31232
	ds_read_b64_tr_b16 v[50:51], v217 offset:31744
	ds_read_b64_tr_b16 v[52:53], v217 offset:32256
	v_lshl_add_u64 v[22:23], s[18:19], 0, v[0:1]
	s_add_i32 s4, s27, 0xe000
	s_mov_b32 s5, m0
	s_mov_b32 m0, s4
	s_nop 0
	global_load_lds_dwordx4 v[22:23], off
	s_mov_b32 m0, s5
	v_lshl_add_u64 v[22:23], s[20:21], 0, v[0:1]
	s_add_i32 s4, s27, 0x10000
	s_mov_b32 s5, m0
	s_mov_b32 m0, s4
	s_nop 0
	global_load_lds_dwordx4 v[22:23], off
	s_mov_b32 m0, s5
	v_max_f32_e32 v22, v131, v131
	v_max_f32_e32 v23, v130, v130
	v_max_f32_e32 v22, v23, v22
	v_max3_f32 v23, v132, v133, v99
	v_max3_f32 v22, v22, v98, v100
	v_max3_f32 v22, v22, v101, v134
	v_max3_f32 v23, v23, v136, v137
	v_max3_f32 v22, v22, v135, v102
	v_max3_f32 v23, v23, v104, v105
	v_max3_f32 v22, v22, v103, v138
	v_max3_f32 v23, v23, v140, v141
	v_max3_f32 v22, v22, v139, v106
	v_max3_f32 v23, v23, v108, v109
	v_max3_f32 v22, v22, v107, v142
	v_max3_f32 v23, v23, v144, v145
	v_max3_f32 v22, v22, v143, v110
	v_max3_f32 v23, v23, v112, v113
	v_max3_f32 v22, v22, v111, v23
	v_mov_b32_e32 v23, v22
	s_nop 1
	v_permlane32_swap_b32_e32 v22, v23
	v_max_f32_e32 v23, v23, v23
	v_max_f32_e32 v22, v22, v22
	v_max_f32_e32 v22, v22, v23
	v_cmp_lt_f32_e32 vcc, s15, v22
	s_mov_b64 s[4:5], -1
	s_cbranch_vccnz .LBB0_615
	s_mov_b64 s[4:5], 0

.LBB0_530:
	s_waitcnt lgkmcnt(7)
	v_mfma_f32_32x32x16_bf16 v[114:129], v[82:85], v[174:177], v[2:17]
	v_add_f32_e32 v86, v130, v131
	v_add_f32_e32 v86, v132, v86
	v_add_f32_e32 v86, v133, v86
	v_add_f32_e32 v86, v134, v86
	v_add_f32_e32 v86, v135, v86
	v_cvt_pk_bf16_f32 v146, v130, v131
	v_cvt_pk_bf16_f32 v147, v132, v133
	s_nop 0
	v_add_f32_e32 v82, v136, v86
	v_add_f32_e32 v82, v137, v82
	v_add_f32_e32 v82, v138, v82
	v_add_f32_e32 v130, v139, v82
	s_waitcnt lgkmcnt(6)
	v_mfma_f32_32x32x16_bf16 v[82:97], v[198:201], v[174:177], v[2:17]
	v_cvt_pk_bf16_f32 v148, v134, v135
	v_cvt_pk_bf16_f32 v149, v136, v137
	s_waitcnt lgkmcnt(5)
	v_mfma_f32_32x32x16_bf16 v[114:129], v[202:205], v[170:173], v[114:129]
	v_add_f32_e32 v130, v140, v130
	v_add_f32_e32 v130, v141, v130
	v_add_f32_e32 v130, v142, v130
	v_add_f32_e32 v130, v143, v130
	v_cvt_pk_bf16_f32 v150, v138, v139
	v_cvt_pk_bf16_f32 v151, v140, v141
	s_waitcnt lgkmcnt(4)
	v_mfma_f32_32x32x16_bf16 v[82:97], v[194:197], v[170:173], v[82:97]
	v_add_f32_e32 v130, v144, v130
	v_add_f32_e32 v130, v145, v130
	v_add_f32_e32 v130, v98, v130
	v_add_f32_e32 v130, v99, v130
	v_cvt_pk_bf16_f32 v152, v142, v143
	v_cvt_pk_bf16_f32 v153, v144, v145
	s_waitcnt lgkmcnt(3)
	v_mfma_f32_32x32x16_bf16 v[114:129], v[190:193], v[166:169], v[114:129]
	v_add_f32_e32 v130, v100, v130
	v_add_f32_e32 v130, v101, v130
	v_add_f32_e32 v130, v102, v130
	v_add_f32_e32 v130, v103, v130
	v_cvt_pk_bf16_f32 v154, v98, v99
	v_cvt_pk_bf16_f32 v155, v100, v101
	s_waitcnt lgkmcnt(2)
	v_mfma_f32_32x32x16_bf16 v[82:97], v[186:189], v[166:169], v[82:97]
	v_add_f32_e32 v98, v104, v130
	v_add_f32_e32 v98, v105, v98
	v_add_f32_e32 v98, v106, v98
	v_add_f32_e32 v98, v107, v98
	v_cvt_pk_bf16_f32 v156, v102, v103
	v_cvt_pk_bf16_f32 v157, v104, v105
	s_waitcnt lgkmcnt(1)
	v_mfma_f32_32x32x16_bf16 v[114:129], v[182:185], v[162:165], v[114:129]
	v_add_f32_e32 v98, v108, v98
	v_add_f32_e32 v98, v109, v98
	v_add_f32_e32 v98, v110, v98
	v_add_f32_e32 v98, v111, v98
	v_cvt_pk_bf16_f32 v158, v106, v107
	v_cvt_pk_bf16_f32 v159, v108, v109
	s_waitcnt lgkmcnt(0)
	v_mfma_f32_32x32x16_bf16 v[82:97], v[178:181], v[162:165], v[82:97]
	v_add_f32_e32 v98, v112, v98
	v_add_f32_e32 v98, v113, v98
	v_add_f32_e32 v98, 0, v98
	v_cvt_pk_bf16_f32 v160, v110, v111
	v_cvt_pk_bf16_f32 v161, v112, v113
	ds_read_b64_tr_b16 v[142:143], v217 offset:40960
	ds_read_b64_tr_b16 v[144:145], v217 offset:41472
	ds_read_b64_tr_b16 v[138:139], v217 offset:45056
	ds_read_b64_tr_b16 v[140:141], v217 offset:45568
	ds_read_b64_tr_b16 v[134:135], v217 offset:41984
	ds_read_b64_tr_b16 v[136:137], v217 offset:42496
	ds_read_b64_tr_b16 v[130:131], v217 offset:46080
	ds_read_b64_tr_b16 v[132:133], v217 offset:46592
	v_add_f32_e32 v194, v235, v98
	ds_read_b64_tr_b16 v[110:111], v217 offset:43008
	ds_read_b64_tr_b16 v[112:113], v217 offset:43520
	ds_read_b64_tr_b16 v[102:103], v217 offset:44032
	ds_read_b64_tr_b16 v[104:105], v217 offset:44544
	ds_read_b64_tr_b16 v[106:107], v217 offset:47104
	ds_read_b64_tr_b16 v[108:109], v217 offset:47616
	ds_read_b64_tr_b16 v[98:99], v217 offset:48128
	ds_read_b64_tr_b16 v[100:101], v217 offset:48640
	v_lshl_add_u64 v[178:179], s[22:23], 0, v[0:1]
	s_mov_b32 s4, m0
	s_mov_b32 m0, s26
	s_nop 0
	global_load_lds_dwordx4 v[178:179], off
	s_mov_b32 m0, s4
	v_lshl_add_u64 v[178:179], s[24:25], 0, v[0:1]
	s_add_i32 s4, s26, 0x2000
	s_mov_b32 s5, m0
	s_mov_b32 m0, s4
	s_nop 0
	global_load_lds_dwordx4 v[178:179], off
	s_mov_b32 m0, s5
	v_max_f32_e32 v0, v115, v115
	v_max_f32_e32 v178, v114, v114
	v_max_f32_e32 v0, v178, v0
	v_max3_f32 v178, v116, v117, v83
	v_max3_f32 v0, v0, v82, v84
	v_max3_f32 v0, v0, v85, v118
	v_max3_f32 v178, v178, v120, v121
	v_max3_f32 v0, v0, v119, v86
	v_max3_f32 v178, v178, v88, v89
	v_max3_f32 v0, v0, v87, v122
	v_max3_f32 v178, v178, v124, v125
	v_max3_f32 v0, v0, v123, v90
	v_max3_f32 v178, v178, v92, v93
	v_max3_f32 v0, v0, v91, v126
	v_max3_f32 v178, v178, v128, v129
	v_max3_f32 v0, v0, v127, v94
	v_max3_f32 v178, v178, v96, v97
	v_max3_f32 v0, v0, v95, v178
	v_mov_b32_e32 v178, v0
	s_nop 1
	v_permlane32_swap_b32_e32 v0, v178
	v_max_f32_e32 v178, v178, v178
	v_max_f32_e32 v0, v0, v0
	v_max_f32_e32 v0, v0, v178
	v_cmp_lt_f32_e32 vcc, s15, v0
	s_mov_b64 s[4:5], -1
	s_cbranch_vccnz .LBB0_618
	s_mov_b64 s[4:5], 0

.LBB0_541:
	v_mfma_f32_32x32x16_bf16 v[130:145], v[114:117], v[190:193], v[66:81]
	v_add_f32_e32 v118, v98, v99
	v_add_f32_e32 v118, v100, v118
	v_add_f32_e32 v118, v101, v118
	s_lshl_b32 s18, s18, 1
	v_add_f32_e32 v118, v102, v118
	v_add_u32_e32 v243, s18, v238
	v_add_f32_e32 v114, v103, v118
	v_cvt_pk_bf16_f32 v174, v98, v99
	v_cvt_pk_bf16_f32 v175, v100, v101
	s_nop 0
	v_add_f32_e32 v98, v104, v114
	v_mfma_f32_32x32x16_bf16 v[114:129], v[198:201], v[190:193], v[66:81]
	v_add_f32_e32 v98, v105, v98
	v_add_f32_e32 v98, v106, v98
	v_add_f32_e32 v98, v107, v98
	v_cvt_pk_bf16_f32 v176, v102, v103
	v_cvt_pk_bf16_f32 v177, v104, v105
	v_mfma_f32_32x32x16_bf16 v[130:145], v[202:205], v[186:189], v[130:145]
	v_add_f32_e32 v98, v108, v98
	v_add_f32_e32 v98, v109, v98
	v_add_f32_e32 v98, v110, v98
	v_add_f32_e32 v98, v111, v98
	v_cvt_pk_bf16_f32 v170, v106, v107
	v_cvt_pk_bf16_f32 v171, v108, v109
	v_mfma_f32_32x32x16_bf16 v[114:129], v[194:197], v[186:189], v[114:129]
	v_add_f32_e32 v98, v112, v98
	v_add_f32_e32 v98, v113, v98
	v_add_f32_e32 v98, v82, v98
	v_add_f32_e32 v98, v83, v98
	v_cvt_pk_bf16_f32 v172, v110, v111
	v_cvt_pk_bf16_f32 v173, v112, v113
	v_mfma_f32_32x32x16_bf16 v[130:145], v[158:161], v[182:185], v[130:145]
	v_add_f32_e32 v98, v84, v98
	v_add_f32_e32 v98, v85, v98
	v_add_f32_e32 v98, v86, v98
	v_add_f32_e32 v98, v87, v98
	v_cvt_pk_bf16_f32 v166, v82, v83
	v_cvt_pk_bf16_f32 v167, v84, v85
	v_mfma_f32_32x32x16_bf16 v[114:129], v[154:157], v[182:185], v[114:129]
	v_add_f32_e32 v82, v88, v98
	v_add_f32_e32 v82, v89, v82
	v_add_f32_e32 v82, v90, v82
	v_add_f32_e32 v82, v91, v82
	v_cvt_pk_bf16_f32 v168, v86, v87
	v_cvt_pk_bf16_f32 v169, v88, v89
	v_mfma_f32_32x32x16_bf16 v[130:145], v[150:153], v[178:181], v[130:145]
	v_add_f32_e32 v82, v92, v82
	v_add_f32_e32 v82, v93, v82
	v_add_f32_e32 v82, v94, v82
	v_add_f32_e32 v82, v95, v82
	v_cvt_pk_bf16_f32 v162, v90, v91
	v_cvt_pk_bf16_f32 v163, v92, v93
	v_mfma_f32_32x32x16_bf16 v[114:129], v[146:149], v[178:181], v[114:129]
	v_add_f32_e32 v82, v96, v82
	v_add_f32_e32 v82, v97, v82
	v_add_f32_e32 v242, v242, v82
	v_cvt_pk_bf16_f32 v164, v94, v95
	v_cvt_pk_bf16_f32 v165, v96, v97
	ds_read_b64_tr_b16 v[110:111], v243 offset:24576
	ds_read_b64_tr_b16 v[112:113], v243 offset:25088
	ds_read_b64_tr_b16 v[102:103], v243 offset:25600
	ds_read_b64_tr_b16 v[104:105], v243 offset:26112
	ds_read_b64_tr_b16 v[106:107], v243 offset:28672
	ds_read_b64_tr_b16 v[108:109], v243 offset:29184
	ds_read_b64_tr_b16 v[98:99], v243 offset:29696
	ds_read_b64_tr_b16 v[100:101], v243 offset:30208
	ds_read_b64_tr_b16 v[94:95], v243 offset:26624
	ds_read_b64_tr_b16 v[96:97], v243 offset:27136
	ds_read_b64_tr_b16 v[86:87], v243 offset:27648
	ds_read_b64_tr_b16 v[88:89], v243 offset:28160
	ds_read_b64_tr_b16 v[90:91], v243 offset:30720
	ds_read_b64_tr_b16 v[92:93], v243 offset:31232
	ds_read_b64_tr_b16 v[82:83], v243 offset:31744
	ds_read_b64_tr_b16 v[84:85], v243 offset:32256
	v_subrev_u32_e32 v216, s100, v212
	s_lshl_b32 s45, s33, 1
	v_max3_f32 v146, v130, v131, v132
	v_max3_f32 v147, v133, v134, v135
	v_max3_f32 v146, v146, v136, v137
	v_max3_f32 v147, v147, v138, v139
	v_max3_f32 v146, v146, v140, v141
	v_max3_f32 v147, v147, v142, v143
	v_max3_f32 v146, v146, v144, v145
	v_max3_f32 v147, v147, v114, v115
	v_max3_f32 v146, v146, v116, v117
	v_max3_f32 v147, v147, v118, v119
	v_max3_f32 v146, v146, v120, v121
	v_max3_f32 v147, v147, v122, v123
	v_max3_f32 v146, v146, v124, v125
	v_max3_f32 v147, v147, v126, v127
	v_max3_f32 v146, v146, v128, v129
	v_max_f32_e32 v146, v146, v147
	v_mov_b32_e32 v147, v146
	s_nop 1
	v_permlane32_swap_b32_e32 v146, v147
	v_max_f32_e32 v146, v146, v147
	v_cmp_lt_f32_e32 vcc, s15, v146
	s_mov_b64 s[18:19], -1
	s_cbranch_vccnz .LBB0_549
	s_mov_b64 s[18:19], 0

.LBB0_544:
	s_add_i32 s18, s33, 0x2000
	s_cmpk_lg_i32 s33, 0x4000
	s_cselect_b32 s46, s18, 0
	v_mfma_f32_32x32x16_bf16 v[98:113], v[82:85], v[190:193], v[66:81]
	v_add_f32_e32 v86, v130, v131
	v_add_f32_e32 v86, v132, v86
	v_add_f32_e32 v86, v133, v86
	s_lshl_b32 s18, s43, 1
	v_add_f32_e32 v86, v134, v86
	v_add_u32_e32 v243, s18, v238
	v_add_f32_e32 v82, v135, v86
	v_cvt_pk_bf16_f32 v174, v130, v131
	v_cvt_pk_bf16_f32 v175, v132, v133
	s_nop 0
	v_add_f32_e32 v82, v136, v82
	v_add_f32_e32 v82, v137, v82
	v_add_f32_e32 v82, v138, v82
	v_add_f32_e32 v130, v139, v82
	v_mfma_f32_32x32x16_bf16 v[82:97], v[198:201], v[190:193], v[66:81]
	v_cvt_pk_bf16_f32 v176, v134, v135
	v_cvt_pk_bf16_f32 v177, v136, v137
	v_mfma_f32_32x32x16_bf16 v[98:113], v[202:205], v[186:189], v[98:113]
	v_add_f32_e32 v130, v140, v130
	v_add_f32_e32 v130, v141, v130
	v_add_f32_e32 v130, v142, v130
	v_add_f32_e32 v130, v143, v130
	v_cvt_pk_bf16_f32 v170, v138, v139
	v_cvt_pk_bf16_f32 v171, v140, v141
	v_mfma_f32_32x32x16_bf16 v[82:97], v[194:197], v[186:189], v[82:97]
	v_add_f32_e32 v130, v144, v130
	v_add_f32_e32 v130, v145, v130
	v_add_f32_e32 v130, v114, v130
	v_add_f32_e32 v130, v115, v130
	v_cvt_pk_bf16_f32 v172, v142, v143
	v_cvt_pk_bf16_f32 v173, v144, v145
	v_mfma_f32_32x32x16_bf16 v[98:113], v[158:161], v[182:185], v[98:113]
	v_add_f32_e32 v130, v116, v130
	v_add_f32_e32 v130, v117, v130
	v_add_f32_e32 v130, v118, v130
	v_add_f32_e32 v130, v119, v130
	v_cvt_pk_bf16_f32 v166, v114, v115
	v_cvt_pk_bf16_f32 v167, v116, v117
	v_mfma_f32_32x32x16_bf16 v[82:97], v[154:157], v[182:185], v[82:97]
	v_add_f32_e32 v114, v120, v130
	v_add_f32_e32 v114, v121, v114
	v_add_f32_e32 v114, v122, v114
	v_add_f32_e32 v114, v123, v114
	v_cvt_pk_bf16_f32 v168, v118, v119
	v_cvt_pk_bf16_f32 v169, v120, v121
	v_mfma_f32_32x32x16_bf16 v[98:113], v[150:153], v[178:181], v[98:113]
	v_add_f32_e32 v114, v124, v114
	v_add_f32_e32 v114, v125, v114
	v_add_f32_e32 v114, v126, v114
	v_add_f32_e32 v114, v127, v114
	v_cvt_pk_bf16_f32 v162, v122, v123
	v_cvt_pk_bf16_f32 v163, v124, v125
	v_mfma_f32_32x32x16_bf16 v[82:97], v[146:149], v[178:181], v[82:97]
	v_add_f32_e32 v114, v128, v114
	v_add_f32_e32 v114, v129, v114
	v_add_f32_e32 v242, v242, v114
	v_cvt_pk_bf16_f32 v164, v126, v127
	v_cvt_pk_bf16_f32 v165, v128, v129
	ds_read_b64_tr_b16 v[142:143], v243 offset:24576
	ds_read_b64_tr_b16 v[144:145], v243 offset:25088
	ds_read_b64_tr_b16 v[134:135], v243 offset:25600
	ds_read_b64_tr_b16 v[136:137], v243 offset:26112
	ds_read_b64_tr_b16 v[138:139], v243 offset:28672
	ds_read_b64_tr_b16 v[140:141], v243 offset:29184
	ds_read_b64_tr_b16 v[130:131], v243 offset:29696
	ds_read_b64_tr_b16 v[132:133], v243 offset:30208
	ds_read_b64_tr_b16 v[126:127], v243 offset:26624
	ds_read_b64_tr_b16 v[128:129], v243 offset:27136
	ds_read_b64_tr_b16 v[118:119], v243 offset:27648
	ds_read_b64_tr_b16 v[120:121], v243 offset:28160
	ds_read_b64_tr_b16 v[122:123], v243 offset:30720
	ds_read_b64_tr_b16 v[124:125], v243 offset:31232
	ds_read_b64_tr_b16 v[114:115], v243 offset:31744
	ds_read_b64_tr_b16 v[116:117], v243 offset:32256
	s_add_u32 s18, s100, s16
	s_addc_u32 s19, s101, s17
	s_add_u32 s18, s18, 0x168000
	s_addc_u32 s19, s19, 0
	s_add_i32 m0, s33, s22
	s_nop 0
	global_load_lds_dwordx4 v216, s[18:19]
	s_lshl_b32 s43, s46, 1
	v_max3_f32 v146, v98, v99, v100
	v_max3_f32 v147, v101, v102, v103
	v_max3_f32 v146, v146, v104, v105
	v_max3_f32 v147, v147, v106, v107
	v_max3_f32 v146, v146, v108, v109
	v_max3_f32 v147, v147, v110, v111
	v_max3_f32 v146, v146, v112, v113
	v_max3_f32 v147, v147, v82, v83
	v_max3_f32 v146, v146, v84, v85
	v_max3_f32 v147, v147, v86, v87
	v_max3_f32 v146, v146, v88, v89
	v_max3_f32 v147, v147, v90, v91
	v_max3_f32 v146, v146, v92, v93
	v_max3_f32 v147, v147, v94, v95
	v_max3_f32 v146, v146, v96, v97
	v_max_f32_e32 v146, v146, v147
	v_mov_b32_e32 v147, v146
	s_nop 1
	v_permlane32_swap_b32_e32 v146, v147
	v_max_f32_e32 v146, v146, v147
	v_cmp_lt_f32_e32 vcc, s15, v146
	s_mov_b64 s[18:19], -1
	s_cbranch_vccnz .LBB0_552
	s_mov_b64 s[18:19], 0

.LBB0_555:
	s_waitcnt lgkmcnt(7)
	v_mfma_f32_32x32x16_bf16 v[130:145], v[114:117], v[190:193], v[66:81]
	v_add_f32_e32 v118, v98, v99
	v_add_f32_e32 v118, v100, v118
	v_add_f32_e32 v118, v101, v118
	v_add_f32_e32 v118, v102, v118
	v_add_u32_e32 v214, s45, v238
	v_add_f32_e32 v118, v103, v118
	v_cvt_pk_bf16_f32 v174, v98, v99
	v_cvt_pk_bf16_f32 v175, v100, v101
	s_nop 0
	v_add_f32_e32 v98, v104, v118
	s_waitcnt lgkmcnt(6)
	v_mfma_f32_32x32x16_bf16 v[114:129], v[198:201], v[190:193], v[66:81]
	v_add_f32_e32 v98, v105, v98
	v_add_f32_e32 v98, v106, v98
	v_add_f32_e32 v98, v107, v98
	v_cvt_pk_bf16_f32 v176, v102, v103
	v_cvt_pk_bf16_f32 v177, v104, v105
	s_waitcnt lgkmcnt(5)
	v_mfma_f32_32x32x16_bf16 v[130:145], v[202:205], v[186:189], v[130:145]
	v_add_f32_e32 v98, v108, v98
	v_add_f32_e32 v98, v109, v98
	v_add_f32_e32 v98, v110, v98
	v_add_f32_e32 v98, v111, v98
	v_cvt_pk_bf16_f32 v170, v106, v107
	v_cvt_pk_bf16_f32 v171, v108, v109
	s_waitcnt lgkmcnt(4)
	v_mfma_f32_32x32x16_bf16 v[114:129], v[194:197], v[186:189], v[114:129]
	v_add_f32_e32 v98, v112, v98
	v_add_f32_e32 v98, v113, v98
	v_add_f32_e32 v98, v82, v98
	v_add_f32_e32 v98, v83, v98
	v_cvt_pk_bf16_f32 v172, v110, v111
	v_cvt_pk_bf16_f32 v173, v112, v113
	s_waitcnt lgkmcnt(3)
	v_mfma_f32_32x32x16_bf16 v[130:145], v[158:161], v[182:185], v[130:145]
	v_add_f32_e32 v98, v84, v98
	v_add_f32_e32 v98, v85, v98
	v_add_f32_e32 v98, v86, v98
	v_add_f32_e32 v98, v87, v98
	v_cvt_pk_bf16_f32 v166, v82, v83
	v_cvt_pk_bf16_f32 v167, v84, v85
	s_waitcnt lgkmcnt(2)
	v_mfma_f32_32x32x16_bf16 v[114:129], v[154:157], v[182:185], v[114:129]
	v_add_f32_e32 v82, v88, v98
	v_add_f32_e32 v82, v89, v82
	v_add_f32_e32 v82, v90, v82
	v_add_f32_e32 v82, v91, v82
	v_cvt_pk_bf16_f32 v168, v86, v87
	v_cvt_pk_bf16_f32 v169, v88, v89
	s_waitcnt lgkmcnt(1)
	v_mfma_f32_32x32x16_bf16 v[130:145], v[150:153], v[178:181], v[130:145]
	v_add_f32_e32 v82, v92, v82
	v_add_f32_e32 v82, v93, v82
	v_add_f32_e32 v82, v94, v82
	v_add_f32_e32 v82, v95, v82
	v_cvt_pk_bf16_f32 v162, v90, v91
	v_cvt_pk_bf16_f32 v163, v92, v93
	s_waitcnt lgkmcnt(0)
	v_mfma_f32_32x32x16_bf16 v[114:129], v[146:149], v[178:181], v[114:129]
	v_add_f32_e32 v82, v96, v82
	v_add_f32_e32 v82, v97, v82
	v_add_f32_e32 v82, 0, v82
	v_cvt_pk_bf16_f32 v164, v94, v95
	v_cvt_pk_bf16_f32 v165, v96, v97
	ds_read_b64_tr_b16 v[110:111], v214 offset:24576
	ds_read_b64_tr_b16 v[112:113], v214 offset:25088
	ds_read_b64_tr_b16 v[106:107], v214 offset:28672
	ds_read_b64_tr_b16 v[108:109], v214 offset:29184
	ds_read_b64_tr_b16 v[102:103], v214 offset:25600
	ds_read_b64_tr_b16 v[104:105], v214 offset:26112
	ds_read_b64_tr_b16 v[98:99], v214 offset:29696
	ds_read_b64_tr_b16 v[100:101], v214 offset:30208
	v_add_f32_e32 v215, v242, v82
	ds_read_b64_tr_b16 v[94:95], v214 offset:26624
	ds_read_b64_tr_b16 v[96:97], v214 offset:27136
	ds_read_b64_tr_b16 v[86:87], v214 offset:27648
	ds_read_b64_tr_b16 v[88:89], v214 offset:28160
	ds_read_b64_tr_b16 v[90:91], v214 offset:30720
	ds_read_b64_tr_b16 v[92:93], v214 offset:31232
	ds_read_b64_tr_b16 v[82:83], v214 offset:31744
	ds_read_b64_tr_b16 v[84:85], v214 offset:32256
	s_mov_b64 s[16:17], 0x4890000
	v_lshl_add_u64 v[146:147], v[212:213], 0, s[16:17]
	s_add_i32 s16, s46, s22
	s_add_u32 s52, s36, 0x4800000
	s_addc_u32 s53, s37, 0
	s_lshl_b32 s20, s21, 1
	s_mov_b32 s17, m0
	s_mov_b32 m0, s16
	s_nop 0
	global_load_lds_dwordx4 v[146:147], off
	s_mov_b32 m0, s17
	s_add_i32 s16, s20, s24
	s_add_u32 s74, s36, 0x4800080
	v_lshl_add_u64 v[146:147], s[52:53], 0, v[0:1]
	s_addc_u32 s75, s37, 0
	s_mov_b32 s17, m0
	s_mov_b32 m0, s16
	s_nop 0
	global_load_lds_dwordx4 v[146:147], off
	s_mov_b32 m0, s17
	v_lshl_add_u64 v[146:147], s[74:75], 0, v[0:1]
	s_addk_i32 s16, 0x2000
	s_mov_b32 s17, m0
	s_mov_b32 m0, s16
	s_nop 0
	global_load_lds_dwordx4 v[146:147], off
	s_mov_b32 m0, s17
	v_max_f32_e32 v146, v131, v131
	v_max_f32_e32 v147, v130, v130
	v_max_f32_e32 v146, v147, v146
	v_max3_f32 v147, v132, v133, v115
	v_max3_f32 v146, v146, v114, v116
	v_max3_f32 v146, v146, v117, v134
	v_max3_f32 v147, v147, v136, v137
	v_max3_f32 v146, v146, v135, v118
	v_max3_f32 v147, v147, v120, v121
	v_max3_f32 v146, v146, v119, v138
	v_max3_f32 v147, v147, v140, v141
	v_max3_f32 v146, v146, v139, v122
	v_max3_f32 v147, v147, v124, v125
	v_max3_f32 v146, v146, v123, v142
	v_max3_f32 v147, v147, v144, v145
	v_max3_f32 v146, v146, v143, v126
	v_max3_f32 v147, v147, v128, v129
	v_max3_f32 v146, v146, v127, v147
	v_mov_b32_e32 v147, v146
	s_nop 1
	v_permlane32_swap_b32_e32 v146, v147
	v_max_f32_e32 v147, v147, v147
	v_max_f32_e32 v146, v146, v146
	v_max_f32_e32 v146, v146, v147
	v_cmp_lt_f32_e32 vcc, s15, v146
	s_mov_b64 s[16:17], -1
	s_cbranch_vccnz .LBB0_624
	s_mov_b64 s[16:17], 0

.LBB0_558:
	s_add_i32 s16, s21, 0x2000
	s_cmpk_lg_i32 s21, 0x4000
	s_cselect_b32 s23, s16, 0
	s_waitcnt lgkmcnt(7)
	v_mfma_f32_32x32x16_bf16 v[146:161], v[82:85], v[190:193], v[66:81]
	v_add_f32_e32 v86, v130, v131
	v_add_f32_e32 v86, v132, v86
	v_add_f32_e32 v86, v133, v86
	v_add_f32_e32 v86, v134, v86
	v_add_u32_e32 v216, s43, v238
	v_add_f32_e32 v86, v135, v86
	v_cvt_pk_bf16_f32 v174, v130, v131
	v_cvt_pk_bf16_f32 v175, v132, v133
	s_nop 0
	v_add_f32_e32 v82, v136, v86
	v_add_f32_e32 v82, v137, v82
	v_add_f32_e32 v82, v138, v82
	v_add_f32_e32 v130, v139, v82
	s_waitcnt lgkmcnt(6)
	v_mfma_f32_32x32x16_bf16 v[82:97], v[198:201], v[190:193], v[66:81]
	v_cvt_pk_bf16_f32 v176, v134, v135
	v_cvt_pk_bf16_f32 v177, v136, v137
	s_waitcnt lgkmcnt(5)
	v_mfma_f32_32x32x16_bf16 v[146:161], v[202:205], v[186:189], v[146:161]
	v_add_f32_e32 v130, v140, v130
	v_add_f32_e32 v130, v141, v130
	v_add_f32_e32 v130, v142, v130
	v_add_f32_e32 v130, v143, v130
	v_cvt_pk_bf16_f32 v170, v138, v139
	v_cvt_pk_bf16_f32 v171, v140, v141
	s_waitcnt lgkmcnt(4)
	v_mfma_f32_32x32x16_bf16 v[82:97], v[194:197], v[186:189], v[82:97]
	v_add_f32_e32 v130, v144, v130
	v_add_f32_e32 v130, v145, v130
	v_add_f32_e32 v130, v114, v130
	v_add_f32_e32 v130, v115, v130
	v_cvt_pk_bf16_f32 v172, v142, v143
	v_cvt_pk_bf16_f32 v173, v144, v145
	s_waitcnt lgkmcnt(3)
	v_mfma_f32_32x32x16_bf16 v[146:161], v[110:113], v[182:185], v[146:161]
	v_add_f32_e32 v110, v116, v130
	v_add_f32_e32 v110, v117, v110
	v_add_f32_e32 v110, v118, v110
	v_add_f32_e32 v110, v119, v110
	v_cvt_pk_bf16_f32 v166, v114, v115
	v_cvt_pk_bf16_f32 v167, v116, v117
	s_waitcnt lgkmcnt(2)
	v_mfma_f32_32x32x16_bf16 v[82:97], v[106:109], v[182:185], v[82:97]
	v_add_f32_e32 v106, v120, v110
	v_add_f32_e32 v106, v121, v106
	v_add_f32_e32 v106, v122, v106
	v_add_f32_e32 v106, v123, v106
	v_cvt_pk_bf16_f32 v168, v118, v119
	v_cvt_pk_bf16_f32 v169, v120, v121
	s_waitcnt lgkmcnt(1)
	v_mfma_f32_32x32x16_bf16 v[146:161], v[102:105], v[178:181], v[146:161]
	v_add_f32_e32 v102, v124, v106
	v_add_f32_e32 v102, v125, v102
	v_add_f32_e32 v102, v126, v102
	v_add_f32_e32 v102, v127, v102
	v_cvt_pk_bf16_f32 v162, v122, v123
	v_cvt_pk_bf16_f32 v163, v124, v125
	s_waitcnt lgkmcnt(0)
	v_mfma_f32_32x32x16_bf16 v[82:97], v[98:101], v[178:181], v[82:97]
	v_add_f32_e32 v98, v128, v102
	v_add_f32_e32 v98, v129, v98
	v_add_f32_e32 v98, 0, v98
	v_cvt_pk_bf16_f32 v164, v126, v127
	v_cvt_pk_bf16_f32 v165, v128, v129
	ds_read_b64_tr_b16 v[126:127], v216 offset:24576
	ds_read_b64_tr_b16 v[128:129], v216 offset:25088
	ds_read_b64_tr_b16 v[122:123], v216 offset:28672
	ds_read_b64_tr_b16 v[124:125], v216 offset:29184
	ds_read_b64_tr_b16 v[118:119], v216 offset:25600
	ds_read_b64_tr_b16 v[120:121], v216 offset:26112
	ds_read_b64_tr_b16 v[114:115], v216 offset:29696
	ds_read_b64_tr_b16 v[116:117], v216 offset:30208
	v_add_f32_e32 v215, v215, v98
	ds_read_b64_tr_b16 v[110:111], v216 offset:26624
	ds_read_b64_tr_b16 v[112:113], v216 offset:27136
	ds_read_b64_tr_b16 v[102:103], v216 offset:27648
	ds_read_b64_tr_b16 v[104:105], v216 offset:28160
	ds_read_b64_tr_b16 v[106:107], v216 offset:30720
	ds_read_b64_tr_b16 v[108:109], v216 offset:31232
	ds_read_b64_tr_b16 v[98:99], v216 offset:31744
	ds_read_b64_tr_b16 v[100:101], v216 offset:32256
	s_mov_b64 s[16:17], 0x48d8000
	v_lshl_add_u64 v[130:131], v[212:213], 0, s[16:17]
	s_add_i32 s16, s21, s22
	s_add_u32 s96, s36, 0x4848000
	s_addc_u32 s97, s37, 0
	s_lshl_b32 s25, s23, 1
	s_mov_b32 s17, m0
	s_mov_b32 m0, s16
	s_nop 0
	global_load_lds_dwordx4 v[130:131], off
	s_mov_b32 m0, s17
	s_add_i32 s16, s25, s24
	s_add_u32 s46, s36, 0x4848080
	v_lshl_add_u64 v[130:131], s[96:97], 0, v[0:1]
	s_addc_u32 s47, s37, 0
	s_mov_b32 s17, m0
	s_mov_b32 m0, s16
	s_nop 0
	global_load_lds_dwordx4 v[130:131], off
	s_mov_b32 m0, s17
	v_lshl_add_u64 v[130:131], s[46:47], 0, v[0:1]
	s_addk_i32 s16, 0x2000
	s_mov_b32 s17, m0
	s_mov_b32 m0, s16
	s_nop 0
	global_load_lds_dwordx4 v[130:131], off
	s_mov_b32 m0, s17
	v_max_f32_e32 v130, v147, v147
	v_max_f32_e32 v131, v146, v146
	v_max_f32_e32 v130, v131, v130
	v_max3_f32 v131, v148, v149, v83
	v_max3_f32 v130, v130, v82, v84
	v_max3_f32 v130, v130, v85, v150
	v_max3_f32 v131, v131, v152, v153
	v_max3_f32 v130, v130, v151, v86
	v_max3_f32 v131, v131, v88, v89
	v_max3_f32 v130, v130, v87, v154
	v_max3_f32 v131, v131, v156, v157
	v_max3_f32 v130, v130, v155, v90
	v_max3_f32 v131, v131, v92, v93
	v_max3_f32 v130, v130, v91, v158
	v_max3_f32 v131, v131, v160, v161
	v_max3_f32 v130, v130, v159, v94
	v_max3_f32 v131, v131, v96, v97
	v_max3_f32 v130, v130, v95, v131
	v_mov_b32_e32 v131, v130
	s_nop 1
	v_permlane32_swap_b32_e32 v130, v131
	v_max_f32_e32 v131, v131, v131
	v_max_f32_e32 v130, v130, v130
	v_max_f32_e32 v130, v130, v131
	v_cmp_lt_f32_e32 vcc, s15, v130
	s_mov_b64 s[16:17], -1
	s_cbranch_vccnz .LBB0_627
	s_mov_b64 s[16:17], 0

.LBB0_561:
	s_add_i32 s16, s23, 0x2000
	s_cmpk_lg_i32 s23, 0x4000
	s_cselect_b32 s31, s16, 0
	s_waitcnt lgkmcnt(7)
	v_mfma_f32_32x32x16_bf16 v[130:145], v[98:101], v[190:193], v[66:81]
	v_add_f32_e32 v102, v146, v147
	v_add_f32_e32 v102, v148, v102
	v_add_f32_e32 v102, v149, v102
	v_add_f32_e32 v102, v150, v102
	v_add_u32_e32 v213, s20, v238
	v_add_f32_e32 v102, v151, v102
	v_cvt_pk_bf16_f32 v174, v146, v147
	v_cvt_pk_bf16_f32 v175, v148, v149
	s_nop 0
	v_add_f32_e32 v98, v152, v102
	v_add_f32_e32 v98, v153, v98
	v_add_f32_e32 v98, v154, v98
	v_add_f32_e32 v146, v155, v98
	s_waitcnt lgkmcnt(6)
	v_mfma_f32_32x32x16_bf16 v[98:113], v[198:201], v[190:193], v[66:81]
	v_cvt_pk_bf16_f32 v176, v150, v151
	v_cvt_pk_bf16_f32 v177, v152, v153
	s_waitcnt lgkmcnt(5)
	v_mfma_f32_32x32x16_bf16 v[130:145], v[202:205], v[186:189], v[130:145]
	v_add_f32_e32 v146, v156, v146
	v_add_f32_e32 v146, v157, v146
	v_add_f32_e32 v146, v158, v146
	v_add_f32_e32 v146, v159, v146
	v_cvt_pk_bf16_f32 v170, v154, v155
	v_cvt_pk_bf16_f32 v171, v156, v157
	s_waitcnt lgkmcnt(4)
	v_mfma_f32_32x32x16_bf16 v[98:113], v[194:197], v[186:189], v[98:113]
	v_add_f32_e32 v146, v160, v146
	v_add_f32_e32 v146, v161, v146
	v_add_f32_e32 v146, v82, v146
	v_add_f32_e32 v146, v83, v146
	v_cvt_pk_bf16_f32 v172, v158, v159
	v_cvt_pk_bf16_f32 v173, v160, v161
	s_waitcnt lgkmcnt(3)
	v_mfma_f32_32x32x16_bf16 v[130:145], v[126:129], v[182:185], v[130:145]
	v_add_f32_e32 v126, v84, v146
	v_add_f32_e32 v126, v85, v126
	v_add_f32_e32 v126, v86, v126
	v_add_f32_e32 v126, v87, v126
	v_cvt_pk_bf16_f32 v166, v82, v83
	v_cvt_pk_bf16_f32 v167, v84, v85
	s_waitcnt lgkmcnt(2)
	v_mfma_f32_32x32x16_bf16 v[98:113], v[122:125], v[182:185], v[98:113]
	v_add_f32_e32 v82, v88, v126
	v_add_f32_e32 v82, v89, v82
	v_add_f32_e32 v82, v90, v82
	v_add_f32_e32 v82, v91, v82
	v_cvt_pk_bf16_f32 v168, v86, v87
	v_cvt_pk_bf16_f32 v169, v88, v89
	s_waitcnt lgkmcnt(1)
	v_mfma_f32_32x32x16_bf16 v[130:145], v[118:121], v[178:181], v[130:145]
	v_add_f32_e32 v82, v92, v82
	v_add_f32_e32 v82, v93, v82
	v_add_f32_e32 v82, v94, v82
	v_add_f32_e32 v82, v95, v82
	v_cvt_pk_bf16_f32 v162, v90, v91
	v_cvt_pk_bf16_f32 v163, v92, v93
	s_waitcnt lgkmcnt(0)
	v_mfma_f32_32x32x16_bf16 v[98:113], v[114:117], v[178:181], v[98:113]
	v_add_f32_e32 v82, v96, v82
	v_add_f32_e32 v82, v97, v82
	v_add_f32_e32 v82, 0, v82
	v_cvt_pk_bf16_f32 v164, v94, v95
	v_cvt_pk_bf16_f32 v165, v96, v97
	ds_read_b64_tr_b16 v[126:127], v213 offset:24576
	ds_read_b64_tr_b16 v[128:129], v213 offset:25088
	ds_read_b64_tr_b16 v[122:123], v213 offset:28672
	ds_read_b64_tr_b16 v[124:125], v213 offset:29184
	ds_read_b64_tr_b16 v[118:119], v213 offset:25600
	ds_read_b64_tr_b16 v[120:121], v213 offset:26112
	ds_read_b64_tr_b16 v[114:115], v213 offset:29696
	ds_read_b64_tr_b16 v[116:117], v213 offset:30208
	v_add_f32_e32 v212, v215, v82
	ds_read_b64_tr_b16 v[94:95], v213 offset:26624
	ds_read_b64_tr_b16 v[96:97], v213 offset:27136
	ds_read_b64_tr_b16 v[86:87], v213 offset:27648
	ds_read_b64_tr_b16 v[88:89], v213 offset:28160
	ds_read_b64_tr_b16 v[90:91], v213 offset:30720
	ds_read_b64_tr_b16 v[92:93], v213 offset:31232
	ds_read_b64_tr_b16 v[82:83], v213 offset:31744
	ds_read_b64_tr_b16 v[84:85], v213 offset:32256
	s_add_u32 s16, s36, 0x4890000
	s_addc_u32 s17, s37, 0
	s_lshl_b32 s33, s31, 1
	v_lshl_add_u64 v[146:147], s[16:17], 0, v[0:1]
	s_add_i32 s20, s33, s24
	s_mov_b32 s18, m0
	s_mov_b32 m0, s20
	s_nop 0
	global_load_lds_dwordx4 v[146:147], off
	s_mov_b32 m0, s18
	s_add_u32 s18, s36, 0x4890080
	s_addc_u32 s19, s37, 0
	v_lshl_add_u64 v[146:147], s[18:19], 0, v[0:1]
	s_addk_i32 s20, 0x2000
	s_mov_b32 s21, m0
	s_mov_b32 m0, s20
	s_nop 0
	global_load_lds_dwordx4 v[146:147], off
	s_mov_b32 m0, s21
	v_max_f32_e32 v146, v131, v131
	v_max_f32_e32 v147, v130, v130
	v_max_f32_e32 v146, v147, v146
	v_max3_f32 v147, v132, v133, v99
	v_max3_f32 v146, v146, v98, v100
	v_max3_f32 v146, v146, v101, v134
	v_max3_f32 v147, v147, v136, v137
	v_max3_f32 v146, v146, v135, v102
	v_max3_f32 v147, v147, v104, v105
	v_max3_f32 v146, v146, v103, v138
	v_max3_f32 v147, v147, v140, v141
	v_max3_f32 v146, v146, v139, v106
	v_max3_f32 v147, v147, v108, v109
	v_max3_f32 v146, v146, v107, v142
	v_max3_f32 v147, v147, v144, v145
	v_max3_f32 v146, v146, v143, v110
	v_max3_f32 v147, v147, v112, v113
	v_max3_f32 v146, v146, v111, v147
	v_mov_b32_e32 v147, v146
	s_nop 1
	v_permlane32_swap_b32_e32 v146, v147
	v_max_f32_e32 v147, v147, v147
	v_max_f32_e32 v146, v146, v146
	v_max_f32_e32 v146, v146, v147
	v_cmp_lt_f32_e32 vcc, s15, v146
	s_mov_b64 s[20:21], -1
	s_cbranch_vccnz .LBB0_630
	s_mov_b64 s[20:21], 0

.LBB0_564:
	s_add_i32 s20, s31, 0x2000
	s_cmpk_lg_i32 s31, 0x4000
	s_cselect_b32 s31, s20, 0
	s_waitcnt lgkmcnt(7)
	v_mfma_f32_32x32x16_bf16 v[114:129], v[82:85], v[190:193], v[66:81]
	v_add_f32_e32 v86, v130, v131
	v_add_f32_e32 v86, v132, v86
	v_add_f32_e32 v86, v133, v86
	v_add_f32_e32 v86, v134, v86
	v_add_u32_e32 v213, s25, v238
	v_add_f32_e32 v86, v135, v86
	v_cvt_pk_bf16_f32 v174, v130, v131
	v_cvt_pk_bf16_f32 v175, v132, v133
	s_nop 0
	v_add_f32_e32 v82, v136, v86
	v_add_f32_e32 v82, v137, v82
	v_add_f32_e32 v82, v138, v82
	v_add_f32_e32 v130, v139, v82
	s_waitcnt lgkmcnt(6)
	v_mfma_f32_32x32x16_bf16 v[82:97], v[198:201], v[190:193], v[66:81]
	v_cvt_pk_bf16_f32 v176, v134, v135
	v_cvt_pk_bf16_f32 v177, v136, v137
	s_waitcnt lgkmcnt(5)
	v_mfma_f32_32x32x16_bf16 v[114:129], v[202:205], v[186:189], v[114:129]
	v_add_f32_e32 v130, v140, v130
	v_add_f32_e32 v130, v141, v130
	v_add_f32_e32 v130, v142, v130
	v_add_f32_e32 v130, v143, v130
	v_cvt_pk_bf16_f32 v170, v138, v139
	v_cvt_pk_bf16_f32 v171, v140, v141
	s_waitcnt lgkmcnt(4)
	v_mfma_f32_32x32x16_bf16 v[82:97], v[194:197], v[186:189], v[82:97]
	v_add_f32_e32 v130, v144, v130
	v_add_f32_e32 v130, v145, v130
	v_add_f32_e32 v130, v98, v130
	v_add_f32_e32 v130, v99, v130
	v_cvt_pk_bf16_f32 v172, v142, v143
	v_cvt_pk_bf16_f32 v173, v144, v145
	s_waitcnt lgkmcnt(3)
	v_mfma_f32_32x32x16_bf16 v[114:129], v[158:161], v[182:185], v[114:129]
	v_add_f32_e32 v130, v100, v130
	v_add_f32_e32 v130, v101, v130
	v_add_f32_e32 v130, v102, v130
	v_add_f32_e32 v130, v103, v130
	v_cvt_pk_bf16_f32 v166, v98, v99
	v_cvt_pk_bf16_f32 v167, v100, v101
	s_waitcnt lgkmcnt(2)
	v_mfma_f32_32x32x16_bf16 v[82:97], v[154:157], v[182:185], v[82:97]
	v_add_f32_e32 v98, v104, v130
	v_add_f32_e32 v98, v105, v98
	v_add_f32_e32 v98, v106, v98
	v_add_f32_e32 v98, v107, v98
	v_cvt_pk_bf16_f32 v168, v102, v103
	v_cvt_pk_bf16_f32 v169, v104, v105
	s_waitcnt lgkmcnt(1)
	v_mfma_f32_32x32x16_bf16 v[114:129], v[150:153], v[178:181], v[114:129]
	v_add_f32_e32 v98, v108, v98
	v_add_f32_e32 v98, v109, v98
	v_add_f32_e32 v98, v110, v98
	v_add_f32_e32 v98, v111, v98
	v_cvt_pk_bf16_f32 v162, v106, v107
	v_cvt_pk_bf16_f32 v163, v108, v109
	s_waitcnt lgkmcnt(0)
	v_mfma_f32_32x32x16_bf16 v[82:97], v[146:149], v[178:181], v[82:97]
	v_add_f32_e32 v98, v112, v98
	v_add_f32_e32 v98, v113, v98
	v_add_f32_e32 v98, 0, v98
	v_cvt_pk_bf16_f32 v164, v110, v111
	v_cvt_pk_bf16_f32 v165, v112, v113
	ds_read_b64_tr_b16 v[142:143], v213 offset:24576
	ds_read_b64_tr_b16 v[144:145], v213 offset:25088
	ds_read_b64_tr_b16 v[138:139], v213 offset:28672
	ds_read_b64_tr_b16 v[140:141], v213 offset:29184
	ds_read_b64_tr_b16 v[134:135], v213 offset:25600
	ds_read_b64_tr_b16 v[136:137], v213 offset:26112
	ds_read_b64_tr_b16 v[130:131], v213 offset:29696
	ds_read_b64_tr_b16 v[132:133], v213 offset:30208
	v_add_f32_e32 v194, v212, v98
	ds_read_b64_tr_b16 v[110:111], v213 offset:26624
	ds_read_b64_tr_b16 v[112:113], v213 offset:27136
	ds_read_b64_tr_b16 v[102:103], v213 offset:27648
	ds_read_b64_tr_b16 v[104:105], v213 offset:28160
	ds_read_b64_tr_b16 v[106:107], v213 offset:30720
	ds_read_b64_tr_b16 v[108:109], v213 offset:31232
	ds_read_b64_tr_b16 v[98:99], v213 offset:31744
	ds_read_b64_tr_b16 v[100:101], v213 offset:32256
	s_add_u32 s20, s36, 0x48d8000
	s_addc_u32 s21, s37, 0
	s_lshl_b32 s43, s31, 1
	v_lshl_add_u64 v[146:147], s[20:21], 0, v[0:1]
	s_add_i32 s24, s43, s24
	s_mov_b32 s22, m0
	s_mov_b32 m0, s24
	s_nop 0
	global_load_lds_dwordx4 v[146:147], off
	s_mov_b32 m0, s22
	s_add_u32 s22, s36, 0x48d8080
	s_addc_u32 s23, s37, 0
	v_lshl_add_u64 v[146:147], s[22:23], 0, v[0:1]
	s_addk_i32 s24, 0x2000
	s_mov_b32 s25, m0
	s_mov_b32 m0, s24
	s_nop 0
	global_load_lds_dwordx4 v[146:147], off
	s_mov_b32 m0, s25
	v_max_f32_e32 v0, v115, v115
	v_max_f32_e32 v146, v114, v114
	v_max_f32_e32 v0, v146, v0
	v_max3_f32 v146, v116, v117, v83
	v_max3_f32 v0, v0, v82, v84
	v_max3_f32 v0, v0, v85, v118
	v_max3_f32 v146, v146, v120, v121
	v_max3_f32 v0, v0, v119, v86
	v_max3_f32 v146, v146, v88, v89
	v_max3_f32 v0, v0, v87, v122
	v_max3_f32 v146, v146, v124, v125
	v_max3_f32 v0, v0, v123, v90
	v_max3_f32 v146, v146, v92, v93
	v_max3_f32 v0, v0, v91, v126
	v_max3_f32 v146, v146, v128, v129
	v_max3_f32 v0, v0, v127, v94
	v_max3_f32 v146, v146, v96, v97
	v_max3_f32 v0, v0, v95, v146
	v_mov_b32_e32 v146, v0
	s_nop 1
	v_permlane32_swap_b32_e32 v0, v146
	v_max_f32_e32 v146, v146, v146
	v_max_f32_e32 v0, v0, v0
	v_max_f32_e32 v0, v0, v146
	v_cmp_lt_f32_e32 vcc, s15, v0
	s_mov_b64 s[24:25], -1
	s_cbranch_vccnz .LBB0_633
	s_mov_b64 s[24:25], 0

.LBB0_573:
	v_mfma_f32_32x32x16_bf16 v[130:145], v[114:117], v[190:193], v[66:81]
	v_add_f32_e32 v118, v98, v99
	v_add_f32_e32 v118, v100, v118
	v_add_f32_e32 v118, v101, v118
	s_lshl_b32 s6, s6, 1
	v_add_f32_e32 v118, v102, v118
	v_add_u32_e32 v243, s6, v238
	v_add_f32_e32 v114, v103, v118
	v_cvt_pk_bf16_f32 v174, v98, v99
	v_cvt_pk_bf16_f32 v175, v100, v101
	s_nop 0
	v_add_f32_e32 v98, v104, v114
	v_mfma_f32_32x32x16_bf16 v[114:129], v[198:201], v[190:193], v[66:81]
	v_add_f32_e32 v98, v105, v98
	v_add_f32_e32 v98, v106, v98
	v_add_f32_e32 v98, v107, v98
	v_cvt_pk_bf16_f32 v176, v102, v103
	v_cvt_pk_bf16_f32 v177, v104, v105
	v_mfma_f32_32x32x16_bf16 v[130:145], v[202:205], v[186:189], v[130:145]
	v_add_f32_e32 v98, v108, v98
	v_add_f32_e32 v98, v109, v98
	v_add_f32_e32 v98, v110, v98
	v_add_f32_e32 v98, v111, v98
	v_cvt_pk_bf16_f32 v170, v106, v107
	v_cvt_pk_bf16_f32 v171, v108, v109
	v_mfma_f32_32x32x16_bf16 v[114:129], v[194:197], v[186:189], v[114:129]
	v_add_f32_e32 v98, v112, v98
	v_add_f32_e32 v98, v113, v98
	v_add_f32_e32 v98, v82, v98
	v_add_f32_e32 v98, v83, v98
	v_cvt_pk_bf16_f32 v172, v110, v111
	v_cvt_pk_bf16_f32 v173, v112, v113
	v_mfma_f32_32x32x16_bf16 v[130:145], v[158:161], v[182:185], v[130:145]
	v_add_f32_e32 v98, v84, v98
	v_add_f32_e32 v98, v85, v98
	v_add_f32_e32 v98, v86, v98
	v_add_f32_e32 v98, v87, v98
	v_cvt_pk_bf16_f32 v166, v82, v83
	v_cvt_pk_bf16_f32 v167, v84, v85
	v_mfma_f32_32x32x16_bf16 v[114:129], v[154:157], v[182:185], v[114:129]
	v_add_f32_e32 v82, v88, v98
	v_add_f32_e32 v82, v89, v82
	v_add_f32_e32 v82, v90, v82
	v_add_f32_e32 v82, v91, v82
	v_cvt_pk_bf16_f32 v168, v86, v87
	v_cvt_pk_bf16_f32 v169, v88, v89
	v_mfma_f32_32x32x16_bf16 v[130:145], v[150:153], v[178:181], v[130:145]
	v_add_f32_e32 v82, v92, v82
	v_add_f32_e32 v82, v93, v82
	v_add_f32_e32 v82, v94, v82
	v_add_f32_e32 v82, v95, v82
	v_cvt_pk_bf16_f32 v162, v90, v91
	v_cvt_pk_bf16_f32 v163, v92, v93
	v_mfma_f32_32x32x16_bf16 v[114:129], v[146:149], v[178:181], v[114:129]
	v_add_f32_e32 v82, v96, v82
	v_add_f32_e32 v82, v97, v82
	v_add_f32_e32 v242, v242, v82
	v_cvt_pk_bf16_f32 v164, v94, v95
	v_cvt_pk_bf16_f32 v165, v96, v97
	ds_read_b64_tr_b16 v[110:111], v243 offset:24576
	ds_read_b64_tr_b16 v[112:113], v243 offset:25088
	ds_read_b64_tr_b16 v[102:103], v243 offset:25600
	ds_read_b64_tr_b16 v[104:105], v243 offset:26112
	ds_read_b64_tr_b16 v[106:107], v243 offset:28672
	ds_read_b64_tr_b16 v[108:109], v243 offset:29184
	ds_read_b64_tr_b16 v[98:99], v243 offset:29696
	ds_read_b64_tr_b16 v[100:101], v243 offset:30208
	ds_read_b64_tr_b16 v[94:95], v243 offset:26624
	ds_read_b64_tr_b16 v[96:97], v243 offset:27136
	ds_read_b64_tr_b16 v[86:87], v243 offset:27648
	ds_read_b64_tr_b16 v[88:89], v243 offset:28160
	ds_read_b64_tr_b16 v[90:91], v243 offset:30720
	ds_read_b64_tr_b16 v[92:93], v243 offset:31232
	ds_read_b64_tr_b16 v[82:83], v243 offset:31744
	ds_read_b64_tr_b16 v[84:85], v243 offset:32256
	v_subrev_u32_e32 v216, s100, v212
	s_lshl_b32 s11, s45, 1
	v_max3_f32 v146, v130, v131, v132
	v_max3_f32 v147, v133, v134, v135
	v_max3_f32 v146, v146, v136, v137
	v_max3_f32 v147, v147, v138, v139
	v_max3_f32 v146, v146, v140, v141
	v_max3_f32 v147, v147, v142, v143
	v_max3_f32 v146, v146, v144, v145
	v_max3_f32 v147, v147, v114, v115
	v_max3_f32 v146, v146, v116, v117
	v_max3_f32 v147, v147, v118, v119
	v_max3_f32 v146, v146, v120, v121
	v_max3_f32 v147, v147, v122, v123
	v_max3_f32 v146, v146, v124, v125
	v_max3_f32 v147, v147, v126, v127
	v_max3_f32 v146, v146, v128, v129
	v_max_f32_e32 v146, v146, v147
	v_mov_b32_e32 v147, v146
	s_nop 1
	v_permlane32_swap_b32_e32 v146, v147
	v_max_f32_e32 v146, v146, v147
	v_cmp_lt_f32_e32 vcc, s15, v146
	s_mov_b64 s[6:7], -1
	s_cbranch_vccnz .LBB0_581
	s_mov_b64 s[6:7], 0

.LBB0_576:
	s_add_i32 s6, s45, 0x2000
	s_cmpk_lg_i32 s45, 0x4000
	s_cselect_b32 s57, s6, 0
	v_mfma_f32_32x32x16_bf16 v[98:113], v[82:85], v[190:193], v[66:81]
	v_add_f32_e32 v86, v130, v131
	v_add_f32_e32 v86, v132, v86
	v_add_f32_e32 v86, v133, v86
	s_lshl_b32 s6, s56, 1
	v_add_f32_e32 v86, v134, v86
	v_add_u32_e32 v243, s6, v238
	v_add_f32_e32 v82, v135, v86
	v_cvt_pk_bf16_f32 v174, v130, v131
	v_cvt_pk_bf16_f32 v175, v132, v133
	s_nop 0
	v_add_f32_e32 v82, v136, v82
	v_add_f32_e32 v82, v137, v82
	v_add_f32_e32 v82, v138, v82
	v_add_f32_e32 v130, v139, v82
	v_mfma_f32_32x32x16_bf16 v[82:97], v[198:201], v[190:193], v[66:81]
	v_cvt_pk_bf16_f32 v176, v134, v135
	v_cvt_pk_bf16_f32 v177, v136, v137
	v_mfma_f32_32x32x16_bf16 v[98:113], v[202:205], v[186:189], v[98:113]
	v_add_f32_e32 v130, v140, v130
	v_add_f32_e32 v130, v141, v130
	v_add_f32_e32 v130, v142, v130
	v_add_f32_e32 v130, v143, v130
	v_cvt_pk_bf16_f32 v170, v138, v139
	v_cvt_pk_bf16_f32 v171, v140, v141
	v_mfma_f32_32x32x16_bf16 v[82:97], v[194:197], v[186:189], v[82:97]
	v_add_f32_e32 v130, v144, v130
	v_add_f32_e32 v130, v145, v130
	v_add_f32_e32 v130, v114, v130
	v_add_f32_e32 v130, v115, v130
	v_cvt_pk_bf16_f32 v172, v142, v143
	v_cvt_pk_bf16_f32 v173, v144, v145
	v_mfma_f32_32x32x16_bf16 v[98:113], v[158:161], v[182:185], v[98:113]
	v_add_f32_e32 v130, v116, v130
	v_add_f32_e32 v130, v117, v130
	v_add_f32_e32 v130, v118, v130
	v_add_f32_e32 v130, v119, v130
	v_cvt_pk_bf16_f32 v166, v114, v115
	v_cvt_pk_bf16_f32 v167, v116, v117
	v_mfma_f32_32x32x16_bf16 v[82:97], v[154:157], v[182:185], v[82:97]
	v_add_f32_e32 v114, v120, v130
	v_add_f32_e32 v114, v121, v114
	v_add_f32_e32 v114, v122, v114
	v_add_f32_e32 v114, v123, v114
	v_cvt_pk_bf16_f32 v168, v118, v119
	v_cvt_pk_bf16_f32 v169, v120, v121
	v_mfma_f32_32x32x16_bf16 v[98:113], v[150:153], v[178:181], v[98:113]
	v_add_f32_e32 v114, v124, v114
	v_add_f32_e32 v114, v125, v114
	v_add_f32_e32 v114, v126, v114
	v_add_f32_e32 v114, v127, v114
	v_cvt_pk_bf16_f32 v162, v122, v123
	v_cvt_pk_bf16_f32 v163, v124, v125
	v_mfma_f32_32x32x16_bf16 v[82:97], v[146:149], v[178:181], v[82:97]
	v_add_f32_e32 v114, v128, v114
	v_add_f32_e32 v114, v129, v114
	v_add_f32_e32 v242, v242, v114
	v_cvt_pk_bf16_f32 v164, v126, v127
	v_cvt_pk_bf16_f32 v165, v128, v129
	ds_read_b64_tr_b16 v[142:143], v243 offset:24576
	ds_read_b64_tr_b16 v[144:145], v243 offset:25088
	ds_read_b64_tr_b16 v[134:135], v243 offset:25600
	ds_read_b64_tr_b16 v[136:137], v243 offset:26112
	ds_read_b64_tr_b16 v[138:139], v243 offset:28672
	ds_read_b64_tr_b16 v[140:141], v243 offset:29184
	ds_read_b64_tr_b16 v[130:131], v243 offset:29696
	ds_read_b64_tr_b16 v[132:133], v243 offset:30208
	ds_read_b64_tr_b16 v[126:127], v243 offset:26624
	ds_read_b64_tr_b16 v[128:129], v243 offset:27136
	ds_read_b64_tr_b16 v[118:119], v243 offset:27648
	ds_read_b64_tr_b16 v[120:121], v243 offset:28160
	ds_read_b64_tr_b16 v[122:123], v243 offset:30720
	ds_read_b64_tr_b16 v[124:125], v243 offset:31232
	ds_read_b64_tr_b16 v[114:115], v243 offset:31744
	ds_read_b64_tr_b16 v[116:117], v243 offset:32256
	s_add_u32 s6, s100, s4
	s_addc_u32 s7, s101, s5
	s_add_u32 s6, s6, 0x168000
	s_addc_u32 s7, s7, 0
	s_add_i32 m0, s45, s33
	s_nop 0
	global_load_lds_dwordx4 v216, s[6:7]
	s_lshl_b32 s10, s57, 1
	v_max3_f32 v146, v98, v99, v100
	v_max3_f32 v147, v101, v102, v103
	v_max3_f32 v146, v146, v104, v105
	v_max3_f32 v147, v147, v106, v107
	v_max3_f32 v146, v146, v108, v109
	v_max3_f32 v147, v147, v110, v111
	v_max3_f32 v146, v146, v112, v113
	v_max3_f32 v147, v147, v82, v83
	v_max3_f32 v146, v146, v84, v85
	v_max3_f32 v147, v147, v86, v87
	v_max3_f32 v146, v146, v88, v89
	v_max3_f32 v147, v147, v90, v91
	v_max3_f32 v146, v146, v92, v93
	v_max3_f32 v147, v147, v94, v95
	v_max3_f32 v146, v146, v96, v97
	v_max_f32_e32 v146, v146, v147
	v_mov_b32_e32 v147, v146
	s_nop 1
	v_permlane32_swap_b32_e32 v146, v147
	v_max_f32_e32 v146, v146, v147
	v_cmp_lt_f32_e32 vcc, s15, v146
	s_mov_b64 s[6:7], -1
	s_cbranch_vccnz .LBB0_584
	s_mov_b64 s[6:7], 0

.LBB0_595:
	s_add_i32 s4, s11, 0x2000
	s_cmpk_lg_i32 s11, 0x4000
	s_cselect_b32 s10, s4, 0
	s_waitcnt lgkmcnt(7)
	v_mfma_f32_32x32x16_bf16 v[130:145], v[98:101], v[190:193], v[66:81]
	v_add_f32_e32 v102, v146, v147
	v_add_f32_e32 v102, v148, v102
	v_add_f32_e32 v102, v149, v102
	v_add_f32_e32 v102, v150, v102
	v_add_u32_e32 v213, s8, v238
	v_add_f32_e32 v102, v151, v102
	v_cvt_pk_bf16_f32 v174, v146, v147
	v_cvt_pk_bf16_f32 v175, v148, v149
	s_nop 0
	v_add_f32_e32 v98, v152, v102
	v_add_f32_e32 v98, v153, v98
	v_add_f32_e32 v98, v154, v98
	v_add_f32_e32 v146, v155, v98
	s_waitcnt lgkmcnt(6)
	v_mfma_f32_32x32x16_bf16 v[98:113], v[198:201], v[190:193], v[66:81]
	v_cvt_pk_bf16_f32 v176, v150, v151
	v_cvt_pk_bf16_f32 v177, v152, v153
	s_waitcnt lgkmcnt(5)
	v_mfma_f32_32x32x16_bf16 v[130:145], v[202:205], v[186:189], v[130:145]
	v_add_f32_e32 v146, v156, v146
	v_add_f32_e32 v146, v157, v146
	v_add_f32_e32 v146, v158, v146
	v_add_f32_e32 v146, v159, v146
	v_cvt_pk_bf16_f32 v170, v154, v155
	v_cvt_pk_bf16_f32 v171, v156, v157
	s_waitcnt lgkmcnt(4)
	v_mfma_f32_32x32x16_bf16 v[98:113], v[194:197], v[186:189], v[98:113]
	v_add_f32_e32 v146, v160, v146
	v_add_f32_e32 v146, v161, v146
	v_add_f32_e32 v146, v82, v146
	v_add_f32_e32 v146, v83, v146
	v_cvt_pk_bf16_f32 v172, v158, v159
	v_cvt_pk_bf16_f32 v173, v160, v161
	s_waitcnt lgkmcnt(3)
	v_mfma_f32_32x32x16_bf16 v[130:145], v[126:129], v[182:185], v[130:145]
	v_add_f32_e32 v126, v84, v146
	v_add_f32_e32 v126, v85, v126
	v_add_f32_e32 v126, v86, v126
	v_add_f32_e32 v126, v87, v126
	v_cvt_pk_bf16_f32 v166, v82, v83
	v_cvt_pk_bf16_f32 v167, v84, v85
	s_waitcnt lgkmcnt(2)
	v_mfma_f32_32x32x16_bf16 v[98:113], v[122:125], v[182:185], v[98:113]
	v_add_f32_e32 v82, v88, v126
	v_add_f32_e32 v82, v89, v82
	v_add_f32_e32 v82, v90, v82
	v_add_f32_e32 v82, v91, v82
	v_cvt_pk_bf16_f32 v168, v86, v87
	v_cvt_pk_bf16_f32 v169, v88, v89
	s_waitcnt lgkmcnt(1)
	v_mfma_f32_32x32x16_bf16 v[130:145], v[118:121], v[178:181], v[130:145]
	v_add_f32_e32 v82, v92, v82
	v_add_f32_e32 v82, v93, v82
	v_add_f32_e32 v82, v94, v82
	v_add_f32_e32 v82, v95, v82
	v_cvt_pk_bf16_f32 v162, v90, v91
	v_cvt_pk_bf16_f32 v163, v92, v93
	s_waitcnt lgkmcnt(0)
	v_mfma_f32_32x32x16_bf16 v[98:113], v[114:117], v[178:181], v[98:113]
	v_add_f32_e32 v82, v96, v82
	v_add_f32_e32 v82, v97, v82
	v_add_f32_e32 v82, 0, v82
	v_cvt_pk_bf16_f32 v164, v94, v95
	v_cvt_pk_bf16_f32 v165, v96, v97
	ds_read_b64_tr_b16 v[126:127], v213 offset:24576
	ds_read_b64_tr_b16 v[128:129], v213 offset:25088
	ds_read_b64_tr_b16 v[122:123], v213 offset:28672
	ds_read_b64_tr_b16 v[124:125], v213 offset:29184
	ds_read_b64_tr_b16 v[118:119], v213 offset:25600
	ds_read_b64_tr_b16 v[120:121], v213 offset:26112
	ds_read_b64_tr_b16 v[114:115], v213 offset:29696
	ds_read_b64_tr_b16 v[116:117], v213 offset:30208
	v_add_f32_e32 v212, v215, v82
	ds_read_b64_tr_b16 v[94:95], v213 offset:26624
	ds_read_b64_tr_b16 v[96:97], v213 offset:27136
	ds_read_b64_tr_b16 v[86:87], v213 offset:27648
	ds_read_b64_tr_b16 v[88:89], v213 offset:28160
	ds_read_b64_tr_b16 v[90:91], v213 offset:30720
	ds_read_b64_tr_b16 v[92:93], v213 offset:31232
	ds_read_b64_tr_b16 v[82:83], v213 offset:31744
	ds_read_b64_tr_b16 v[84:85], v213 offset:32256
	v_lshl_add_u64 v[146:147], s[16:17], 0, v[0:1]
	s_lshl_b32 s8, s10, 1
	s_add_i32 s4, s8, s28
	s_mov_b32 s5, m0
	s_mov_b32 m0, s4
	s_nop 0
	global_load_lds_dwordx4 v[146:147], off
	s_mov_b32 m0, s5
	v_lshl_add_u64 v[146:147], s[18:19], 0, v[0:1]
	s_addk_i32 s4, 0x2000
	s_mov_b32 s5, m0
	s_mov_b32 m0, s4
	s_nop 0
	global_load_lds_dwordx4 v[146:147], off
	s_mov_b32 m0, s5
	v_max_f32_e32 v146, v131, v131
	v_max_f32_e32 v147, v130, v130
	v_max_f32_e32 v146, v147, v146
	v_max3_f32 v147, v132, v133, v99
	v_max3_f32 v146, v146, v98, v100
	v_max3_f32 v146, v146, v101, v134
	v_max3_f32 v147, v147, v136, v137
	v_max3_f32 v146, v146, v135, v102
	v_max3_f32 v147, v147, v104, v105
	v_max3_f32 v146, v146, v103, v138
	v_max3_f32 v147, v147, v140, v141
	v_max3_f32 v146, v146, v139, v106
	v_max3_f32 v147, v147, v108, v109
	v_max3_f32 v146, v146, v107, v142
	v_max3_f32 v147, v147, v144, v145
	v_max3_f32 v146, v146, v143, v110
	v_max3_f32 v147, v147, v112, v113
	v_max3_f32 v146, v146, v111, v147
	v_mov_b32_e32 v147, v146
	s_nop 1
	v_permlane32_swap_b32_e32 v146, v147
	v_max_f32_e32 v147, v147, v147
	v_max_f32_e32 v146, v146, v146
	v_max_f32_e32 v146, v146, v147
	v_cmp_lt_f32_e32 vcc, s15, v146
	s_mov_b64 s[4:5], -1
	s_cbranch_vccnz .LBB0_645
	s_mov_b64 s[4:5], 0

.LBB0_598:
	s_add_i32 s4, s10, 0x2000
	s_cmpk_lg_i32 s10, 0x4000
	s_cselect_b32 s10, s4, 0
	s_waitcnt lgkmcnt(7)
	v_mfma_f32_32x32x16_bf16 v[114:129], v[82:85], v[190:193], v[66:81]
	v_add_f32_e32 v86, v130, v131
	v_add_f32_e32 v86, v132, v86
	v_add_f32_e32 v86, v133, v86
	v_add_f32_e32 v86, v134, v86
	v_add_u32_e32 v213, s9, v238
	v_add_f32_e32 v86, v135, v86
	v_cvt_pk_bf16_f32 v174, v130, v131
	v_cvt_pk_bf16_f32 v175, v132, v133
	s_nop 0
	v_add_f32_e32 v82, v136, v86
	v_add_f32_e32 v82, v137, v82
	v_add_f32_e32 v82, v138, v82
	v_add_f32_e32 v130, v139, v82
	s_waitcnt lgkmcnt(6)
	v_mfma_f32_32x32x16_bf16 v[82:97], v[198:201], v[190:193], v[66:81]
	v_cvt_pk_bf16_f32 v176, v134, v135
	v_cvt_pk_bf16_f32 v177, v136, v137
	s_waitcnt lgkmcnt(5)
	v_mfma_f32_32x32x16_bf16 v[114:129], v[202:205], v[186:189], v[114:129]
	v_add_f32_e32 v130, v140, v130
	v_add_f32_e32 v130, v141, v130
	v_add_f32_e32 v130, v142, v130
	v_add_f32_e32 v130, v143, v130
	v_cvt_pk_bf16_f32 v170, v138, v139
	v_cvt_pk_bf16_f32 v171, v140, v141
	s_waitcnt lgkmcnt(4)
	v_mfma_f32_32x32x16_bf16 v[82:97], v[194:197], v[186:189], v[82:97]
	v_add_f32_e32 v130, v144, v130
	v_add_f32_e32 v130, v145, v130
	v_add_f32_e32 v130, v98, v130
	v_add_f32_e32 v130, v99, v130
	v_cvt_pk_bf16_f32 v172, v142, v143
	v_cvt_pk_bf16_f32 v173, v144, v145
	s_waitcnt lgkmcnt(3)
	v_mfma_f32_32x32x16_bf16 v[114:129], v[158:161], v[182:185], v[114:129]
	v_add_f32_e32 v130, v100, v130
	v_add_f32_e32 v130, v101, v130
	v_add_f32_e32 v130, v102, v130
	v_add_f32_e32 v130, v103, v130
	v_cvt_pk_bf16_f32 v166, v98, v99
	v_cvt_pk_bf16_f32 v167, v100, v101
	s_waitcnt lgkmcnt(2)
	v_mfma_f32_32x32x16_bf16 v[82:97], v[154:157], v[182:185], v[82:97]
	v_add_f32_e32 v98, v104, v130
	v_add_f32_e32 v98, v105, v98
	v_add_f32_e32 v98, v106, v98
	v_add_f32_e32 v98, v107, v98
	v_cvt_pk_bf16_f32 v168, v102, v103
	v_cvt_pk_bf16_f32 v169, v104, v105
	s_waitcnt lgkmcnt(1)
	v_mfma_f32_32x32x16_bf16 v[114:129], v[150:153], v[178:181], v[114:129]
	v_add_f32_e32 v98, v108, v98
	v_add_f32_e32 v98, v109, v98
	v_add_f32_e32 v98, v110, v98
	v_add_f32_e32 v98, v111, v98
	v_cvt_pk_bf16_f32 v162, v106, v107
	v_cvt_pk_bf16_f32 v163, v108, v109
	s_waitcnt lgkmcnt(0)
	v_mfma_f32_32x32x16_bf16 v[82:97], v[146:149], v[178:181], v[82:97]
	v_add_f32_e32 v98, v112, v98
	v_add_f32_e32 v98, v113, v98
	v_add_f32_e32 v98, 0, v98
	v_cvt_pk_bf16_f32 v164, v110, v111
	v_cvt_pk_bf16_f32 v165, v112, v113
	ds_read_b64_tr_b16 v[142:143], v213 offset:24576
	ds_read_b64_tr_b16 v[144:145], v213 offset:25088
	ds_read_b64_tr_b16 v[138:139], v213 offset:28672
	ds_read_b64_tr_b16 v[140:141], v213 offset:29184
	ds_read_b64_tr_b16 v[134:135], v213 offset:25600
	ds_read_b64_tr_b16 v[136:137], v213 offset:26112
	ds_read_b64_tr_b16 v[130:131], v213 offset:29696
	ds_read_b64_tr_b16 v[132:133], v213 offset:30208
	v_add_f32_e32 v194, v212, v98
	ds_read_b64_tr_b16 v[110:111], v213 offset:26624
	ds_read_b64_tr_b16 v[112:113], v213 offset:27136
	ds_read_b64_tr_b16 v[102:103], v213 offset:27648
	ds_read_b64_tr_b16 v[104:105], v213 offset:28160
	ds_read_b64_tr_b16 v[106:107], v213 offset:30720
	ds_read_b64_tr_b16 v[108:109], v213 offset:31232
	ds_read_b64_tr_b16 v[98:99], v213 offset:31744
	ds_read_b64_tr_b16 v[100:101], v213 offset:32256
	v_lshl_add_u64 v[146:147], s[20:21], 0, v[0:1]
	s_lshl_b32 s9, s10, 1
	s_add_i32 s4, s9, s28
	s_mov_b32 s5, m0
	s_mov_b32 m0, s4
	s_nop 0
	global_load_lds_dwordx4 v[146:147], off
	s_mov_b32 m0, s5
	v_lshl_add_u64 v[146:147], s[22:23], 0, v[0:1]
	s_addk_i32 s4, 0x2000
	s_mov_b32 s5, m0
	s_mov_b32 m0, s4
	s_nop 0
	global_load_lds_dwordx4 v[146:147], off
	s_mov_b32 m0, s5
	v_max_f32_e32 v0, v115, v115
	v_max_f32_e32 v146, v114, v114
	v_max_f32_e32 v0, v146, v0
	v_max3_f32 v146, v116, v117, v83
	v_max3_f32 v0, v0, v82, v84
	v_max3_f32 v0, v0, v85, v118
	v_max3_f32 v146, v146, v120, v121
	v_max3_f32 v0, v0, v119, v86
	v_max3_f32 v146, v146, v88, v89
	v_max3_f32 v0, v0, v87, v122
	v_max3_f32 v146, v146, v124, v125
	v_max3_f32 v0, v0, v123, v90
	v_max3_f32 v146, v146, v92, v93
	v_max3_f32 v0, v0, v91, v126
	v_max3_f32 v146, v146, v128, v129
	v_max3_f32 v0, v0, v127, v94
	v_max3_f32 v146, v146, v96, v97
	v_max3_f32 v0, v0, v95, v146
	v_mov_b32_e32 v146, v0
	s_nop 1
	v_permlane32_swap_b32_e32 v0, v146
	v_max_f32_e32 v146, v146, v146
	v_max_f32_e32 v0, v0, v0
	v_max_f32_e32 v0, v0, v146
	v_cmp_lt_f32_e32 vcc, s15, v0
	s_mov_b64 s[4:5], -1
	s_cbranch_vccnz .LBB0_648
	s_mov_b64 s[4:5], 0

; #define WAIT_BAR(N) asm volatile("s_waitcnt vmcnt(" #N ") lgkmcnt(0)\n\ts_barrier":::"memory")
;   #define DMA_K(t,slot) glds16(ksrc+(long)(t)*KVBLK*PQ,(unsigned)__builtin_amdgcn_readfirstlane(kdst+(slot)))
;   #define DMA_V(t,slot) glds16(vsrc+(long)(t)*KVBLK*PQ,(unsigned)__builtin_amdgcn_readfirstlane(vdst+(slot)))
; template<int THRL> __device__ __forceinline__ void attn_unit(const bf16*Qblk,const bf16*__restrict__ Kh,const bf16*__restrict__ Vh,bf16*Oblk,const int po,const int NT,char*shm){
;   int tid_=threadIdx.x; asm volatile("":"+v"(tid_));
;   const int tid=tid_,lane=tid&63,r32=lane&31,hi=lane>>5; const int wid=__builtin_amdgcn_readfirstlane(tid>>6);
;   const bf16*Qw=Qblk+(long)wid*QBLK*PQ;
;   const unsigned lds0=(unsigned)(uintptr_t)shm;
;   float*wsf=(float*)(shm+LDS_WS)+wid*64;
;   const bf16*ksrc=Kh+(long)lane*PQ+wid*8;
;   const bf16*vsrc=Vh+(long)(16*(wid&3)+(lane>>2))*PQ+(wid>>2)*32+(lane&3)*8;
;   const unsigned kdst=lds0+LDS_K+wid*1024, vdst=lds0+LDS_V+wid*1024;
;     ...
;   const int vb0=(int)(lds0+LDS_V)+((lane>>4)&1)*32+(lane&3)*8+(4*hi+((lane&15)>>2))*64;
;   const char*Kbase=shm+LDS_K; bf16x8 kf[8];
;   const lds_cptr shm3=(lds_cptr)shm; const lds_cptr kp0=shm3+LDS_K+hi*1024+r32*16; const lds_cptr vp0=shm3+LDS_V+((lane>>4)&1)*32+(lane&3)*8+(4*hi+((lane&15)>>2))*64;
;   DMA_K(0,0);DMA_V(0,0);DMA_K(1,SLOTB);
;   bf16x8 qr[4];
;   #pragma unroll
;   for(int d0=0;d0<4;++d0)qr[d0]=*reinterpret_cast<const bf16x8*>(&Qw[(long)r32*PQ+d0*16+hi*8]);
;   float mhat=0.f,l_reg=0.f;f32x16 o[2];o[0]=f32x16{};o[1]=f32x16{};f32x16 negm=f32x16{};asm volatile("":"+v"(negm));
;     ...
;   bool resc=false;
;     ...
;   f32x16 pA0,pA1,pB0,pB1;
;   int sl_prev=0,sl_cur=0,sl_next=SLOTB;
;     ...
;   DMA_K(2,2*SLOTB);
;   WAIT_BAR(3);
;   qkt(pA0,pA1,Kbase,qr,negm,r32,hi);asm volatile("s_nop 15\n\ts_nop 7":"+v"(pA0),"+v"(pA1));CMASK(pA0,pA1,0);
;   START(pA0,pA1);
;   _Pragma("unroll") for(int r=0;r<16;++r)pA1[r]=__builtin_amdgcn_exp2f(pA1[r]);
;   WAIT_BAR(0);
; DI void p_attn(const bfu* QKV, bfu* AOR, bfu* AO, const float* lq1, const float* lk1, const float* lq2, const float* lk2, const float* subln, float lam_init, bool ctx_out, char* lds, int bx, int G, int vcu, int xmap) {
;     ...
;         if (u < 1024) attn_gqa(QKV, AO, (u >> 6) >> 3, (u >> 6) & 7, CTXL + (size_t)(u & 63) * 256, SEGR / 64, lds);
;         else attn_gqa(QKV, AO, (u - 1024) >> 3, (u - 1024) & 7, 0, CTXL / 64, lds);
.LBB0_666:
	s_andn2_b64 vcc, exec, s[2:3]
	s_mov_b64 s[2:3], -1
	s_cbranch_vccnz .LBB0_657
	s_cmpk_gt_i32 s8, 0x3ff
	s_cbranch_scc0 .LBB0_680
	s_add_i32 s2, s8, 0xfffffc00
	s_lshr_b32 s9, s2, 3
	s_and_b32 s3, s8, 7
	s_mul_i32 s4, s9, 0x4920000
	s_mul_hi_u32 s2, s9, 0x4920000
	s_add_u32 s4, s58, s4
	s_addc_u32 s2, s59, s2
	s_lshl_b32 s5, s3, 7
	s_add_u32 s5, s4, s5
	s_addc_u32 s18, s2, 0
	s_lshl_b32 s6, s8, 5
	s_and_b32 s6, s6, 0x80
	v_mov_b32_e32 v36, v220
	s_add_u32 s6, s4, s6
	s_addc_u32 s7, s2, 0
	v_readfirstlane_b32 s4, v36
	s_ashr_i32 s2, s4, 6
	v_and_b32_e32 v184, 63, v36
	s_mul_i32 s20, s2, 0x24000
	s_mul_hi_i32 s19, s2, 0x24000
	s_add_u32 s20, s5, s20
	v_mul_u32_u24_e32 v0, 0x900, v184
	s_addc_u32 s21, s18, s19
	v_lshlrev_b32_e32 v0, 1, v0
	s_lshl_b32 s18, s2, 3
	v_lshl_add_u64 v[2:3], s[6:7], 0, v[0:1]
	s_ashr_i32 s19, s18, 31
	v_lshl_add_u64 v[34:35], s[18:19], 1, v[2:3]
	s_mov_b64 s[18:19], 0x1000
	v_lshl_add_u64 v[2:3], v[34:35], 0, s[18:19]
	s_lshl_b32 s18, s2, 4
	v_bfe_u32 v0, v36, 2, 4
	v_and_or_b32 v0, s18, 48, v0
	v_mul_u32_u24_e32 v0, 0x900, v0
	s_and_b32 s5, s4, 0x3fffffc0
	v_lshlrev_b32_e32 v0, 1, v0
	s_ashr_i32 s4, s4, 3
	v_lshl_add_u64 v[4:5], s[6:7], 0, v[0:1]
	s_and_b32 s6, s4, 0xffffffe0
	v_lshlrev_b32_e32 v185, 3, v36
	s_ashr_i32 s7, s6, 31
	v_and_b32_e32 v188, 24, v185
	v_lshl_add_u64 v[4:5], s[6:7], 1, v[4:5]
	v_lshlrev_b32_e32 v0, 1, v188
	s_lshl_b32 s4, s2, 10
	v_lshl_add_u64 v[38:39], v[4:5], 0, v[0:1]
	s_mov_b64 s[6:7], 0x1100
	s_cmp_lg_u32 0, -1
	v_lshl_add_u64 v[182:183], v[38:39], 0, s[6:7]
	s_cselect_b32 s6, 0, 0
	v_and_b32_e32 v186, 31, v36
	s_add_i32 s4, s6, s4
	s_mov_b32 s6, m0
	s_mov_b32 m0, s4
	s_nop 0
	global_load_lds_dwordx4 v[2:3], off
	s_mov_b32 m0, s6
	s_add_i32 s18, s4, 0x6000
	s_mov_b32 s6, m0
	s_mov_b32 m0, s18
	s_nop 0
	global_load_lds_dwordx4 v[182:183], off
	s_mov_b32 m0, s6
	v_mul_u32_u24_e32 v0, 0x900, v186
	v_bfe_u32 v187, v36, 5, 1
	s_mov_b64 s[6:7], 0x49000
	v_lshlrev_b32_e32 v0, 1, v0
	v_lshl_add_u64 v[2:3], v[34:35], 0, s[6:7]
	s_add_i32 s6, s4, 0x2000
	s_mov_b32 s7, m0
	s_mov_b32 m0, s6
	s_nop 0
	global_load_lds_dwordx4 v[2:3], off
	s_mov_b32 m0, s7
	v_lshl_or_b32 v0, v187, 4, v0
	global_load_dwordx4 v[142:145], v0, s[20:21] offset:3072
	global_load_dwordx4 v[138:141], v0, s[20:21] offset:3104
	global_load_dwordx4 v[118:121], v0, s[20:21] offset:3136
	global_load_dwordx4 v[114:117], v0, s[20:21] offset:3168
	v_mov_b32_e32 v2, v1
	v_mov_b32_e32 v3, v1
	v_mov_b32_e32 v4, v1
	v_mov_b32_e32 v5, v1
	v_mov_b32_e32 v6, v1
	v_mov_b32_e32 v7, v1
	v_mov_b32_e32 v8, v1
	v_mov_b32_e32 v9, v1
	v_mov_b32_e32 v10, v1
	v_mov_b32_e32 v11, v1
	v_mov_b32_e32 v12, v1
	v_mov_b32_e32 v13, v1
	v_mov_b32_e32 v14, v1
	v_mov_b32_e32 v15, v1
	v_lshlrev_b32_e32 v0, 4, v186
	v_lshl_add_u32 v16, v187, 10, 0
	v_add_u32_e32 v194, v16, v0
	v_mov_b32_e32 v0, v1
	v_mov_b64_e32 v[16:17], v[14:15]
	s_mov_b64 s[6:7], 0x91000
	v_mov_b64_e32 v[14:15], v[12:13]
	v_mov_b64_e32 v[12:13], v[10:11]
	v_mov_b64_e32 v[10:11], v[8:9]
	v_mov_b64_e32 v[8:9], v[6:7]
	v_mov_b64_e32 v[6:7], v[4:5]
	v_mov_b64_e32 v[4:5], v[2:3]
	v_mov_b64_e32 v[2:3], v[0:1]
	v_lshl_add_u64 v[18:19], v[34:35], 0, s[6:7]
	s_add_i32 s6, s4, 0x4000
	s_mov_b32 s7, m0
	s_mov_b32 m0, s6
	s_nop 0
	global_load_lds_dwordx4 v[18:19], off
	s_mov_b32 m0, s7
	s_waitcnt vmcnt(3) lgkmcnt(0)
	s_barrier
	ds_read_b128 v[40:43], v194
	ds_read_b128 v[44:47], v194 offset:512
	s_lshl_b32 s5, s5, 2
	s_mov_b64 s[6:7], 0xd9000
	s_add_i32 s19, s5, 0
	v_lshlrev_b32_e32 v0, 1, v36
	v_lshlrev_b32_e32 v36, 4, v36
	v_and_b32_e32 v0, 32, v0
	v_and_b32_e32 v36, 0xc0, v36
	s_waitcnt vmcnt(3) lgkmcnt(1)
	v_mfma_f32_32x32x16_bf16 v[18:33], v[40:43], v[142:145], v[2:17]
	v_lshl_or_b32 v189, v187, 8, v36
	v_add3_u32 v36, 0, v0, v188
	v_add_u32_e32 v193, v36, v189
	v_cmp_gt_u32_e64 s[40:41], 32, v184
	v_lshl_add_u32 v190, v186, 2, s19
	s_waitcnt lgkmcnt(0)
	v_mfma_f32_32x32x16_bf16 v[2:17], v[44:47], v[142:145], v[2:17]
	ds_read_b128 v[40:43], v194 offset:2048
	ds_read_b128 v[44:47], v194 offset:2560
	s_waitcnt vmcnt(2) lgkmcnt(1)
	v_mfma_f32_32x32x16_bf16 v[18:33], v[40:43], v[138:141], v[18:33]
	s_waitcnt lgkmcnt(0)
	v_mfma_f32_32x32x16_bf16 v[2:17], v[44:47], v[138:141], v[2:17]
	ds_read_b128 v[40:43], v194 offset:4096
	ds_read_b128 v[44:47], v194 offset:4608
	s_waitcnt vmcnt(1) lgkmcnt(1)
	v_mfma_f32_32x32x16_bf16 v[18:33], v[40:43], v[118:121], v[18:33]
	s_waitcnt lgkmcnt(0)
	v_mfma_f32_32x32x16_bf16 v[2:17], v[44:47], v[118:121], v[2:17]
	ds_read_b128 v[40:43], v194 offset:6144
	ds_read_b128 v[44:47], v194 offset:6656
	s_waitcnt vmcnt(0) lgkmcnt(1)
	v_mfma_f32_32x32x16_bf16 v[18:33], v[40:43], v[114:117], v[18:33]
	s_waitcnt lgkmcnt(0)
	v_mfma_f32_32x32x16_bf16 v[2:17], v[44:47], v[114:117], v[2:17]
	s_nop 15
	s_nop 7
	s_nop 0
	v_max3_f32 v37, v18, v19, v2
	v_max3_f32 v40, v20, v21, v3
	s_nop 0
	v_max3_f32 v37, v37, v4, v5
	v_max3_f32 v40, v40, v24, v25
	s_nop 0
	v_max3_f32 v37, v37, v22, v23
	v_max3_f32 v40, v40, v8, v9
	s_nop 0
	v_max3_f32 v37, v37, v6, v7
	v_max3_f32 v40, v40, v28, v29
	s_nop 0
	v_max3_f32 v37, v37, v26, v27
	v_max3_f32 v40, v40, v12, v13
	s_nop 0
	v_max3_f32 v37, v37, v10, v11
	v_max3_f32 v40, v40, v32, v33
	s_nop 0
	v_max3_f32 v37, v37, v30, v31
	v_max3_f32 v40, v40, v16, v17
	s_nop 0
	v_max3_f32 v37, v37, v14, v15
	s_nop 0
	v_max_f32_e32 v37, v37, v40
	s_nop 0
	v_mov_b32_e32 v40, v37
	s_nop 1
	v_permlane32_swap_b32_e32 v37, v40
	v_max_f32_e32 v37, v37, v40
	s_nop 0
	v_add_f32_e32 v191, v1, v37
	v_sub_f32_e32 v40, v2, v37
	v_sub_f32_e32 v18, v18, v37
	v_sub_f32_e32 v19, v19, v37
	v_sub_f32_e32 v41, v3, v37
	v_sub_f32_e32 v20, v20, v37
	s_nop 0
	v_xor_b32_e32 v2, 0x80000000, v191
	v_sub_f32_e32 v42, v4, v37
	v_sub_f32_e32 v21, v21, v37
	v_sub_f32_e32 v43, v5, v37
	v_sub_f32_e32 v22, v22, v37
	v_sub_f32_e32 v44, v6, v37
	v_sub_f32_e32 v23, v23, v37
	v_sub_f32_e32 v45, v7, v37
	v_sub_f32_e32 v24, v24, v37
	v_sub_f32_e32 v46, v8, v37
	v_sub_f32_e32 v25, v25, v37
	v_sub_f32_e32 v47, v9, v37
	v_sub_f32_e32 v26, v26, v37
	v_sub_f32_e32 v48, v10, v37
	v_sub_f32_e32 v27, v27, v37
	v_sub_f32_e32 v49, v11, v37
	v_sub_f32_e32 v28, v28, v37
	v_sub_f32_e32 v50, v12, v37
	v_sub_f32_e32 v29, v29, v37
	v_sub_f32_e32 v51, v13, v37
	v_sub_f32_e32 v30, v30, v37
	v_sub_f32_e32 v52, v14, v37
	v_sub_f32_e32 v31, v31, v37
	v_sub_f32_e32 v53, v15, v37
	v_sub_f32_e32 v32, v32, v37
	v_sub_f32_e32 v54, v16, v37
	v_sub_f32_e32 v33, v33, v37
	v_sub_f32_e32 v37, v17, v37
	v_mov_b32_e32 v3, v2
	v_mov_b32_e32 v4, v2
	v_mov_b32_e32 v5, v2
	v_mov_b32_e32 v6, v2
	v_mov_b32_e32 v7, v2
	v_mov_b32_e32 v8, v2
	v_mov_b32_e32 v9, v2
	v_mov_b32_e32 v10, v2
	v_mov_b32_e32 v11, v2
	v_mov_b32_e32 v12, v2
	v_mov_b32_e32 v13, v2
	v_mov_b32_e32 v14, v2
	v_mov_b32_e32 v15, v2
	v_mov_b32_e32 v16, v2
	v_mov_b32_e32 v17, v2
	s_waitcnt vmcnt(0) lgkmcnt(0)
	s_barrier
; #define WAIT_BAR(N) asm volatile("s_waitcnt vmcnt(" #N ") lgkmcnt(0)\n\ts_barrier":::"memory")
;   #define DMA_K(t,slot) glds16(ksrc+(long)(t)*KVBLK*PQ,(unsigned)__builtin_amdgcn_readfirstlane(kdst+(slot)))
;   #define DMA_V(t,slot) glds16(vsrc+(long)(t)*KVBLK*PQ,(unsigned)__builtin_amdgcn_readfirstlane(vdst+(slot)))
;   #define ROT() do{sl_prev=sl_cur;sl_cur=sl_next;sl_next=(sl_next==(NSLOT-1)*SLOTB)?0:sl_next+SLOTB;}while(0)
;   #define DMA_K(t,slot) glds16((const char*)Kh+(size_t)(t)*(KVBLK*PQ*2)+koff,(unsigned)__builtin_amdgcn_readfirstlane(kdst+(slot)))
;   #define DMA_V(t,slot) do{ glds16((const char*)Vh+(size_t)(t)*(KVBLK*PQ*2)+voff,(unsigned)__builtin_amdgcn_readfirstlane(vdst+2*(slot))); glds16((const char*)Vh+(size_t)(t)*(KVBLK*PQ*2)+128+voff,(unsigned)__builtin_amdgcn_readfirstlane(vdst+2*(slot)+8192)); }while(0)
;   #define ROT() do{sl_prev=sl_cur;sl_cur=sl_next;sl_next=(sl_next==(NSLOT-1)*SLOTB)?0:sl_next+SLOTB;}while(0)
; template<int THRL> __device__ __forceinline__ void attn_unit(const bf16*Qblk,const bf16*__restrict__ Kh,const bf16*__restrict__ Vh,bf16*Oblk,const int po,const int NT,char*shm){
;     ...
;   _Pragma("unroll") for(int r=0;r<16;++r)pA1[r]=__builtin_amdgcn_exp2f(pA1[r]);
;   WAIT_BAR(0);
;   DMA_K(3,0);DMA_V(1,SLOTB);
;   ROT();
;   kload8(kf,kp0+sl_cur);
;   WAIT_BAR(2);
;   s16x4 vlo[8],vhi[8]; u32x4 pw0,pw1,pw2,pw3;
	v_exp_f32_e32 v55, v18
	v_exp_f32_e32 v56, v19
	v_lshl_add_u64 v[18:19], v[34:35], 0, s[6:7]
	s_mov_b32 s5, m0
	s_mov_b32 m0, s4
	s_nop 0
	global_load_lds_dwordx4 v[18:19], off
	s_mov_b32 m0, s5
	s_mov_b64 s[6:7], 0x49100
	v_lshl_add_u64 v[18:19], v[38:39], 0, s[6:7]
	s_add_i32 s5, s4, 0x8000
	s_mov_b32 s6, m0
	s_mov_b32 m0, s5
	s_nop 0
	global_load_lds_dwordx4 v[18:19], off
	s_mov_b32 m0, s6
	v_exp_f32_e32 v59, v22
	v_exp_f32_e32 v60, v23
	v_exp_f32_e32 v61, v24
	v_exp_f32_e32 v62, v25
	v_exp_f32_e32 v63, v26
	v_exp_f32_e32 v64, v27
	v_exp_f32_e32 v65, v28
	v_exp_f32_e32 v94, v29
	v_exp_f32_e32 v95, v30
	v_exp_f32_e32 v96, v31
	v_exp_f32_e32 v97, v32
	v_exp_f32_e32 v130, v33
	v_exp_f32_e32 v131, v40
	v_exp_f32_e32 v132, v41
	v_exp_f32_e32 v133, v42
	v_exp_f32_e32 v134, v43
	v_exp_f32_e32 v135, v44
	v_exp_f32_e32 v136, v45
	v_exp_f32_e32 v137, v46
	v_exp_f32_e32 v146, v47
	ds_read_b128 v[22:25], v194 offset:8192
	ds_read_b128 v[26:29], v194 offset:8704
	ds_read_b128 v[30:33], v194 offset:10240
	ds_read_b128 v[40:43], v194 offset:10752
	ds_read_b128 v[44:47], v194 offset:12288
	ds_read_b128 v[82:85], v194 offset:12800
	ds_read_b128 v[86:89], v194 offset:14336
	ds_read_b128 v[90:93], v194 offset:14848
	v_exp_f32_e32 v57, v20
	v_exp_f32_e32 v58, v21
	s_waitcnt vmcnt(2) lgkmcnt(0)
	s_barrier
	v_exp_f32_e32 v48, v48
	v_exp_f32_e32 v49, v49
	v_exp_f32_e32 v147, v50
	v_exp_f32_e32 v148, v51
	v_exp_f32_e32 v149, v52
	v_exp_f32_e32 v150, v53
	v_exp_f32_e32 v151, v54
	v_exp_f32_e32 v152, v37
	ds_read_b64_tr_b16 v[18:19], v193 offset:24576
	ds_read_b64_tr_b16 v[20:21], v193 offset:25088
	s_waitcnt lgkmcnt(9)
	v_mfma_f32_32x32x16_bf16 v[98:113], v[22:25], v[142:145], v[2:17]
	v_add_f32_e32 v34, v55, v56
	v_add_f32_e32 v34, v34, v57
	v_add_f32_e32 v34, v34, v58
	v_add_f32_e32 v34, v34, v59
	v_add_f32_e32 v50, v34, v60
	v_cvt_pk_bf16_f32 v126, v55, v56
	v_cvt_pk_bf16_f32 v127, v57, v58
	ds_read_b64_tr_b16 v[34:35], v193 offset:28672
	ds_read_b64_tr_b16 v[36:37], v193 offset:29184
	s_waitcnt lgkmcnt(10)
	v_mfma_f32_32x32x16_bf16 v[66:81], v[26:29], v[142:145], v[2:17]
	v_add_f32_e32 v22, v61, v50
	v_add_f32_e32 v22, v62, v22
	v_add_f32_e32 v22, v63, v22
	v_add_f32_e32 v22, v64, v22
	v_cvt_pk_bf16_f32 v128, v59, v60
	v_cvt_pk_bf16_f32 v129, v61, v62
	ds_read_b64_tr_b16 v[50:51], v193 offset:25600
	ds_read_b64_tr_b16 v[52:53], v193 offset:26112
	s_waitcnt lgkmcnt(11)
	v_mfma_f32_32x32x16_bf16 v[98:113], v[30:33], v[138:141], v[98:113]
	v_add_f32_e32 v22, v65, v22
	v_add_f32_e32 v22, v94, v22
	v_add_f32_e32 v22, v95, v22
	v_add_f32_e32 v22, v96, v22
	v_cvt_pk_bf16_f32 v122, v63, v64
	v_cvt_pk_bf16_f32 v123, v65, v94
	ds_read_b64_tr_b16 v[54:55], v193 offset:29696
	ds_read_b64_tr_b16 v[56:57], v193 offset:30208
	s_waitcnt lgkmcnt(12)
	v_mfma_f32_32x32x16_bf16 v[66:81], v[40:43], v[138:141], v[66:81]
	v_add_f32_e32 v22, v97, v22
	v_add_f32_e32 v22, v130, v22
	v_add_f32_e32 v22, v131, v22
	v_add_f32_e32 v22, v132, v22
	v_cvt_pk_bf16_f32 v124, v95, v96
	v_cvt_pk_bf16_f32 v125, v97, v130
	ds_read_b64_tr_b16 v[58:59], v193 offset:26624
	ds_read_b64_tr_b16 v[60:61], v193 offset:27136
	s_waitcnt lgkmcnt(13)
	v_mfma_f32_32x32x16_bf16 v[98:113], v[44:47], v[118:121], v[98:113]
	v_add_f32_e32 v22, v133, v22
	v_add_f32_e32 v22, v134, v22
	v_add_f32_e32 v22, v135, v22
	v_add_f32_e32 v22, v136, v22
	v_cvt_pk_bf16_f32 v130, v131, v132
	v_cvt_pk_bf16_f32 v131, v133, v134
	ds_read_b64_tr_b16 v[62:63], v193 offset:30720
	ds_read_b64_tr_b16 v[64:65], v193 offset:31232
	s_waitcnt lgkmcnt(14)
	v_mfma_f32_32x32x16_bf16 v[66:81], v[82:85], v[118:121], v[66:81]
	v_add_f32_e32 v22, v137, v22
	v_add_f32_e32 v22, v146, v22
	v_add_f32_e32 v22, v48, v22
	v_add_f32_e32 v22, v49, v22
	v_cvt_pk_bf16_f32 v132, v135, v136
	v_cvt_pk_bf16_f32 v133, v137, v146
	ds_read_b64_tr_b16 v[82:83], v193 offset:27648
	ds_read_b64_tr_b16 v[84:85], v193 offset:28160
	s_waitcnt lgkmcnt(14)
	v_mfma_f32_32x32x16_bf16 v[98:113], v[86:89], v[114:117], v[98:113]
	v_add_f32_e32 v22, v147, v22
	v_add_f32_e32 v22, v148, v22
	v_add_f32_e32 v22, v149, v22
	v_add_f32_e32 v22, v150, v22
	v_cvt_pk_bf16_f32 v134, v48, v49
	v_cvt_pk_bf16_f32 v135, v147, v148
	ds_read_b64_tr_b16 v[86:87], v193 offset:31744
	ds_read_b64_tr_b16 v[88:89], v193 offset:32256
	v_mfma_f32_32x32x16_bf16 v[66:81], v[90:93], v[114:117], v[66:81]
	v_add_f32_e32 v22, v151, v22
	v_add_f32_e32 v22, v152, v22
	v_add_f32_e32 v22, 0, v22
	v_cvt_pk_bf16_f32 v136, v149, v150
	v_cvt_pk_bf16_f32 v137, v151, v152
	s_mov_b64 s[6:7], 0x91100
	v_add_f32_e32 v195, 0, v22
	v_lshl_add_u64 v[22:23], v[38:39], 0, s[6:7]
	s_add_i32 s4, s4, 0xa000
	s_mov_b32 s5, m0
	s_mov_b32 m0, s4
	s_nop 0
	global_load_lds_dwordx4 v[22:23], off
	s_mov_b32 m0, s5
	v_max_f32_e32 v22, v99, v99
	v_max_f32_e32 v23, v98, v98
	v_max_f32_e32 v22, v23, v22
	v_max3_f32 v23, v100, v101, v67
	v_max3_f32 v22, v22, v66, v68
	v_max3_f32 v22, v22, v69, v102
	v_max3_f32 v23, v23, v104, v105
	v_max3_f32 v22, v22, v103, v70
	v_max3_f32 v23, v23, v72, v73
	v_max3_f32 v22, v22, v71, v106
	v_max3_f32 v23, v23, v108, v109
	v_max3_f32 v22, v22, v107, v74
	v_max3_f32 v23, v23, v76, v77
	v_max3_f32 v22, v22, v75, v110
	v_max3_f32 v23, v23, v112, v113
	v_max3_f32 v22, v22, v111, v78
	v_max3_f32 v23, v23, v80, v81
	v_max3_f32 v22, v22, v79, v23
	v_mov_b32_e32 v23, v22
	s_nop 1
	v_permlane32_swap_b32_e32 v22, v23
	v_max_f32_e32 v23, v23, v23
	v_max_f32_e32 v22, v22, v22
	v_max_f32_e32 v22, v22, v23
	v_cmp_lt_f32_e32 vcc, s15, v22
	s_mov_b64 s[4:5], -1
	s_cbranch_vccnz .LBB0_713
	s_mov_b64 s[4:5], 0

.LBB0_674:
	ds_read_b64_tr_b16 v[98:99], v193 offset:40960
	ds_read_b64_tr_b16 v[100:101], v193 offset:41472
	v_add_f32_e32 v66, v82, v83
	v_add_f32_e32 v66, v84, v66
	v_add_f32_e32 v66, v85, v66
	v_add_f32_e32 v66, v86, v66
	v_add_f32_e32 v106, v87, v66
	s_waitcnt lgkmcnt(9)
	v_mfma_f32_32x32x16_bf16 v[66:81], v[166:169], v[142:145], v[2:17]
	v_cvt_pk_bf16_f32 v126, v82, v83
	v_cvt_pk_bf16_f32 v127, v84, v85
	ds_read_b64_tr_b16 v[82:83], v193 offset:45056
	ds_read_b64_tr_b16 v[84:85], v193 offset:45568
	s_waitcnt lgkmcnt(10)
	v_mfma_f32_32x32x16_bf16 v[2:17], v[162:165], v[142:145], v[2:17]
	v_add_f32_e32 v106, v88, v106
	v_add_f32_e32 v106, v89, v106
	v_add_f32_e32 v106, v90, v106
	v_add_f32_e32 v106, v91, v106
	v_cvt_pk_bf16_f32 v128, v86, v87
	v_cvt_pk_bf16_f32 v129, v88, v89
	ds_read_b64_tr_b16 v[86:87], v193 offset:41984
	ds_read_b64_tr_b16 v[88:89], v193 offset:42496
	s_waitcnt lgkmcnt(11)
	v_mfma_f32_32x32x16_bf16 v[66:81], v[158:161], v[138:141], v[66:81]
	v_add_f32_e32 v106, v92, v106
	v_add_f32_e32 v106, v93, v106
	v_add_f32_e32 v106, v94, v106
	v_add_f32_e32 v106, v95, v106
	v_cvt_pk_bf16_f32 v122, v90, v91
	v_cvt_pk_bf16_f32 v123, v92, v93
	ds_read_b64_tr_b16 v[90:91], v193 offset:46080
	ds_read_b64_tr_b16 v[92:93], v193 offset:46592
	s_waitcnt lgkmcnt(12)
	v_mfma_f32_32x32x16_bf16 v[2:17], v[154:157], v[138:141], v[2:17]
	v_add_f32_e32 v106, v96, v106
	v_add_f32_e32 v106, v97, v106
	v_add_f32_e32 v106, v50, v106
	v_add_f32_e32 v106, v51, v106
	v_cvt_pk_bf16_f32 v124, v94, v95
	v_cvt_pk_bf16_f32 v125, v96, v97
	ds_read_b64_tr_b16 v[94:95], v193 offset:43008
	ds_read_b64_tr_b16 v[96:97], v193 offset:43520
	s_waitcnt lgkmcnt(13)
	v_mfma_f32_32x32x16_bf16 v[66:81], v[102:105], v[118:121], v[66:81]
	v_add_f32_e32 v102, v52, v106
	v_add_f32_e32 v102, v53, v102
	v_add_f32_e32 v102, v54, v102
	v_add_f32_e32 v106, v55, v102
	v_cvt_pk_bf16_f32 v130, v50, v51
	v_cvt_pk_bf16_f32 v131, v52, v53
	ds_read_b64_tr_b16 v[102:103], v193 offset:47104
	ds_read_b64_tr_b16 v[104:105], v193 offset:47616
	s_waitcnt lgkmcnt(14)
	v_mfma_f32_32x32x16_bf16 v[2:17], v[150:153], v[118:121], v[2:17]
	v_add_f32_e32 v50, v56, v106
	v_add_f32_e32 v50, v57, v50
	v_add_f32_e32 v50, v58, v50
	v_add_f32_e32 v50, v59, v50
	v_cvt_pk_bf16_f32 v132, v54, v55
	v_cvt_pk_bf16_f32 v133, v56, v57
	ds_read_b64_tr_b16 v[106:107], v193 offset:44032
	ds_read_b64_tr_b16 v[108:109], v193 offset:44544
	s_waitcnt lgkmcnt(14)
	v_mfma_f32_32x32x16_bf16 v[66:81], v[146:149], v[114:117], v[66:81]
	v_add_f32_e32 v50, v60, v50
	v_add_f32_e32 v50, v61, v50
	v_add_f32_e32 v50, v62, v50
	v_add_f32_e32 v50, v63, v50
	v_cvt_pk_bf16_f32 v134, v58, v59
	v_cvt_pk_bf16_f32 v135, v60, v61
	ds_read_b64_tr_b16 v[118:119], v193 offset:48128
	ds_read_b64_tr_b16 v[120:121], v193 offset:48640
	v_mfma_f32_32x32x16_bf16 v[2:17], v[110:113], v[114:117], v[2:17]
	v_add_f32_e32 v50, v64, v50
	v_add_f32_e32 v50, v65, v50
	v_add_f32_e32 v50, 0, v50
	v_cvt_pk_bf16_f32 v136, v62, v63
	v_cvt_pk_bf16_f32 v137, v64, v65
	v_max_f32_e32 v51, v67, v67
	v_max_f32_e32 v52, v66, v66
	v_max_f32_e32 v51, v52, v51
	s_nop 3
	v_max3_f32 v52, v68, v69, v3
	v_max3_f32 v51, v51, v2, v4
	v_max3_f32 v51, v51, v5, v70
	v_max3_f32 v52, v52, v72, v73
	v_max3_f32 v51, v51, v71, v6
	v_max3_f32 v52, v52, v8, v9
	v_max3_f32 v51, v51, v7, v74
	v_max3_f32 v52, v52, v76, v77
	v_max3_f32 v51, v51, v75, v10
	v_max3_f32 v52, v52, v12, v13
	v_max3_f32 v51, v51, v11, v78
	v_max3_f32 v52, v52, v80, v81
	v_max3_f32 v51, v51, v79, v14
	v_max3_f32 v52, v52, v16, v17
	v_add_f32_e32 v110, v170, v50
	v_max3_f32 v50, v51, v15, v52
	v_mov_b32_e32 v51, v50
	s_nop 1
	v_permlane32_swap_b32_e32 v50, v51
	v_max_f32_e32 v51, v51, v51
	v_max_f32_e32 v50, v50, v50
	v_max_f32_e32 v50, v50, v51
	v_cmp_lt_f32_e32 vcc, s15, v50
	s_mov_b64 s[4:5], -1
	s_cbranch_vccnz .LBB0_719
	s_mov_b64 s[4:5], 0

.LBB0_682:
	v_add_u32_e32 v187, s6, v211
	ds_read_b64_tr_b16 v[178:179], v187 offset:24576
	ds_read_b64_tr_b16 v[180:181], v187 offset:25088
	v_mfma_f32_32x32x16_bf16 v[98:113], v[82:85], v[158:161], v[34:49]
	v_add_f32_e32 v86, v66, v67
	v_add_f32_e32 v86, v68, v86
	v_add_f32_e32 v86, v69, v86
	v_add_f32_e32 v86, v70, v86
	v_add_f32_e32 v86, v71, v86
	v_cvt_pk_bf16_f32 v150, v66, v67
	v_cvt_pk_bf16_f32 v151, v68, v69
	ds_read_b64_tr_b16 v[174:175], v187 offset:28672
	ds_read_b64_tr_b16 v[176:177], v187 offset:29184
	v_add_f32_e32 v66, v72, v86
	v_mfma_f32_32x32x16_bf16 v[82:97], v[166:169], v[158:161], v[34:49]
	v_add_f32_e32 v66, v73, v66
	v_add_f32_e32 v66, v74, v66
	v_add_f32_e32 v130, v75, v66
	v_cvt_pk_bf16_f32 v152, v70, v71
	v_cvt_pk_bf16_f32 v153, v72, v73
	ds_read_b64_tr_b16 v[66:67], v187 offset:25600
	ds_read_b64_tr_b16 v[68:69], v187 offset:26112
	v_mfma_f32_32x32x16_bf16 v[98:113], v[170:173], v[154:157], v[98:113]
	v_add_f32_e32 v70, v76, v130
	v_add_f32_e32 v70, v77, v70
	v_add_f32_e32 v70, v78, v70
	v_add_f32_e32 v130, v79, v70
	v_cvt_pk_bf16_f32 v142, v74, v75
	v_cvt_pk_bf16_f32 v143, v76, v77
	ds_read_b64_tr_b16 v[70:71], v187 offset:29696
	ds_read_b64_tr_b16 v[72:73], v187 offset:30208
	v_mfma_f32_32x32x16_bf16 v[82:97], v[162:165], v[154:157], v[82:97]
	v_add_f32_e32 v74, v80, v130
	v_add_f32_e32 v74, v81, v74
	v_add_f32_e32 v74, v50, v74
	v_add_f32_e32 v130, v51, v74
	v_cvt_pk_bf16_f32 v144, v78, v79
	v_cvt_pk_bf16_f32 v145, v80, v81
	ds_read_b64_tr_b16 v[74:75], v187 offset:26624
	ds_read_b64_tr_b16 v[76:77], v187 offset:27136
	v_mfma_f32_32x32x16_bf16 v[98:113], v[126:129], v[146:149], v[98:113]
	v_add_f32_e32 v78, v52, v130
	v_add_f32_e32 v78, v53, v78
	v_add_f32_e32 v78, v54, v78
	v_add_f32_e32 v78, v55, v78
	v_cvt_pk_bf16_f32 v134, v50, v51
	v_cvt_pk_bf16_f32 v135, v52, v53
	ds_read_b64_tr_b16 v[50:51], v187 offset:30720
	ds_read_b64_tr_b16 v[52:53], v187 offset:31232
	v_mfma_f32_32x32x16_bf16 v[82:97], v[122:125], v[146:149], v[82:97]
	v_add_f32_e32 v78, v56, v78
	v_add_f32_e32 v78, v57, v78
	v_add_f32_e32 v78, v58, v78
	v_add_f32_e32 v78, v59, v78
	v_cvt_pk_bf16_f32 v136, v54, v55
	v_cvt_pk_bf16_f32 v137, v56, v57
	ds_read_b64_tr_b16 v[54:55], v187 offset:27648
	ds_read_b64_tr_b16 v[56:57], v187 offset:28160
	v_mfma_f32_32x32x16_bf16 v[98:113], v[118:121], v[138:141], v[98:113]
	v_add_f32_e32 v78, v60, v78
	v_add_f32_e32 v78, v61, v78
	v_add_f32_e32 v78, v62, v78
	v_add_f32_e32 v78, v63, v78
	v_cvt_pk_bf16_f32 v130, v58, v59
	v_cvt_pk_bf16_f32 v131, v60, v61
	ds_read_b64_tr_b16 v[58:59], v187 offset:31744
	ds_read_b64_tr_b16 v[60:61], v187 offset:32256
	v_mfma_f32_32x32x16_bf16 v[82:97], v[114:117], v[138:141], v[82:97]
	v_add_f32_e32 v78, v64, v78
	v_add_f32_e32 v78, v65, v78
	v_cvt_pk_bf16_f32 v132, v62, v63
	v_cvt_pk_bf16_f32 v133, v64, v65
	v_add_f32_e32 v186, v186, v78
	v_max3_f32 v62, v98, v99, v100
	v_max3_f32 v63, v101, v102, v103
	v_max3_f32 v62, v62, v104, v105
	v_max3_f32 v63, v63, v106, v107
	v_max3_f32 v62, v62, v108, v109
	v_max3_f32 v63, v63, v110, v111
	v_max3_f32 v62, v62, v112, v113
	v_max3_f32 v63, v63, v82, v83
	v_max3_f32 v62, v62, v84, v85
	v_max3_f32 v63, v63, v86, v87
	v_max3_f32 v62, v62, v88, v89
	v_max3_f32 v63, v63, v90, v91
	v_max3_f32 v62, v62, v92, v93
	v_max3_f32 v63, v63, v94, v95
	v_max3_f32 v62, v62, v96, v97
	v_max_f32_e32 v62, v62, v63
	v_mov_b32_e32 v63, v62
	s_nop 1
	v_permlane32_swap_b32_e32 v62, v63
	v_max_f32_e32 v62, v62, v63
	v_cmp_lt_f32_e32 vcc, s15, v62
	s_mov_b64 s[6:7], -1
	s_cbranch_vccnz .LBB0_690
	s_mov_b64 s[6:7], 0

.LBB0_685:
	s_add_i32 s6, s23, 0x2000
	s_cmpk_lg_i32 s23, 0x4000
	s_cselect_b32 s24, s6, 0
	v_add_u32_e32 v187, s26, v211
	ds_read_b64_tr_b16 v[118:119], v187 offset:24576
	ds_read_b64_tr_b16 v[120:121], v187 offset:25088
	v_mfma_f32_32x32x16_bf16 v[66:81], v[62:65], v[158:161], v[34:49]
	v_add_f32_e32 v50, v98, v99
	v_add_f32_e32 v50, v100, v50
	v_add_f32_e32 v50, v101, v50
	v_add_f32_e32 v50, v102, v50
	v_add_f32_e32 v50, v103, v50
	v_cvt_pk_bf16_f32 v150, v98, v99
	v_cvt_pk_bf16_f32 v151, v100, v101
	ds_read_b64_tr_b16 v[114:115], v187 offset:28672
	ds_read_b64_tr_b16 v[116:117], v187 offset:29184
	v_add_f32_e32 v50, v104, v50
	v_add_f32_e32 v50, v105, v50
	v_add_f32_e32 v50, v106, v50
	v_add_f32_e32 v130, v107, v50
	v_mfma_f32_32x32x16_bf16 v[50:65], v[174:177], v[158:161], v[34:49]
	v_cvt_pk_bf16_f32 v152, v102, v103
	v_cvt_pk_bf16_f32 v153, v104, v105
	ds_read_b64_tr_b16 v[98:99], v187 offset:25600
	ds_read_b64_tr_b16 v[100:101], v187 offset:26112
	v_mfma_f32_32x32x16_bf16 v[66:81], v[178:181], v[154:157], v[66:81]
	v_add_f32_e32 v102, v108, v130
	v_add_f32_e32 v102, v109, v102
	v_add_f32_e32 v102, v110, v102
	v_add_f32_e32 v130, v111, v102
	v_cvt_pk_bf16_f32 v142, v106, v107
	v_cvt_pk_bf16_f32 v143, v108, v109
	ds_read_b64_tr_b16 v[102:103], v187 offset:29696
	ds_read_b64_tr_b16 v[104:105], v187 offset:30208
	v_mfma_f32_32x32x16_bf16 v[50:65], v[170:173], v[154:157], v[50:65]
	v_add_f32_e32 v106, v112, v130
	v_add_f32_e32 v106, v113, v106
	v_add_f32_e32 v106, v82, v106
	v_add_f32_e32 v130, v83, v106
	v_cvt_pk_bf16_f32 v144, v110, v111
	v_cvt_pk_bf16_f32 v145, v112, v113
	ds_read_b64_tr_b16 v[106:107], v187 offset:26624
	ds_read_b64_tr_b16 v[108:109], v187 offset:27136
	v_mfma_f32_32x32x16_bf16 v[66:81], v[166:169], v[146:149], v[66:81]
	v_add_f32_e32 v110, v84, v130
	v_add_f32_e32 v110, v85, v110
	v_add_f32_e32 v110, v86, v110
	v_add_f32_e32 v130, v87, v110
	v_cvt_pk_bf16_f32 v134, v82, v83
	v_cvt_pk_bf16_f32 v135, v84, v85
	ds_read_b64_tr_b16 v[110:111], v187 offset:30720
	ds_read_b64_tr_b16 v[112:113], v187 offset:31232
	v_mfma_f32_32x32x16_bf16 v[50:65], v[162:165], v[146:149], v[50:65]
	v_add_f32_e32 v82, v88, v130
	v_add_f32_e32 v82, v89, v82
	v_add_f32_e32 v82, v90, v82
	v_add_f32_e32 v82, v91, v82
	v_cvt_pk_bf16_f32 v136, v86, v87
	v_cvt_pk_bf16_f32 v137, v88, v89
	ds_read_b64_tr_b16 v[86:87], v187 offset:27648
	ds_read_b64_tr_b16 v[88:89], v187 offset:28160
	v_mfma_f32_32x32x16_bf16 v[66:81], v[126:129], v[138:141], v[66:81]
	v_add_f32_e32 v82, v92, v82
	v_add_f32_e32 v82, v93, v82
	v_add_f32_e32 v82, v94, v82
	v_add_f32_e32 v82, v95, v82
	v_cvt_pk_bf16_f32 v130, v90, v91
	v_cvt_pk_bf16_f32 v131, v92, v93
	ds_read_b64_tr_b16 v[90:91], v187 offset:31744
	ds_read_b64_tr_b16 v[92:93], v187 offset:32256
	v_mfma_f32_32x32x16_bf16 v[50:65], v[122:125], v[138:141], v[50:65]
	v_add_f32_e32 v82, v96, v82
	v_add_f32_e32 v82, v97, v82
	v_cvt_pk_bf16_f32 v132, v94, v95
	v_cvt_pk_bf16_f32 v133, v96, v97
	v_add_f32_e32 v186, v186, v82
	v_max3_f32 v82, v66, v67, v68
	v_max3_f32 v83, v69, v70, v71
	v_max3_f32 v82, v82, v72, v73
	v_max3_f32 v83, v83, v74, v75
	v_max3_f32 v82, v82, v76, v77
	v_max3_f32 v83, v83, v78, v79
	v_max3_f32 v82, v82, v80, v81
	v_max3_f32 v83, v83, v50, v51
	v_max3_f32 v82, v82, v52, v53
	v_max3_f32 v83, v83, v54, v55
	v_max3_f32 v82, v82, v56, v57
	v_max3_f32 v83, v83, v58, v59
	v_max3_f32 v82, v82, v60, v61
	v_max3_f32 v83, v83, v62, v63
	v_max3_f32 v82, v82, v64, v65
	v_max_f32_e32 v82, v82, v83
	v_mov_b32_e32 v83, v82
	s_nop 1
	v_permlane32_swap_b32_e32 v82, v83
	v_max_f32_e32 v82, v82, v83
	v_cmp_lt_f32_e32 vcc, s15, v82
	s_mov_b64 s[6:7], -1
	s_cbranch_vccnz .LBB0_693
	s_mov_b64 s[6:7], 0

.LBB0_708:
	v_add_u32_e32 v171, s22, v211
	ds_read_b64_tr_b16 v[98:99], v171 offset:24576
	ds_read_b64_tr_b16 v[100:101], v171 offset:25088
	v_add_f32_e32 v66, v82, v83
	v_add_f32_e32 v66, v84, v66
	v_add_f32_e32 v66, v85, v66
	v_add_f32_e32 v66, v86, v66
	v_add_f32_e32 v106, v87, v66
	s_waitcnt lgkmcnt(9)
	v_mfma_f32_32x32x16_bf16 v[66:81], v[166:169], v[158:161], v[34:49]
	v_cvt_pk_bf16_f32 v150, v82, v83
	v_cvt_pk_bf16_f32 v151, v84, v85
	ds_read_b64_tr_b16 v[82:83], v171 offset:28672
	ds_read_b64_tr_b16 v[84:85], v171 offset:29184
	s_waitcnt lgkmcnt(10)
	v_mfma_f32_32x32x16_bf16 v[34:49], v[162:165], v[158:161], v[34:49]
	v_add_f32_e32 v106, v88, v106
	v_add_f32_e32 v106, v89, v106
	v_add_f32_e32 v106, v90, v106
	v_add_f32_e32 v106, v91, v106
	v_cvt_pk_bf16_f32 v152, v86, v87
	v_cvt_pk_bf16_f32 v153, v88, v89
	ds_read_b64_tr_b16 v[86:87], v171 offset:25600
	ds_read_b64_tr_b16 v[88:89], v171 offset:26112
	s_waitcnt lgkmcnt(11)
	v_mfma_f32_32x32x16_bf16 v[66:81], v[126:129], v[154:157], v[66:81]
	v_add_f32_e32 v106, v92, v106
	v_add_f32_e32 v106, v93, v106
	v_add_f32_e32 v106, v94, v106
	v_add_f32_e32 v106, v95, v106
	v_cvt_pk_bf16_f32 v142, v90, v91
	v_cvt_pk_bf16_f32 v143, v92, v93
	ds_read_b64_tr_b16 v[90:91], v171 offset:29696
	ds_read_b64_tr_b16 v[92:93], v171 offset:30208
	s_waitcnt lgkmcnt(12)
	v_mfma_f32_32x32x16_bf16 v[34:49], v[122:125], v[154:157], v[34:49]
	v_add_f32_e32 v106, v96, v106
	v_add_f32_e32 v106, v97, v106
	v_add_f32_e32 v106, v50, v106
	v_add_f32_e32 v106, v51, v106
	v_cvt_pk_bf16_f32 v144, v94, v95
	v_cvt_pk_bf16_f32 v145, v96, v97
	ds_read_b64_tr_b16 v[94:95], v171 offset:26624
	ds_read_b64_tr_b16 v[96:97], v171 offset:27136
	s_waitcnt lgkmcnt(13)
	v_mfma_f32_32x32x16_bf16 v[66:81], v[102:105], v[146:149], v[66:81]
	v_add_f32_e32 v102, v52, v106
	v_add_f32_e32 v102, v53, v102
	v_add_f32_e32 v102, v54, v102
	v_add_f32_e32 v106, v55, v102
	v_cvt_pk_bf16_f32 v134, v50, v51
	v_cvt_pk_bf16_f32 v135, v52, v53
	ds_read_b64_tr_b16 v[102:103], v171 offset:30720
	ds_read_b64_tr_b16 v[104:105], v171 offset:31232
	s_waitcnt lgkmcnt(14)
	v_mfma_f32_32x32x16_bf16 v[34:49], v[118:121], v[146:149], v[34:49]
	v_add_f32_e32 v50, v56, v106
	v_add_f32_e32 v50, v57, v50
	v_add_f32_e32 v50, v58, v50
	v_add_f32_e32 v50, v59, v50
	v_cvt_pk_bf16_f32 v136, v54, v55
	v_cvt_pk_bf16_f32 v137, v56, v57
	ds_read_b64_tr_b16 v[106:107], v171 offset:27648
	ds_read_b64_tr_b16 v[108:109], v171 offset:28160
	s_waitcnt lgkmcnt(14)
	v_mfma_f32_32x32x16_bf16 v[66:81], v[114:117], v[138:141], v[66:81]
	v_add_f32_e32 v50, v60, v50
	v_add_f32_e32 v50, v61, v50
	v_add_f32_e32 v50, v62, v50
	v_add_f32_e32 v50, v63, v50
	v_cvt_pk_bf16_f32 v130, v58, v59
	v_cvt_pk_bf16_f32 v131, v60, v61
	ds_read_b64_tr_b16 v[114:115], v171 offset:31744
	ds_read_b64_tr_b16 v[116:117], v171 offset:32256
	v_mfma_f32_32x32x16_bf16 v[34:49], v[110:113], v[138:141], v[34:49]
	v_add_f32_e32 v50, v64, v50
	v_add_f32_e32 v50, v65, v50
	v_add_f32_e32 v50, 0, v50
	v_cvt_pk_bf16_f32 v132, v62, v63
	v_cvt_pk_bf16_f32 v133, v64, v65
	v_max_f32_e32 v51, v67, v67
	v_max_f32_e32 v52, v66, v66
	v_max_f32_e32 v51, v52, v51
	s_nop 3
	v_max3_f32 v52, v68, v69, v35
	v_max3_f32 v51, v51, v34, v36
	v_max3_f32 v51, v51, v37, v70
	v_max3_f32 v52, v52, v72, v73
	v_max3_f32 v51, v51, v71, v38
	v_max3_f32 v52, v52, v40, v41
	v_max3_f32 v51, v51, v39, v74
	v_max3_f32 v52, v52, v76, v77
	v_max3_f32 v51, v51, v75, v42
	v_max3_f32 v52, v52, v44, v45
	v_max3_f32 v51, v51, v43, v78
	v_max3_f32 v52, v52, v80, v81
	v_max3_f32 v51, v51, v79, v46
	v_max3_f32 v52, v52, v48, v49
	v_add_f32_e32 v110, v170, v50
	v_max3_f32 v50, v51, v47, v52
	v_mov_b32_e32 v51, v50
	s_nop 1
	v_permlane32_swap_b32_e32 v50, v51
	v_max_f32_e32 v51, v51, v51
	v_max_f32_e32 v50, v50, v50
	v_max_f32_e32 v50, v50, v51
	v_cmp_lt_f32_e32 vcc, s15, v50
	s_mov_b64 s[6:7], -1
	s_cbranch_vccnz .LBB0_734
	s_mov_b64 s[6:7], 0
